# speedup vs baseline: 1.0374x; 1.0101x over previous
; DEVINL unsigned xb_ld(unsigned* p) { return __hip_atomic_load(p, __ATOMIC_RELAXED, __HIP_MEMORY_SCOPE_AGENT); }
;     ...
;     __threadfence();
;     unsigned nx = 0; for (unsigned j = 0; j < 16; ++j) nx += (xb_ld(&bar[XB_XCNT(j)]) > 0u);
;     *sh = make_uint4(x, xb_ld(&bar[XB_XCNT(x)]), nx, 0u);
;   }
;   __syncthreads();
;   const uint4 t = *sh;
;   __syncthreads();
;   if (threadIdx.x == 0) { unsigned* st = bar + XCD_BAR_WORDS + blockIdx.x * 4; st[0] = t.x; st[1] = t.y; st[2] = t.z; }
.LBB0_35:
	s_or_b64 exec, exec, s[0:1]
	v_mov_b32_e32 v0, 0
	s_waitcnt lgkmcnt(0)
	s_barrier
	ds_read_b96 v[0:2], v0
	s_mov_b32 s3, 0
	s_waitcnt lgkmcnt(0)
	v_readfirstlane_b32 s4, v0
	v_readfirstlane_b32 s5, v1
	v_readfirstlane_b32 vcc_lo, v2
	s_nop 1
	v_writelane_b32 v255, s4, 60
	v_writelane_b32 v255, s5, 61
	v_writelane_b32 v255, vcc_lo, 62
	s_barrier
	s_mov_b64 s[0:1], exec
	v_readlane_b32 s4, v255, 5
	v_readlane_b32 s5, v255, 6
	s_and_b64 s[4:5], s[0:1], s[4:5]
	s_mov_b64 exec, s[4:5]
	s_cbranch_execz .LBB0_37
	v_readlane_b32 s2, v255, 0
	s_lshl_b32 s2, s2, 2
	s_lshl_b64 s[2:3], s[2:3], 2
	v_readlane_b32 s4, v255, 3
	v_readlane_b32 s5, v255, 4
	s_add_u32 s2, s4, s2
	s_addc_u32 s3, s5, s3
	v_mov_b32_e32 v3, 0x3000
	global_store_dwordx3 v3, v[0:2], s[2:3] offset:1536

; DEVINL void ret_state_phase(CParams& p, const Ctx& cx, int l, const GI& gi) {
;     ...
;   const int tid = cx.tid, wave = tid >> 6, lane = tid & 63, fr = lane & 15, fq = lane >> 4;
;   const int ep = wave & 1, dq = wave >> 1;
;   const int srow = tid >> 4, sch = tid & 15;
;   const int nchunk = gi.L >> 7;
;   const int nitems = gi.nseq * 32;
;   for (int it = cx.bid; it < nitems; it += cx.nb) {
;     const int es = it & 3, dir = (it >> 2) & 1, h = (it >> 3) & 3, sq = it >> 5;
;     const float gC = exp2f(128.f * p.lg2[(l * 2 + dir) * 4 + h]);
;     const u16* kT = dir == 0 ? p.kTf : p.kTb;
;     u16* S = dir == 0 ? p.Sf : p.Sb;
;     f32x4 acc[2][2];
; #pragma unroll
;     for (int et = 0; et < 2; ++et)
; #pragma unroll
;       for (int n = 0; n < 2; ++n) acc[et][n] = f32x4{0.f, 0.f, 0.f, 0.f};
;     struct Regs { bf16x8 v[2]; bf16x8 k[4]; };
;     auto chof = [&](int cc) -> size_t { const int c = dir == 0 ? cc : nchunk - 1 - cc; return (size_t)(sq * nchunk + c) * 4 + h; };
.LBB0_277:
	s_andn2_b64 vcc, exec, s[6:7]
	s_cbranch_vccnz .LBB0_1526
	v_readlane_b32 s4, v255, 44
	s_cmp_gt_i32 s4, 1
	s_mov_b64 s[4:5], -1
	s_cbranch_scc0 .LBB0_436
	s_lshl_b32 s12, s50, 5
	s_cmp_ge_i32 s59, s12
	v_ashrrev_i32_e32 v94, 2, v150
	s_movk_i32 s30, 0x4000
	s_movk_i32 s31, 0x6000
	s_movk_i32 s8, 0x110
	s_mov_b32 s34, 0xc2fc0000
	s_cbranch_scc1 .LBB0_290
	v_readlane_b32 s4, v255, 45
	s_lshr_b32 s13, s4, 7
	v_readlane_b32 s4, v255, 41
	v_readlane_b32 s5, v255, 42
	s_lshl_b32 s14, s4, 3
	s_load_dwordx2 s[4:5], s[88:89], 0x150
	s_load_dwordx2 s[6:7], s[88:89], 0x1a8
	v_bfe_u32 v3, v150, 6, 1
	v_bfe_u32 v7, v150, 4, 2
	v_and_b32_e32 v8, 15, v150
	v_lshlrev_b32_e32 v4, 12, v3
	v_ashrrev_i32_e32 v66, 4, v150
	v_lshlrev_b32_e32 v0, 4, v8
	v_lshl_or_b32 v95, v7, 9, v4
	v_and_b32_e32 v4, 0xffffffe0, v94
	v_lshlrev_b32_e32 v6, 1, v8
	v_lshlrev_b32_e32 v2, 3, v8
	s_waitcnt lgkmcnt(0)
	v_lshl_add_u64 v[68:69], s[6:7], 0, v[0:1]
	v_mul_lo_u32 v9, v66, s8
	v_lshl_or_b32 v3, v3, 5, v8
	v_lshlrev_b32_e32 v7, 4, v7
	v_or_b32_e32 v8, v6, v4
	v_readlane_b32 s6, v255, 25
	v_add_u32_e32 v10, 0, v9
	v_mul_lo_u32 v97, v8, s8
	v_add_u32_e32 v8, s6, v9
	v_add_u32_e32 v9, s6, v7
	v_readlane_b32 s6, v255, 26
	v_ashrrev_i32_e32 v67, 31, v66
	v_ashrrev_i32_e32 v5, 31, v4
	v_add_u32_e32 v11, s6, v7
	v_readlane_b32 s6, v255, 27
	v_add_u32_e32 v96, 0, v7
	v_mul_u32_u24_e32 v3, 0x110, v3
	v_add_u32_e32 v12, s6, v7
	v_readlane_b32 s6, v255, 28
	s_add_i32 s15, s13, -1
	v_lshlrev_b64 v[70:71], 8, v[66:67]
	v_add_u32_e32 v7, s6, v7
	s_add_i32 s16, s13, -2
	s_add_i32 s17, s13, -4
	v_lshlrev_b32_e32 v72, 1, v2
	v_lshlrev_b32_e32 v74, 1, v6
	v_add_u32_e32 v98, v8, v0
	v_add_u32_e32 v99, v9, v97
	v_add_u32_e32 v100, v11, v97
	v_add_u32_e32 v101, v12, v97
	v_add_u32_e32 v102, v7, v97
	v_add_u32_e32 v103, v10, v0
	v_lshlrev_b64 v[76:77], 1, v[4:5]
	v_add_u32_e32 v104, v96, v3
	v_readlane_b32 s18, v255, 38
	s_cmpk_lg_i32 s33, 0x100
	s_cbranch_scc1 .Lscan_noperm
	s_and_b32 s6, s12, 0xff
	s_cmp_lg_u32 s6, 0
	s_cbranch_scc1 .Lscan_noperm
	s_nop 1
	s_and_b32 s6, s18, 7
	s_lshl_b32 s6, s6, 2
	s_bfe_u32 s7, s18, 0x20003
	s_or_b32 s6, s6, s7
	s_and_b32 s18, s18, 0xffffffe0
	s_or_b32 s18, s18, s6
.Lscan_noperm:
	s_branch .LBB0_282
.LBB0_281:
	s_add_i32 s18, s18, s33
	s_cmp_ge_i32 s18, s12
	s_cbranch_scc1 .LBB0_290

; DEVINL void na_phase(CParams& p, const Ctx& cx, int l, const GI& gi) {
;     ...
;   auto gload = [&](int pr) {
;     const int tokp = pr * 128, seqbase = (tokp / L) * L, r0 = (tokp - seqbase) >> 6;
;     const int w0 = min(max(r0 - 4, 0), rows - 8), w1 = min(max(r0 - 3, 0), rows - 8) + 8;
;     const int g0 = (seqbase >> 6) + w0, nwin = w1 - w0;
; #pragma unroll
;     for (int i = 0; i < 9; ++i) {
;       const int gr = g0 + min(i, nwin - 1);
;       rk[i] = *(const bf16x8*)(p.kn + ((size_t)gr * 64 + st_r) * 512 + h * 64 + st_c * 8);
;       rv[i] = *(const bf16x8*)(p.vnT + (((size_t)gr * 512 + h * 64 + st_r) << 6) + st_c * 8);
;     }
;     const u16* qp = p.qn + (size_t)(tokp + wave * 16 + (lane & 15)) * 512 + h * 64 + (lane >> 4) * 8;
;     rq0 = *(const bf16x8*)qp; rq1 = *(const bf16x8*)(qp + 32);
;   };
;   for (int pr = cx.bid >> 3; pr < npairs; pr += nbh) {
;     gload(pr);
;     const int sw = (st_c ^ (st_r & 7)) * 16;
; #pragma unroll
;     for (int i = 0; i < 9; ++i) {
;       *(bf16x8*)(Kb + (i * 64 + st_r) * 128 + sw) = rk[i];
;       *(bf16x8*)(Vb + (i * 64 + st_r) * 128 + sw) = rv[i];
;     }
;     const bf16x8 bq0 = rq0, bq1 = rq1;
;     __syncthreads();
.LBB0_306:
	s_abs_i32 s5, s96
	v_readlane_b32 s6, v255, 51
	s_mul_hi_u32 s6, s5, s6
	v_readlane_b32 s7, v255, 45
	s_mul_i32 s6, s6, s7
	s_sub_i32 s5, s5, s6
	s_ashr_i32 s4, s96, 31
	s_sub_i32 s6, s5, s7
	s_cmp_ge_u32 s5, s7
	s_cselect_b32 s5, s6, s5
	s_sub_i32 s6, s5, s7
	s_cmp_ge_u32 s5, s7
	s_cselect_b32 s5, s6, s5
	s_xor_b32 s5, s5, s4
	s_sub_i32 s6, s5, s4
	s_ashr_i32 s6, s6, 6
	s_sub_i32 s4, s4, s5
	s_max_i32 s5, s6, 4
	s_add_i32 s5, s5, -4
	v_readlane_b32 s10, v255, 47
	s_min_i32 s7, s5, s10
	s_max_i32 s5, s6, 3
	s_add_i32 s5, s5, -3
	s_min_i32 s5, s5, s10
	s_not_b32 s8, s7
	s_add_i32 s4, s96, s4
	s_add_i32 s5, s5, s8
	s_ashr_i32 s4, s4, 6
	s_add_i32 s9, s5, 8
	s_add_i32 s8, s7, s4
	s_min_i32 s4, s9, 0
	s_add_i32 s4, s4, s8
	s_ashr_i32 s5, s4, 31
	s_lshl_b64 s[4:5], s[4:5], 16
	v_lshl_add_u64 v[2:3], v[86:87], 0, s[4:5]
	global_load_dwordx4 v[6:9], v[2:3], off
	v_lshl_add_u64 v[2:3], v[90:91], 0, s[4:5]
	s_min_i32 s4, s9, 1
	s_add_i32 s4, s4, s8
	s_ashr_i32 s5, s4, 31
	s_lshl_b64 s[4:5], s[4:5], 16
	global_load_dwordx4 v[10:13], v[2:3], off
	v_lshl_add_u64 v[2:3], v[86:87], 0, s[4:5]
	global_load_dwordx4 v[14:17], v[2:3], off
	v_lshl_add_u64 v[2:3], v[90:91], 0, s[4:5]
	s_min_i32 s4, s9, 2
	s_add_i32 s4, s4, s8
	s_ashr_i32 s5, s4, 31
	s_lshl_b64 s[4:5], s[4:5], 16
	global_load_dwordx4 v[18:21], v[2:3], off
	v_lshl_add_u64 v[2:3], v[86:87], 0, s[4:5]
	global_load_dwordx4 v[22:25], v[2:3], off
	v_lshl_add_u64 v[2:3], v[90:91], 0, s[4:5]
	s_min_i32 s4, s9, 3
	s_add_i32 s4, s4, s8
	s_ashr_i32 s5, s4, 31
	s_lshl_b64 s[4:5], s[4:5], 16
	global_load_dwordx4 v[26:29], v[2:3], off
	v_lshl_add_u64 v[2:3], v[86:87], 0, s[4:5]
	global_load_dwordx4 v[30:33], v[2:3], off
	v_lshl_add_u64 v[2:3], v[90:91], 0, s[4:5]
	s_min_i32 s4, s9, 4
	s_add_i32 s4, s4, s8
	s_ashr_i32 s5, s4, 31
	s_lshl_b64 s[4:5], s[4:5], 16
	global_load_dwordx4 v[34:37], v[2:3], off
	v_lshl_add_u64 v[2:3], v[86:87], 0, s[4:5]
	global_load_dwordx4 v[38:41], v[2:3], off
	v_lshl_add_u64 v[2:3], v[90:91], 0, s[4:5]
	s_min_i32 s4, s9, 5
	s_add_i32 s4, s4, s8
	s_ashr_i32 s5, s4, 31
	s_lshl_b64 s[4:5], s[4:5], 16
	global_load_dwordx4 v[42:45], v[2:3], off
	v_lshl_add_u64 v[2:3], v[86:87], 0, s[4:5]
	global_load_dwordx4 v[46:49], v[2:3], off
	v_lshl_add_u64 v[2:3], v[90:91], 0, s[4:5]
	s_min_i32 s4, s9, 6
	s_add_i32 s4, s4, s8
	s_ashr_i32 s5, s4, 31
	s_lshl_b64 s[4:5], s[4:5], 16
	global_load_dwordx4 v[50:53], v[2:3], off
	v_lshl_add_u64 v[2:3], v[86:87], 0, s[4:5]
	global_load_dwordx4 v[54:57], v[2:3], off
	v_lshl_add_u64 v[2:3], v[90:91], 0, s[4:5]
	s_min_i32 s4, s9, 7
	s_add_i32 s4, s4, s8
	s_ashr_i32 s5, s4, 31
	s_lshl_b64 s[4:5], s[4:5], 16
	global_load_dwordx4 v[58:61], v[2:3], off
	v_lshl_add_u64 v[2:3], v[86:87], 0, s[4:5]
	global_load_dwordx4 v[62:65], v[2:3], off
	v_lshl_add_u64 v[2:3], v[90:91], 0, s[4:5]
	s_min_i32 s4, s9, 8
	s_add_i32 s4, s4, s8
	s_ashr_i32 s5, s4, 31
	s_lshl_b64 s[4:5], s[4:5], 16
	global_load_dwordx4 v[70:73], v[2:3], off
	v_lshl_add_u64 v[2:3], v[86:87], 0, s[4:5]
	global_load_dwordx4 v[74:77], v[2:3], off
	v_lshl_add_u64 v[2:3], v[90:91], 0, s[4:5]
	global_load_dwordx4 v[78:81], v[2:3], off
	v_add_u32_e32 v2, s96, v140
	v_ashrrev_i32_e32 v3, 31, v2
	v_lshlrev_b64 v[2:3], 10, v[2:3]
	v_lshl_add_u64 v[2:3], v[88:89], 0, v[2:3]
	global_load_dwordx4 v[66:69], v[2:3], off
	s_nop 0
	global_load_dwordx4 v[2:5], v[2:3], off offset:64
	v_add_u32_e32 v0, v131, v130
	s_waitcnt vmcnt(19)
	ds_write_b128 v0, v[6:9]
	v_add_u32_e32 v6, v132, v130
	s_waitcnt vmcnt(18)
	ds_write_b128 v6, v[10:13]
	s_waitcnt vmcnt(17)
	ds_write_b128 v0, v[14:17] offset:8192
	s_waitcnt vmcnt(16)
	ds_write_b128 v6, v[18:21] offset:8192
	s_waitcnt vmcnt(15)
	ds_write_b128 v0, v[22:25] offset:16384
	s_waitcnt vmcnt(14)
	ds_write_b128 v6, v[26:29] offset:16384
	s_waitcnt vmcnt(13)
	ds_write_b128 v0, v[30:33] offset:24576
	s_waitcnt vmcnt(12)
	ds_write_b128 v6, v[34:37] offset:24576
	s_waitcnt vmcnt(11)
	ds_write_b128 v0, v[38:41] offset:32768
	s_waitcnt vmcnt(10)
	ds_write_b128 v6, v[42:45] offset:32768
	s_waitcnt vmcnt(9)
	ds_write_b128 v0, v[46:49] offset:40960
	s_waitcnt vmcnt(8)
	ds_write_b128 v6, v[50:53] offset:40960
	s_waitcnt vmcnt(7)
	ds_write_b128 v0, v[54:57] offset:49152
	s_waitcnt vmcnt(6)
	ds_write_b128 v6, v[58:61] offset:49152
	s_waitcnt vmcnt(5)
	ds_write_b128 v0, v[62:65] offset:57344
	s_waitcnt vmcnt(4)
	ds_write_b128 v6, v[70:73] offset:57344
	v_add_u32_e32 v73, s6, v133
	v_add_u32_e32 v0, v131, v139
	v_max_i32_e32 v6, 4, v73
	v_add_u32_e32 v6, -4, v6
	v_mov_b32_e32 v70, v128
	s_waitcnt vmcnt(3)
	ds_write_b128 v0, v[74:77]
	v_add_u32_e32 v0, v132, v139
	s_waitcnt vmcnt(2)
	ds_write_b128 v0, v[78:81]
	v_min_i32_e32 v78, s10, v6
	v_subrev_u32_e32 v6, s7, v78
	v_lshlrev_b32_e32 v72, 6, v6
	s_waitcnt lgkmcnt(0)
	s_barrier
; DEVINL void na_phase(CParams& p, const Ctx& cx, int l, const GI& gi) {
;     ...
;     const int x7 = (kstart + fr) & 7;
;     const char* kb0 = Kb + (wb * 64 + kstart + fr) * 128 + ((fq ^ x7) * 16);
;     const char* kb1 = Kb + (wb * 64 + kstart + fr) * 128 + (((4 + fq) ^ x7) * 16);
; #pragma unroll
;     for (int t = 0; t < 16; ++t) {
;       const bf16x8 a0 = *(const bf16x8*)(kb0 + ((t >> 1) * 64 + (t & 1) * 16) * 128), a1 = *(const bf16x8*)(kb1 + ((t >> 1) * 64 + (t & 1) * 16) * 128);
;       f32x4 z = {0.f, 0.f, 0.f, 0.f};
;       z = __builtin_amdgcn_mfma_f32_16x16x32_bf16(a0, bq0, z, 0, 0, 0);
;       s[t] = __builtin_amdgcn_mfma_f32_16x16x32_bf16(a1, bq1, z, 0, 0, 0);
;       if ((t & 3) == 3) __builtin_amdgcn_sched_barrier(0);
;     }
;     const int c = cb * 16 + fr, cs = min(max(c - 8, 0), 48);
;     float mx = -1e30f;
; #pragma unroll
;     for (int t = 0; t < 16; ++t) {
;       const int ro = rs + (t >> 1) - r + 7;
; #pragma unroll
;       for (int j = 0; j < 4; ++j) {
;         const int kc = kstart + (t & 1) * 16 + fq * 4 + j;
;         const bool valid = kc >= cs && kc < cs + 16;
;         const int ci = min(max(kc - c + 15, 0), 30);
;         const float bv = rp[ro * 31 + ci];
;         const float v = valid ? s[t][j] + bv : -1e30f;
;         s[t][j] = v; mx = fmaxf(mx, v);
	v_or_b32_e32 v6, v72, v135
	v_and_b32_e32 v0, 15, v70
	v_ashrrev_i32_e32 v71, 4, v70
	v_add_u32_e32 v6, v6, v0
	v_lshl_add_u32 v10, v6, 7, 0
	v_bitop3_b32 v6, v71, v70, 7 bitop3:0x78
	v_lshl_add_u32 v79, v6, 4, v10
	ds_read_b128 v[6:9], v79
	v_add_u32_e32 v11, 4, v71
	v_bitop3_b32 v11, v11, v70, 7 bitop3:0x78
	v_lshl_add_u32 v80, v11, 4, v10
	ds_read_b128 v[10:13], v79 offset:2048
	s_waitcnt vmcnt(1) lgkmcnt(1)
	v_mfma_f32_16x16x32_bf16 v[6:9], v[6:9], v[66:69], 0
	ds_read_b128 v[14:17], v80
	ds_read_b128 v[18:21], v80 offset:2048
	s_waitcnt vmcnt(0) lgkmcnt(1)
	v_mfma_f32_16x16x32_bf16 v[62:65], v[14:17], v[2:5], v[6:9]
	v_mfma_f32_16x16x32_bf16 v[6:9], v[10:13], v[66:69], 0
	s_waitcnt lgkmcnt(0)
	v_mfma_f32_16x16x32_bf16 v[58:61], v[18:21], v[2:5], v[6:9]
	s_nop 5
	ds_read_b128 v[6:9], v79 offset:8192
	ds_read_b128 v[10:13], v79 offset:10240
	ds_read_b128 v[14:17], v80 offset:8192
	ds_read_b128 v[18:21], v80 offset:10240
	s_waitcnt lgkmcnt(3)
	v_mfma_f32_16x16x32_bf16 v[6:9], v[6:9], v[66:69], 0
	s_waitcnt lgkmcnt(1)
	v_mfma_f32_16x16x32_bf16 v[54:57], v[14:17], v[2:5], v[6:9]
	v_mfma_f32_16x16x32_bf16 v[6:9], v[10:13], v[66:69], 0
	s_waitcnt lgkmcnt(0)
	v_mfma_f32_16x16x32_bf16 v[50:53], v[18:21], v[2:5], v[6:9]
	s_nop 5
	ds_read_b128 v[6:9], v79 offset:16384
	ds_read_b128 v[10:13], v80 offset:16384
	s_waitcnt lgkmcnt(1)
	v_mfma_f32_16x16x32_bf16 v[6:9], v[6:9], v[66:69], 0
	s_waitcnt lgkmcnt(0)
	v_mfma_f32_16x16x32_bf16 v[46:49], v[10:13], v[2:5], v[6:9]
	s_nop 5
	ds_read_b128 v[6:9], v80 offset:18432
	ds_read_b128 v[10:13], v79 offset:18432
	s_waitcnt lgkmcnt(0)
	v_mfma_f32_16x16x32_bf16 v[10:13], v[10:13], v[66:69], 0
	v_mfma_f32_16x16x32_bf16 v[42:45], v[6:9], v[2:5], v[10:13]
	ds_read_b128 v[6:9], v80 offset:24576
	s_nop 5
	ds_read_b128 v[10:13], v79 offset:24576
	s_waitcnt lgkmcnt(0)
	v_mfma_f32_16x16x32_bf16 v[10:13], v[10:13], v[66:69], 0
	v_mfma_f32_16x16x32_bf16 v[38:41], v[6:9], v[2:5], v[10:13]
	ds_read_b128 v[6:9], v80 offset:26624
	s_nop 5
	ds_read_b128 v[10:13], v79 offset:26624
	s_waitcnt lgkmcnt(0)
	v_mfma_f32_16x16x32_bf16 v[10:13], v[10:13], v[66:69], 0
	v_mfma_f32_16x16x32_bf16 v[34:37], v[6:9], v[2:5], v[10:13]
	ds_read_b128 v[6:9], v79 offset:32768
	s_nop 5
	ds_read_b128 v[10:13], v80 offset:32768
	s_waitcnt lgkmcnt(1)
	v_mfma_f32_16x16x32_bf16 v[6:9], v[6:9], v[66:69], 0
	s_waitcnt lgkmcnt(0)
	v_mfma_f32_16x16x32_bf16 v[30:33], v[10:13], v[2:5], v[6:9]
	s_nop 5
	ds_read_b128 v[6:9], v80 offset:34816
	ds_read_b128 v[10:13], v79 offset:34816
	s_waitcnt lgkmcnt(0)
	v_mfma_f32_16x16x32_bf16 v[10:13], v[10:13], v[66:69], 0
	v_mfma_f32_16x16x32_bf16 v[26:29], v[6:9], v[2:5], v[10:13]
	ds_read_b128 v[6:9], v80 offset:40960
	s_nop 5
	ds_read_b128 v[10:13], v79 offset:40960
	s_waitcnt lgkmcnt(0)
	v_mfma_f32_16x16x32_bf16 v[10:13], v[10:13], v[66:69], 0
	v_mfma_f32_16x16x32_bf16 v[22:25], v[6:9], v[2:5], v[10:13]
	ds_read_b128 v[6:9], v80 offset:43008
	s_nop 5
	ds_read_b128 v[10:13], v79 offset:43008
	s_waitcnt lgkmcnt(0)
	v_mfma_f32_16x16x32_bf16 v[10:13], v[10:13], v[66:69], 0
	v_mfma_f32_16x16x32_bf16 v[18:21], v[6:9], v[2:5], v[10:13]
	ds_read_b128 v[6:9], v79 offset:49152
	s_nop 5
	ds_read_b128 v[10:13], v79 offset:51200
	ds_read_b128 v[14:17], v80 offset:49152
	s_waitcnt lgkmcnt(2)
	v_mfma_f32_16x16x32_bf16 v[6:9], v[6:9], v[66:69], 0
	ds_read_b128 v[74:77], v80 offset:57344
	s_waitcnt lgkmcnt(1)
	v_mfma_f32_16x16x32_bf16 v[14:17], v[14:17], v[2:5], v[6:9]
	s_nop 4
	ds_read_b128 v[6:9], v80 offset:51200
	v_mfma_f32_16x16x32_bf16 v[10:13], v[10:13], v[66:69], 0
	s_waitcnt lgkmcnt(0)
	v_mfma_f32_16x16x32_bf16 v[10:13], v[6:9], v[2:5], v[10:13]
	ds_read_b128 v[6:9], v79 offset:57344
	s_waitcnt lgkmcnt(0)
	v_mfma_f32_16x16x32_bf16 v[6:9], v[6:9], v[66:69], 0
	v_mfma_f32_16x16x32_bf16 v[6:9], v[74:77], v[2:5], v[6:9]
	ds_read_b128 v[74:77], v79 offset:59392
	s_waitcnt lgkmcnt(0)
	v_mfma_f32_16x16x32_bf16 v[66:69], v[74:77], v[66:69], 0
	ds_read_b128 v[74:77], v80 offset:59392
	s_waitcnt lgkmcnt(0)
	v_mfma_f32_16x16x32_bf16 v[2:5], v[74:77], v[2:5], v[66:69]
	v_or_b32_e32 v79, v0, v134
	s_nop 3
	v_max_i32_e32 v66, 8, v79
	v_add_u32_e32 v66, -8, v66
	v_min_u32_e32 v80, 48, v66
	v_sub_u32_e32 v66, v78, v73
	v_lshlrev_b32_e32 v141, 2, v71
	s_movk_i32 s4, 0x7c
	v_add_u32_e32 v82, v141, v135
	v_add_u32_e32 v81, 16, v80
	v_mul_lo_u32 v66, v66, s4
	v_readlane_b32 s4, v255, 29
	v_mov_b32_e32 v190, 0xf149f2ca
	s_nop 0
	v_add_u32_e32 v68, s4, v66
	v_cmp_ge_i32_e32 vcc, v82, v80
	v_cmp_lt_i32_e64 s[4:5], v82, v81
	v_sub_u32_e32 v189, v82, v79
	s_and_b64 s[4:5], vcc, s[4:5]
	v_max_i32_e32 v189, -15, v189
	v_add_u32_e32 v189, 15, v189
	v_min_u32_e32 v189, 30, v189
	v_lshl_add_u32 v180, v189, 2, v68
	v_add_u32_e32 v188, 1, v82
	v_cmp_ge_i32_e32 vcc, v188, v80
	v_cmp_lt_i32_e64 s[8:9], v188, v81
	v_sub_u32_e32 v189, v188, v79
	s_and_b64 s[8:9], vcc, s[8:9]
	v_max_i32_e32 v189, -15, v189
	v_add_u32_e32 v189, 15, v189
	v_min_u32_e32 v189, 30, v189
	v_lshl_add_u32 v181, v189, 2, v68
	v_add_u32_e32 v188, 2, v82
	v_cmp_ge_i32_e32 vcc, v188, v80
	v_cmp_lt_i32_e64 s[10:11], v188, v81
	v_sub_u32_e32 v189, v188, v79
	s_and_b64 s[10:11], vcc, s[10:11]
	v_max_i32_e32 v189, -15, v189
	v_add_u32_e32 v189, 15, v189
	v_min_u32_e32 v189, 30, v189
	v_lshl_add_u32 v182, v189, 2, v68
	v_add_u32_e32 v188, 3, v82
	v_cmp_ge_i32_e32 vcc, v188, v80
	v_cmp_lt_i32_e64 s[12:13], v188, v81
	v_sub_u32_e32 v189, v188, v79
	s_and_b64 s[12:13], vcc, s[12:13]
	v_max_i32_e32 v189, -15, v189
	v_add_u32_e32 v189, 15, v189
	v_min_u32_e32 v189, 30, v189
	v_lshl_add_u32 v183, v189, 2, v68
	v_add_u32_e32 v188, 16, v82
	v_cmp_ge_i32_e32 vcc, v188, v80
	v_cmp_lt_i32_e64 s[14:15], v188, v81
; DEVINL void na_phase(CParams& p, const Ctx& cx, int l, const GI& gi) {
;     ...
;     const int c = cb * 16 + fr, cs = min(max(c - 8, 0), 48);
;     float mx = -1e30f;
; #pragma unroll
;     for (int t = 0; t < 16; ++t) {
;       const int ro = rs + (t >> 1) - r + 7;
; #pragma unroll
;       for (int j = 0; j < 4; ++j) {
;         const int kc = kstart + (t & 1) * 16 + fq * 4 + j;
;         const bool valid = kc >= cs && kc < cs + 16;
;         const int ci = min(max(kc - c + 15, 0), 30);
;         const float bv = rp[ro * 31 + ci];
;         const float v = valid ? s[t][j] + bv : -1e30f;
;         s[t][j] = v; mx = fmaxf(mx, v);
	v_sub_u32_e32 v189, v188, v79
	s_and_b64 s[14:15], vcc, s[14:15]
	v_max_i32_e32 v189, -15, v189
	v_add_u32_e32 v189, 15, v189
	v_min_u32_e32 v189, 30, v189
	v_lshl_add_u32 v184, v189, 2, v68
	v_add_u32_e32 v188, 17, v82
	v_cmp_ge_i32_e32 vcc, v188, v80
	v_cmp_lt_i32_e64 s[16:17], v188, v81
	v_sub_u32_e32 v189, v188, v79
	s_and_b64 s[16:17], vcc, s[16:17]
	v_max_i32_e32 v189, -15, v189
	v_add_u32_e32 v189, 15, v189
	v_min_u32_e32 v189, 30, v189
	v_lshl_add_u32 v185, v189, 2, v68
	v_add_u32_e32 v188, 18, v82
	v_cmp_ge_i32_e32 vcc, v188, v80
	v_cmp_lt_i32_e64 s[18:19], v188, v81
	v_sub_u32_e32 v189, v188, v79
	s_and_b64 s[18:19], vcc, s[18:19]
	v_max_i32_e32 v189, -15, v189
	v_add_u32_e32 v189, 15, v189
	v_min_u32_e32 v189, 30, v189
	v_lshl_add_u32 v186, v189, 2, v68
	v_add_u32_e32 v188, 19, v82
	v_cmp_ge_i32_e32 vcc, v188, v80
	v_cmp_lt_i32_e64 s[6:7], v188, v81
	v_sub_u32_e32 v189, v188, v79
	s_and_b64 s[6:7], vcc, s[6:7]
	v_max_i32_e32 v189, -15, v189
	v_add_u32_e32 v189, 15, v189
	v_min_u32_e32 v189, 30, v189
	v_lshl_add_u32 v187, v189, 2, v68
	ds_read_b32 v92, v180 offset:868
	ds_read_b32 v93, v181 offset:868
	ds_read_b32 v94, v182 offset:868
	ds_read_b32 v95, v183 offset:868
	ds_read_b32 v96, v184 offset:868
	ds_read_b32 v97, v185 offset:868
	ds_read_b32 v98, v186 offset:868
	ds_read_b32 v99, v187 offset:868
	ds_read_b32 v100, v180 offset:992
	ds_read_b32 v101, v181 offset:992
	ds_read_b32 v102, v182 offset:992
	ds_read_b32 v103, v183 offset:992
	ds_read_b32 v104, v184 offset:992
	ds_read_b32 v105, v185 offset:992
	ds_read_b32 v106, v186 offset:992
	ds_read_b32 v107, v187 offset:992
	ds_read_b32 v108, v180 offset:1116
	ds_read_b32 v109, v181 offset:1116
	ds_read_b32 v110, v182 offset:1116
	ds_read_b32 v111, v183 offset:1116
	ds_read_b32 v112, v184 offset:1116
	ds_read_b32 v113, v185 offset:1116
	ds_read_b32 v114, v186 offset:1116
	ds_read_b32 v115, v187 offset:1116
	ds_read_b32 v116, v180 offset:1240
	ds_read_b32 v117, v181 offset:1240
	ds_read_b32 v118, v182 offset:1240
	ds_read_b32 v119, v183 offset:1240
	ds_read_b32 v120, v184 offset:1240
	ds_read_b32 v121, v185 offset:1240
	ds_read_b32 v122, v186 offset:1240
	ds_read_b32 v123, v187 offset:1240
	ds_read_b32 v124, v180 offset:1364
	ds_read_b32 v125, v181 offset:1364
	ds_read_b32 v126, v182 offset:1364
	ds_read_b32 v127, v183 offset:1364
	ds_read_b32 v152, v184 offset:1364
	ds_read_b32 v153, v185 offset:1364
	ds_read_b32 v154, v186 offset:1364
	ds_read_b32 v155, v187 offset:1364
	ds_read_b32 v156, v180 offset:1488
	ds_read_b32 v157, v181 offset:1488
	ds_read_b32 v158, v182 offset:1488
	ds_read_b32 v159, v183 offset:1488
	ds_read_b32 v160, v184 offset:1488
	ds_read_b32 v161, v185 offset:1488
	ds_read_b32 v162, v186 offset:1488
	ds_read_b32 v163, v187 offset:1488
	ds_read_b32 v164, v180 offset:1612
	ds_read_b32 v165, v181 offset:1612
	ds_read_b32 v166, v182 offset:1612
	ds_read_b32 v167, v183 offset:1612
	ds_read_b32 v168, v184 offset:1612
	ds_read_b32 v169, v185 offset:1612
	ds_read_b32 v170, v186 offset:1612
	ds_read_b32 v171, v187 offset:1612
	ds_read_b32 v172, v180 offset:1736
	ds_read_b32 v173, v181 offset:1736
	ds_read_b32 v174, v182 offset:1736
	ds_read_b32 v175, v183 offset:1736
	ds_read_b32 v176, v184 offset:1736
	ds_read_b32 v177, v185 offset:1736
	ds_read_b32 v178, v186 offset:1736
	ds_read_b32 v179, v187 offset:1736
	s_waitcnt lgkmcnt(0)
; DEVINL void na_phase(CParams& p, const Ctx& cx, int l, const GI& gi) {
;     ...
;     for (int t = 0; t < 16; ++t) {
;       const int ro = rs + (t >> 1) - r + 7;
; #pragma unroll
;       for (int j = 0; j < 4; ++j) {
;         const int kc = kstart + (t & 1) * 16 + fq * 4 + j;
;         const bool valid = kc >= cs && kc < cs + 16;
;         const int ci = min(max(kc - c + 15, 0), 30);
;         const float bv = rp[ro * 31 + ci];
;         const float v = valid ? s[t][j] + bv : -1e30f;
;         s[t][j] = v; mx = fmaxf(mx, v);
;       }
;     }
	v_add_f32_e32 v92, v62, v92
	v_cndmask_b32_e64 v67, v190, v92, s[4:5]
	v_add_f32_e32 v93, v63, v93
	v_cndmask_b32_e64 v66, v190, v93, s[8:9]
	v_add_f32_e32 v94, v64, v94
	v_cndmask_b32_e64 v63, v190, v94, s[10:11]
	v_add_f32_e32 v95, v65, v95
	v_cndmask_b32_e64 v62, v190, v95, s[12:13]
	v_add_f32_e32 v96, v58, v96
	v_cndmask_b32_e64 v65, v190, v96, s[14:15]
	v_add_f32_e32 v97, v59, v97
	v_cndmask_b32_e64 v64, v190, v97, s[16:17]
	v_add_f32_e32 v98, v60, v98
	v_cndmask_b32_e64 v58, v190, v98, s[18:19]
	v_add_f32_e32 v99, v61, v99
	v_cndmask_b32_e64 v59, v190, v99, s[6:7]
	v_add_f32_e32 v100, v54, v100
	v_cndmask_b32_e64 v61, v190, v100, s[4:5]
	v_add_f32_e32 v101, v55, v101
	v_cndmask_b32_e64 v60, v190, v101, s[8:9]
	v_add_f32_e32 v102, v56, v102
	v_cndmask_b32_e64 v55, v190, v102, s[10:11]
	v_add_f32_e32 v103, v57, v103
	v_cndmask_b32_e64 v54, v190, v103, s[12:13]
	v_add_f32_e32 v104, v50, v104
	v_cndmask_b32_e64 v57, v190, v104, s[14:15]
	v_add_f32_e32 v105, v51, v105
	v_cndmask_b32_e64 v56, v190, v105, s[16:17]
	v_add_f32_e32 v106, v52, v106
	v_cndmask_b32_e64 v51, v190, v106, s[18:19]
	v_add_f32_e32 v107, v53, v107
	v_cndmask_b32_e64 v50, v190, v107, s[6:7]
	v_add_f32_e32 v108, v46, v108
	v_cndmask_b32_e64 v53, v190, v108, s[4:5]
	v_add_f32_e32 v109, v47, v109
	v_cndmask_b32_e64 v52, v190, v109, s[8:9]
	v_add_f32_e32 v110, v48, v110
	v_cndmask_b32_e64 v47, v190, v110, s[10:11]
	v_add_f32_e32 v111, v49, v111
	v_cndmask_b32_e64 v46, v190, v111, s[12:13]
	v_add_f32_e32 v112, v42, v112
	v_cndmask_b32_e64 v49, v190, v112, s[14:15]
	v_add_f32_e32 v113, v43, v113
	v_cndmask_b32_e64 v48, v190, v113, s[16:17]
	v_add_f32_e32 v114, v44, v114
	v_cndmask_b32_e64 v43, v190, v114, s[18:19]
	v_add_f32_e32 v115, v45, v115
	v_cndmask_b32_e64 v42, v190, v115, s[6:7]
	v_add_f32_e32 v116, v38, v116
	v_cndmask_b32_e64 v45, v190, v116, s[4:5]
	v_add_f32_e32 v117, v39, v117
	v_cndmask_b32_e64 v44, v190, v117, s[8:9]
	v_add_f32_e32 v118, v40, v118
	v_cndmask_b32_e64 v39, v190, v118, s[10:11]
	v_add_f32_e32 v119, v41, v119
	v_cndmask_b32_e64 v38, v190, v119, s[12:13]
	v_add_f32_e32 v120, v34, v120
	v_cndmask_b32_e64 v41, v190, v120, s[14:15]
	v_add_f32_e32 v121, v35, v121
	v_cndmask_b32_e64 v40, v190, v121, s[16:17]
	v_add_f32_e32 v122, v36, v122
	v_cndmask_b32_e64 v35, v190, v122, s[18:19]
	v_add_f32_e32 v123, v37, v123
	v_cndmask_b32_e64 v34, v190, v123, s[6:7]
	v_add_f32_e32 v124, v30, v124
	v_cndmask_b32_e64 v37, v190, v124, s[4:5]
	v_add_f32_e32 v125, v31, v125
	v_cndmask_b32_e64 v36, v190, v125, s[8:9]
	v_add_f32_e32 v126, v32, v126
	v_cndmask_b32_e64 v31, v190, v126, s[10:11]
	v_add_f32_e32 v127, v33, v127
	v_cndmask_b32_e64 v30, v190, v127, s[12:13]
	v_add_f32_e32 v152, v26, v152
	v_cndmask_b32_e64 v33, v190, v152, s[14:15]
	v_add_f32_e32 v153, v27, v153
	v_cndmask_b32_e64 v32, v190, v153, s[16:17]
	v_add_f32_e32 v154, v28, v154
	v_cndmask_b32_e64 v27, v190, v154, s[18:19]
	v_add_f32_e32 v155, v29, v155
	v_cndmask_b32_e64 v26, v190, v155, s[6:7]
	v_add_f32_e32 v156, v22, v156
	v_cndmask_b32_e64 v29, v190, v156, s[4:5]
	v_add_f32_e32 v157, v23, v157
	v_cndmask_b32_e64 v28, v190, v157, s[8:9]
	v_add_f32_e32 v158, v24, v158
	v_cndmask_b32_e64 v23, v190, v158, s[10:11]
	v_add_f32_e32 v159, v25, v159
	v_cndmask_b32_e64 v22, v190, v159, s[12:13]
	v_add_f32_e32 v160, v18, v160
	v_cndmask_b32_e64 v25, v190, v160, s[14:15]
	v_add_f32_e32 v161, v19, v161
	v_cndmask_b32_e64 v24, v190, v161, s[16:17]
	v_add_f32_e32 v162, v20, v162
	v_cndmask_b32_e64 v19, v190, v162, s[18:19]
	v_add_f32_e32 v163, v21, v163
	v_cndmask_b32_e64 v18, v190, v163, s[6:7]
	v_add_f32_e32 v164, v14, v164
	v_cndmask_b32_e64 v21, v190, v164, s[4:5]
	v_add_f32_e32 v165, v15, v165
	v_cndmask_b32_e64 v20, v190, v165, s[8:9]
	v_add_f32_e32 v166, v16, v166
	v_cndmask_b32_e64 v15, v190, v166, s[10:11]
	v_add_f32_e32 v167, v17, v167
	v_cndmask_b32_e64 v14, v190, v167, s[12:13]
	v_add_f32_e32 v168, v10, v168
	v_cndmask_b32_e64 v17, v190, v168, s[14:15]
	v_add_f32_e32 v169, v11, v169
	v_cndmask_b32_e64 v16, v190, v169, s[16:17]
	v_add_f32_e32 v170, v12, v170
	v_cndmask_b32_e64 v11, v190, v170, s[18:19]
	v_add_f32_e32 v171, v13, v171
	v_cndmask_b32_e64 v10, v190, v171, s[6:7]
	v_add_f32_e32 v172, v6, v172
	v_cndmask_b32_e64 v13, v190, v172, s[4:5]
	v_add_f32_e32 v173, v7, v173
	v_cndmask_b32_e64 v12, v190, v173, s[8:9]
	v_add_f32_e32 v174, v8, v174
	v_cndmask_b32_e64 v69, v190, v174, s[10:11]
	v_add_f32_e32 v175, v9, v175
	v_cndmask_b32_e64 v7, v190, v175, s[12:13]
	v_add_f32_e32 v176, v2, v176
	v_cndmask_b32_e64 v8, v190, v176, s[14:15]
	v_add_f32_e32 v177, v3, v177
	v_cndmask_b32_e64 v6, v190, v177, s[16:17]
	v_add_f32_e32 v178, v4, v178
	v_cndmask_b32_e64 v2, v190, v178, s[18:19]
	v_add_f32_e32 v179, v5, v179
	v_cndmask_b32_e64 v3, v190, v179, s[6:7]
	v_writelane_b32 v255, s24, 52
	s_branch .LBB0_305

;   DEVINL void operator()(Acc& acc, int brow, int bcol) const {
;     ...
;         const int row0 = brow + ai * 128 + wr * 64 + m * 16 + fq * 4;
;         float o1[2][4], o2[2][4];
;         _Pragma("unroll") for (int j = 0; j < 4; ++j) {
;           const int pos = (row0 + j) % L;
;           const float2 cs = *(const float2*)(P.ctab + pos * 64 + i0), sn = *(const float2*)(P.stab + pos * 64 + i0);
;           o1[0][j] = acc[ai][0][m][0][j] * cs.x - acc[ai][1][m][0][j] * sn.x; o2[0][j] = acc[ai][0][m][0][j] * sn.x + acc[ai][1][m][0][j] * cs.x;
;           o1[1][j] = acc[ai][0][m][1][j] * cs.y - acc[ai][1][m][1][j] * sn.y; o2[1][j] = acc[ai][0][m][1][j] * sn.y + acc[ai][1][m][1][j] * cs.y;
;         }
.LBB0_768:
	v_or_b32_e32 v118, 16, v146
	v_add_u32_e32 v117, v118, v147
	v_xor_b32_e32 v117, v117, v147
	v_mul_hi_u32 v119, v117, v174
	v_mul_lo_u32 v119, v119, s62
	v_sub_u32_e32 v117, v117, v119
	v_cmp_le_u32_e32 vcc, s62, v117
	v_subrev_u32_e32 v119, s62, v117
	v_mov_b32_e32 v126, v102
	v_cndmask_b32_e32 v117, v117, v119, vcc
	v_cmp_le_u32_e32 vcc, s62, v117
	v_subrev_u32_e32 v119, s62, v117
	v_or_b32_e32 v102, 17, v146
	v_cndmask_b32_e32 v117, v117, v119, vcc
	v_xor_b32_e32 v117, v117, v147
	v_sub_u32_e32 v117, v117, v147
	v_lshlrev_b32_e32 v120, 6, v117
	v_ashrrev_i32_e32 v121, 31, v120
	v_lshlrev_b64 v[120:121], 2, v[120:121]
	v_lshl_add_u64 v[122:123], v[142:143], 0, v[120:121]
	v_lshl_add_u64 v[120:121], v[144:145], 0, v[120:121]
	global_load_dwordx2 v[220:221], v[122:123], off offset:256
	global_load_dwordx2 v[222:223], v[120:121], off offset:256
	global_load_dwordx2 v[224:225], v[122:123], off offset:512
	global_load_dwordx2 v[226:227], v[120:121], off offset:512
	global_load_dwordx2 v[228:229], v[122:123], off offset:768
	global_load_dwordx2 v[230:231], v[120:121], off offset:768
	global_load_dwordx2 v[124:125], v[122:123], off
	s_nop 0
	global_load_dwordx2 v[120:121], v[120:121], off
	v_mov_b32_e32 v127, v98
	v_add_u32_e32 v98, v102, v147
	v_xor_b32_e32 v98, v98, v147
	v_mov_b32_e32 v129, v106
	v_mul_hi_u32 v106, v98, v174
	v_mul_lo_u32 v106, v106, s62
	v_sub_u32_e32 v98, v98, v106
	v_cmp_le_u32_e32 vcc, s62, v98
	v_subrev_u32_e32 v106, s62, v98
	v_mov_b32_e32 v128, v110
	v_cndmask_b32_e32 v98, v98, v106, vcc
	v_cmp_le_u32_e32 vcc, s62, v98
	v_subrev_u32_e32 v106, s62, v98
	v_mov_b32_e32 v148, v104
	v_cndmask_b32_e32 v98, v98, v106, vcc
	v_xor_b32_e32 v98, v98, v147
	v_sub_u32_e32 v98, v98, v147
	v_mov_b32_e32 v106, v111
	v_or_b32_e32 v104, 19, v146
	v_mov_b32_e32 v149, v100
	v_add_u32_e32 v100, v104, v147
	v_xor_b32_e32 v100, v100, v147
	v_mov_b32_e32 v152, v112
	v_mov_b32_e32 v153, v108
	v_mov_b32_e32 v108, v113
	v_and_b32_e32 v115, 12, v189
	v_or_b32_e32 v115, v115, v188
	s_mov_b64 s[10:11], -1
	v_ashrrev_i32_e32 v119, 31, v118
	s_waitcnt vmcnt(0)
	v_pk_mul_f32 v[122:123], v[128:129], v[120:121]
	v_pk_mul_f32 v[120:121], v[126:127], v[120:121]
	v_pk_fma_f32 v[122:123], v[126:127], v[124:125], v[122:123] neg_lo:[0,0,1] neg_hi:[0,0,1]
	v_pk_fma_f32 v[120:121], v[128:129], v[124:125], v[120:121]
	v_lshlrev_b32_e32 v124, 6, v98
	v_ashrrev_i32_e32 v125, 31, v124
	v_lshlrev_b64 v[124:125], 2, v[124:125]
	v_lshl_add_u64 v[126:127], v[142:143], 0, v[124:125]
	v_lshl_add_u64 v[124:125], v[144:145], 0, v[124:125]
	v_mov_b32_e32 v126, v220
	v_mov_b32_e32 v127, v221
	v_mov_b32_e32 v124, v222
	v_mov_b32_e32 v125, v223
	v_mov_b32_e32 v98, v103
	v_pk_mul_f32 v[110:111], v[106:107], v[124:125]
	s_nop 0
	v_pk_fma_f32 v[110:111], v[98:99], v[126:127], v[110:111] neg_lo:[0,0,1] neg_hi:[0,0,1]
	v_pk_mul_f32 v[98:99], v[98:99], v[124:125]
	s_nop 0
	v_pk_fma_f32 v[98:99], v[106:107], v[126:127], v[98:99]
	v_or_b32_e32 v106, 18, v146
	v_add_u32_e32 v103, v106, v147
	v_xor_b32_e32 v103, v103, v147
	v_mul_hi_u32 v107, v103, v174
	v_mul_lo_u32 v107, v107, s62
	v_sub_u32_e32 v103, v103, v107
	v_cmp_le_u32_e32 vcc, s62, v103
	v_subrev_u32_e32 v107, s62, v103
	s_nop 0
	v_cndmask_b32_e32 v103, v103, v107, vcc
	v_cmp_le_u32_e32 vcc, s62, v103
	v_subrev_u32_e32 v107, s62, v103
	s_nop 0
	v_cndmask_b32_e32 v103, v103, v107, vcc
	v_xor_b32_e32 v103, v103, v147
	v_sub_u32_e32 v103, v103, v147
	v_lshlrev_b32_e32 v124, 6, v103
	v_ashrrev_i32_e32 v125, 31, v124
	v_lshlrev_b64 v[124:125], 2, v[124:125]
	v_lshl_add_u64 v[126:127], v[142:143], 0, v[124:125]
	v_lshl_add_u64 v[124:125], v[144:145], 0, v[124:125]
	v_mov_b32_e32 v128, v224
	v_mov_b32_e32 v129, v225
	v_mov_b32_e32 v124, v226
	v_mov_b32_e32 v125, v227
	v_mul_hi_u32 v103, v100, v174
	v_mul_lo_u32 v103, v103, s62
	v_sub_u32_e32 v100, v100, v103
	v_cmp_le_u32_e32 vcc, s62, v100
	v_subrev_u32_e32 v103, s62, v100
	v_ashrrev_i32_e32 v107, 31, v106
	v_cndmask_b32_e32 v100, v100, v103, vcc
	v_cmp_le_u32_e32 vcc, s62, v100
	v_subrev_u32_e32 v103, s62, v100
	v_pk_mul_f32 v[126:127], v[152:153], v[124:125]
	v_cndmask_b32_e32 v100, v100, v103, vcc
	v_xor_b32_e32 v100, v100, v147
	v_pk_mul_f32 v[124:125], v[148:149], v[124:125]
	v_sub_u32_e32 v100, v100, v147
	v_pk_fma_f32 v[126:127], v[148:149], v[128:129], v[126:127] neg_lo:[0,0,1] neg_hi:[0,0,1]
	v_pk_fma_f32 v[124:125], v[152:153], v[128:129], v[124:125]
	v_lshlrev_b32_e32 v128, 6, v100
	v_ashrrev_i32_e32 v129, 31, v128
	v_lshlrev_b64 v[128:129], 2, v[128:129]
	v_lshl_add_u64 v[148:149], v[142:143], 0, v[128:129]
	v_lshl_add_u64 v[128:129], v[144:145], 0, v[128:129]
	v_mov_b32_e32 v148, v228
	v_mov_b32_e32 v149, v229
	v_mov_b32_e32 v128, v230
	v_mov_b32_e32 v129, v231
	v_mov_b32_e32 v100, v105
	v_cndmask_b32_e64 v103, 0, 1, s[12:13]
	v_cmp_ne_u32_e64 s[8:9], 1, v103
	s_andn2_b64 vcc, exec, s[12:13]
	v_ashrrev_i32_e32 v103, 31, v102
	v_ashrrev_i32_e32 v105, 31, v104
	v_pk_mul_f32 v[112:113], v[108:109], v[128:129]
	s_nop 0
	v_pk_fma_f32 v[112:113], v[100:101], v[148:149], v[112:113] neg_lo:[0,0,1] neg_hi:[0,0,1]
	v_pk_mul_f32 v[100:101], v[100:101], v[128:129]
	s_nop 0
	v_pk_fma_f32 v[100:101], v[108:109], v[148:149], v[100:101]
	v_and_b32_e32 v148, 0x7f, v115
	s_cbranch_vccnz .LBB0_770
; DEVINL unsigned pack2(float a, float b) { hf2 v = {a, b}; hbf2 r = __builtin_convertvector(v, hbf2); return __builtin_bit_cast(unsigned, r); }
;   DEVINL void operator()(Acc& acc, int brow, int bcol) const {
;     ...
;           const float ksc = 0.08838834764831845f;
;           float ff[4], fb[4];
;           _Pragma("unroll") for (int j = 0; j < 4; ++j) {
;             const int row = row0 + j, nl = row & 127;
;             o1[0][j] *= ksc; o1[1][j] *= ksc; o2[0][j] *= ksc; o2[1][j] *= ksc;
;             const size_t o = (size_t)row * 512 + head * 128 + i0;
;             *(unsigned*)(P.k + o) = pack2(o1[0][j], o1[1][j]); *(unsigned*)(P.k + o + 64) = pack2(o2[0][j], o2[1][j]);
	s_load_dwordx4 s[12:15], s[88:89], 0x190
	s_load_dwordx2 s[10:11], s[88:89], 0x1a0
	v_mov_b32_e32 v115, v1
	s_mov_b32 s20, 0x3db504f3
	v_pk_mul_f32 v[128:129], v[122:123], s[20:21] op_sel_hi:[1,0]
	s_waitcnt lgkmcnt(0)
; DEVINL unsigned pack2(float a, float b) { hf2 v = {a, b}; hbf2 r = __builtin_convertvector(v, hbf2); return __builtin_bit_cast(unsigned, r); }
;   DEVINL void operator()(Acc& acc, int brow, int bcol) const {
;     ...
;           const float ksc = 0.08838834764831845f;
;           float ff[4], fb[4];
;           _Pragma("unroll") for (int j = 0; j < 4; ++j) {
;             const int row = row0 + j, nl = row & 127;
;             o1[0][j] *= ksc; o1[1][j] *= ksc; o2[0][j] *= ksc; o2[1][j] *= ksc;
;             const size_t o = (size_t)row * 512 + head * 128 + i0;
;             *(unsigned*)(P.k + o) = pack2(o1[0][j], o1[1][j]); *(unsigned*)(P.k + o + 64) = pack2(o2[0][j], o2[1][j]);
;             ff[j] = exp2f((float)(127 - nl) * lgf); fb[j] = exp2f((float)nl * lgb);
;           }
;           const int chunk = row0 >> 7, m0 = row0 & 127;
;           _Pragma("unroll") for (int n = 0; n < 2; ++n) {
;             const size_t o = ((size_t)(chunk * 4 + head) * 128 + i0 + n) * 128 + m0;
;             *(bf16x4*)(P.kTf + o) = pack4(o1[n][0] * ff[0], o1[n][1] * ff[1], o1[n][2] * ff[2], o1[n][3] * ff[3]);
;             *(bf16x4*)(P.kTf + o + 64 * 128) = pack4(o2[n][0] * ff[0], o2[n][1] * ff[1], o2[n][2] * ff[2], o2[n][3] * ff[3]);
;             *(bf16x4*)(P.kTb + o) = pack4(o1[n][0] * fb[0], o1[n][1] * fb[1], o1[n][2] * fb[2], o1[n][3] * fb[3]);
;             *(bf16x4*)(P.kTb + o + 64 * 128) = pack4(o2[n][0] * fb[0], o2[n][1] * fb[1], o2[n][2] * fb[2], o2[n][3] * fb[3]);
;           }
	v_lshl_add_u64 v[108:109], s[12:13], 0, v[0:1]
	v_lshl_add_u64 v[152:153], v[108:109], 0, v[114:115]
	v_lshlrev_b64 v[154:155], 10, v[118:119]
	v_pk_mul_f32 v[108:109], v[120:121], s[20:21] op_sel_hi:[1,0]
	v_cvt_pk_bf16_f32 v117, v128, v129
	v_lshl_add_u64 v[154:155], v[152:153], 0, v[154:155]
	global_store_dword v[154:155], v117, off
	v_cvt_pk_bf16_f32 v117, v108, v109
	global_store_dword v[154:155], v117, off offset:128
	s_movk_i32 s13, 0x7f
	v_mov_b32_e32 v117, 0x5c
	v_bitop3_b32 v117, v118, s13, v117 bitop3:0x6c
	v_cvt_f32_ubyte0_e32 v117, v117
	v_mul_f32_e32 v149, v186, v117
	s_mov_b32 s12, 0xc2fc0000
	v_cmp_gt_f32_e32 vcc, s12, v149
	v_and_b32_e32 v115, 0x5c, v118
	v_cvt_f32_ubyte0_e32 v115, v115
	v_cndmask_b32_e32 v149, 0, v253, vcc
	v_fmac_f32_e32 v149, v186, v117
	v_exp_f32_e32 v117, v149
	v_cndmask_b32_e32 v149, 0, v252, vcc
	v_pk_mul_f32 v[158:159], v[110:111], s[20:21] op_sel_hi:[1,0]
	v_lshlrev_b64 v[166:167], 10, v[102:103]
	v_ldexp_f32 v154, v117, v149
	v_mul_f32_e32 v117, v185, v115
	v_cmp_gt_f32_e32 vcc, s12, v117
	v_pk_mul_f32 v[160:161], v[98:99], s[20:21] op_sel_hi:[1,0]
	v_lshl_add_u64 v[166:167], v[152:153], 0, v[166:167]
	v_cndmask_b32_e32 v117, 0, v253, vcc
	v_fmac_f32_e32 v117, v185, v115
	v_exp_f32_e32 v115, v117
	v_cndmask_b32_e32 v117, 0, v252, vcc
	v_lshlrev_b64 v[170:171], 10, v[106:107]
	v_pk_mul_f32 v[168:169], v[124:125], s[20:21] op_sel_hi:[1,0]
	v_ldexp_f32 v156, v115, v117
	v_cvt_pk_bf16_f32 v117, v158, v159
	global_store_dword v[166:167], v117, off
	v_cvt_pk_bf16_f32 v117, v160, v161
	global_store_dword v[166:167], v117, off offset:128
	v_mov_b32_e32 v117, 0x5d
	v_bitop3_b32 v117, v102, s13, v117 bitop3:0x6c
	v_cvt_f32_ubyte0_e32 v117, v117
	v_mul_f32_e32 v149, v186, v117
	v_cmp_gt_f32_e32 vcc, s12, v149
	v_and_b32_e32 v115, 0x5d, v102
	v_cvt_f32_ubyte0_e32 v115, v115
	v_cndmask_b32_e32 v149, 0, v253, vcc
	v_fmac_f32_e32 v149, v186, v117
	v_exp_f32_e32 v117, v149
	v_cndmask_b32_e32 v149, 0, v252, vcc
	v_pk_mul_f32 v[166:167], v[126:127], s[20:21] op_sel_hi:[1,0]
	v_lshl_add_u64 v[170:171], v[152:153], 0, v[170:171]
	v_ldexp_f32 v155, v117, v149
	v_mul_f32_e32 v117, v185, v115
	v_cmp_gt_f32_e32 vcc, s12, v117
	v_pk_mul_f32 v[188:189], v[112:113], s[20:21] op_sel_hi:[1,0]
	v_lshlrev_b64 v[192:193], 10, v[104:105]
	v_cndmask_b32_e32 v117, 0, v253, vcc
	v_fmac_f32_e32 v117, v185, v115
	v_exp_f32_e32 v115, v117
	v_cndmask_b32_e32 v117, 0, v252, vcc
	v_pk_mul_f32 v[190:191], v[100:101], s[20:21] op_sel_hi:[1,0]
	v_lshl_add_u64 v[152:153], v[152:153], 0, v[192:193]
	v_ldexp_f32 v157, v115, v117
	v_cvt_pk_bf16_f32 v117, v166, v167
	global_store_dword v[170:171], v117, off
	v_cvt_pk_bf16_f32 v117, v168, v169
	global_store_dword v[170:171], v117, off offset:128
	v_mov_b32_e32 v117, 0x5e
	v_bitop3_b32 v117, v106, s13, v117 bitop3:0x6c
	v_cvt_f32_ubyte0_e32 v117, v117
	v_mul_f32_e32 v149, v186, v117
	v_cmp_gt_f32_e32 vcc, s12, v149
	v_and_b32_e32 v115, 0x5e, v106
	v_cvt_f32_ubyte0_e32 v115, v115
	v_cndmask_b32_e32 v149, 0, v253, vcc
	v_fmac_f32_e32 v149, v186, v117
	v_exp_f32_e32 v117, v149
	v_cndmask_b32_e32 v149, 0, v252, vcc
	v_mov_b32_e32 v192, v128
	v_mov_b32_e32 v193, v158
	v_ldexp_f32 v170, v117, v149
	v_mul_f32_e32 v117, v185, v115
	v_cmp_gt_f32_e32 vcc, s12, v117
	v_mov_b32_e32 v196, v166
	v_mov_b32_e32 v197, v188
	v_cndmask_b32_e32 v117, 0, v253, vcc
	v_fmac_f32_e32 v117, v185, v115
	v_exp_f32_e32 v115, v117
	v_cndmask_b32_e32 v117, 0, v252, vcc
	v_pk_mul_f32 v[194:195], v[154:155], v[192:193]
	v_mov_b32_e32 v202, v168
	v_ldexp_f32 v172, v115, v117
	v_cvt_pk_bf16_f32 v117, v188, v189
	global_store_dword v[152:153], v117, off
	v_cvt_pk_bf16_f32 v117, v190, v191
	global_store_dword v[152:153], v117, off offset:128
	v_mov_b32_e32 v117, 0x5f
	v_bitop3_b32 v117, v104, s13, v117 bitop3:0x6c
	v_cvt_f32_ubyte0_e32 v117, v117
	v_mul_f32_e32 v149, v186, v117
	v_cmp_gt_f32_e32 vcc, s12, v149
	v_and_b32_e32 v115, 0x5f, v104
	v_cvt_f32_ubyte0_e32 v115, v115
	v_cndmask_b32_e32 v149, 0, v253, vcc
	v_fmac_f32_e32 v149, v186, v117
	v_exp_f32_e32 v117, v149
	v_cndmask_b32_e32 v149, 0, v252, vcc
	v_cvt_pk_bf16_f32 v194, v194, v195
	v_mov_b32_e32 v203, v190
	v_ldexp_f32 v171, v117, v149
	v_mul_f32_e32 v117, v185, v115
	v_cmp_gt_f32_e32 vcc, s12, v117
	v_pk_mul_f32 v[198:199], v[170:171], v[196:197]
	v_pk_mul_f32 v[204:205], v[170:171], v[202:203]
	v_cndmask_b32_e32 v117, 0, v253, vcc
	v_fmac_f32_e32 v117, v185, v115
	v_exp_f32_e32 v115, v117
	v_cndmask_b32_e32 v117, 0, v252, vcc
	v_cvt_pk_bf16_f32 v195, v198, v199
	s_movk_i32 s12, 0x4000
	v_ldexp_f32 v173, v115, v117
	v_ashrrev_i32_e32 v117, 31, v116
	v_lshlrev_b64 v[152:153], 14, v[116:117]
	v_lshl_or_b32 v115, v183, 7, v152
	v_or_b32_e32 v152, v115, v148
	v_lshlrev_b64 v[152:153], 1, v[152:153]
	v_lshl_add_u64 v[198:199], s[14:15], 0, v[152:153]
	global_store_dwordx2 v[198:199], v[194:195], off offset:32
	v_mov_b32_e32 v194, v108
	v_mov_b32_e32 v195, v160
	v_pk_mul_f32 v[200:201], v[154:155], v[194:195]
	v_pk_mul_f32 v[192:193], v[156:157], v[192:193]
	v_cvt_pk_bf16_f32 v200, v200, v201
	v_cvt_pk_bf16_f32 v201, v204, v205
	v_add_co_u32_e32 v204, vcc, s12, v198
	v_pk_mul_f32 v[196:197], v[172:173], v[196:197]
	s_nop 0
	v_addc_co_u32_e32 v205, vcc, 0, v199, vcc
	v_cvt_pk_bf16_f32 v192, v192, v193
	v_cvt_pk_bf16_f32 v193, v196, v197
	v_lshl_add_u64 v[152:153], s[10:11], 0, v[152:153]
	global_store_dwordx2 v[204:205], v[200:201], off offset:32
	global_store_dwordx2 v[152:153], v[192:193], off offset:32
	v_pk_mul_f32 v[192:193], v[156:157], v[194:195]
	v_pk_mul_f32 v[194:195], v[172:173], v[202:203]
	v_mov_b32_e32 v158, v129
	v_mov_b32_e32 v188, v167
	v_cvt_pk_bf16_f32 v192, v192, v193
	v_cvt_pk_bf16_f32 v193, v194, v195
	v_add_co_u32_e32 v194, vcc, s12, v152
	v_pk_mul_f32 v[128:129], v[154:155], v[158:159]
	v_pk_mul_f32 v[166:167], v[170:171], v[188:189]
	v_addc_co_u32_e32 v195, vcc, 0, v153, vcc
	v_cvt_pk_bf16_f32 v128, v128, v129
	v_cvt_pk_bf16_f32 v129, v166, v167
	v_mov_b32_e32 v160, v109
	v_mov_b32_e32 v190, v169
	global_store_dwordx2 v[194:195], v[192:193], off offset:32
	global_store_dwordx2 v[198:199], v[128:129], off offset:288
	v_pk_mul_f32 v[108:109], v[154:155], v[160:161]
	v_pk_mul_f32 v[128:129], v[170:171], v[190:191]
	v_cvt_pk_bf16_f32 v108, v108, v109
	v_cvt_pk_bf16_f32 v109, v128, v129
	global_store_dwordx2 v[204:205], v[108:109], off offset:288
	v_pk_mul_f32 v[108:109], v[156:157], v[158:159]
	v_pk_mul_f32 v[128:129], v[172:173], v[188:189]
	v_cvt_pk_bf16_f32 v108, v108, v109
	v_cvt_pk_bf16_f32 v109, v128, v129
	global_store_dwordx2 v[152:153], v[108:109], off offset:288
	v_pk_mul_f32 v[108:109], v[156:157], v[160:161]
	v_pk_mul_f32 v[128:129], v[172:173], v[190:191]
	v_cvt_pk_bf16_f32 v108, v108, v109
	v_cvt_pk_bf16_f32 v109, v128, v129
	s_mov_b64 s[10:11], 0
	global_store_dwordx2 v[194:195], v[108:109], off offset:288

;   DEVINL void operator()(Acc& acc, int brow, int bcol) const {
;     ...
;         const int row0 = brow + ai * 128 + wr * 64 + m * 16 + fq * 4;
;         float o1[2][4], o2[2][4];
;         _Pragma("unroll") for (int j = 0; j < 4; ++j) {
;           const int pos = (row0 + j) % L;
;           const float2 cs = *(const float2*)(P.ctab + pos * 64 + i0), sn = *(const float2*)(P.stab + pos * 64 + i0);
;           o1[0][j] = acc[ai][0][m][0][j] * cs.x - acc[ai][1][m][0][j] * sn.x; o2[0][j] = acc[ai][0][m][0][j] * sn.x + acc[ai][1][m][0][j] * cs.x;
;           o1[1][j] = acc[ai][0][m][1][j] * cs.y - acc[ai][1][m][1][j] * sn.y; o2[1][j] = acc[ai][0][m][1][j] * sn.y + acc[ai][1][m][1][j] * cs.y;
;         }
.LBB0_772:
	v_or_b32_e32 v98, 32, v146
	v_add_u32_e32 v99, v98, v147
	v_xor_b32_e32 v99, v99, v147
	v_mul_hi_u32 v100, v99, v174
	v_mul_lo_u32 v100, v100, s62
	v_sub_u32_e32 v99, v99, v100
	v_cmp_le_u32_e32 vcc, s62, v99
	v_subrev_u32_e32 v100, s62, v99
	v_mov_b32_e32 v106, v86
	v_cndmask_b32_e32 v99, v99, v100, vcc
	v_cmp_le_u32_e32 vcc, s62, v99
	v_subrev_u32_e32 v100, s62, v99
	v_or_b32_e32 v86, 33, v146
	v_cndmask_b32_e32 v99, v99, v100, vcc
	v_xor_b32_e32 v99, v99, v147
	v_sub_u32_e32 v99, v99, v147
	v_lshlrev_b32_e32 v100, 6, v99
	v_ashrrev_i32_e32 v101, 31, v100
	v_lshlrev_b64 v[100:101], 2, v[100:101]
	v_lshl_add_u64 v[102:103], v[142:143], 0, v[100:101]
	v_lshl_add_u64 v[100:101], v[144:145], 0, v[100:101]
	global_load_dwordx2 v[220:221], v[102:103], off offset:256
	global_load_dwordx2 v[222:223], v[100:101], off offset:256
	global_load_dwordx2 v[224:225], v[102:103], off offset:512
	global_load_dwordx2 v[226:227], v[100:101], off offset:512
	global_load_dwordx2 v[228:229], v[102:103], off offset:768
	global_load_dwordx2 v[230:231], v[100:101], off offset:768
	global_load_dwordx2 v[104:105], v[102:103], off
	s_nop 0
	global_load_dwordx2 v[100:101], v[100:101], off
	v_mov_b32_e32 v107, v82
	v_add_u32_e32 v82, v86, v147
	v_xor_b32_e32 v82, v82, v147
	v_mov_b32_e32 v109, v90
	v_mul_hi_u32 v90, v82, v174
	v_mul_lo_u32 v90, v90, s62
	v_sub_u32_e32 v82, v82, v90
	v_cmp_le_u32_e32 vcc, s62, v82
	v_subrev_u32_e32 v90, s62, v82
	v_mov_b32_e32 v108, v94
	v_cndmask_b32_e32 v82, v82, v90, vcc
	v_cmp_le_u32_e32 vcc, s62, v82
	v_subrev_u32_e32 v90, s62, v82
	v_mov_b32_e32 v110, v88
	v_cndmask_b32_e32 v82, v82, v90, vcc
	v_xor_b32_e32 v82, v82, v147
	v_sub_u32_e32 v82, v82, v147
	v_mov_b32_e32 v90, v95
	v_or_b32_e32 v88, 35, v146
	v_mov_b32_e32 v111, v84
	v_add_u32_e32 v84, v88, v147
	v_xor_b32_e32 v84, v84, v147
	v_mov_b32_e32 v112, v96
	v_mov_b32_e32 v113, v92
	v_mov_b32_e32 v92, v97
	s_mov_b64 s[10:11], -1
	v_ashrrev_i32_e32 v99, 31, v98
	s_waitcnt vmcnt(0)
	v_pk_mul_f32 v[102:103], v[108:109], v[100:101]
	v_pk_mul_f32 v[100:101], v[106:107], v[100:101]
	v_pk_fma_f32 v[102:103], v[106:107], v[104:105], v[102:103] neg_lo:[0,0,1] neg_hi:[0,0,1]
	v_pk_fma_f32 v[100:101], v[108:109], v[104:105], v[100:101]
	v_lshlrev_b32_e32 v104, 6, v82
	v_ashrrev_i32_e32 v105, 31, v104
	v_lshlrev_b64 v[104:105], 2, v[104:105]
	v_lshl_add_u64 v[106:107], v[142:143], 0, v[104:105]
	v_lshl_add_u64 v[104:105], v[144:145], 0, v[104:105]
	v_mov_b32_e32 v106, v220
	v_mov_b32_e32 v107, v221
	v_mov_b32_e32 v104, v222
	v_mov_b32_e32 v105, v223
	v_mov_b32_e32 v82, v87
	v_pk_mul_f32 v[94:95], v[90:91], v[104:105]
	s_nop 0
	v_pk_fma_f32 v[94:95], v[82:83], v[106:107], v[94:95] neg_lo:[0,0,1] neg_hi:[0,0,1]
	v_pk_mul_f32 v[82:83], v[82:83], v[104:105]
	s_nop 0
	v_pk_fma_f32 v[82:83], v[90:91], v[106:107], v[82:83]
	v_or_b32_e32 v90, 34, v146
	v_add_u32_e32 v87, v90, v147
	v_xor_b32_e32 v87, v87, v147
	v_mul_hi_u32 v91, v87, v174
	v_mul_lo_u32 v91, v91, s62
	v_sub_u32_e32 v87, v87, v91
	v_cmp_le_u32_e32 vcc, s62, v87
	v_subrev_u32_e32 v91, s62, v87
	s_nop 0
	v_cndmask_b32_e32 v87, v87, v91, vcc
	v_cmp_le_u32_e32 vcc, s62, v87
	v_subrev_u32_e32 v91, s62, v87
	s_nop 0
	v_cndmask_b32_e32 v87, v87, v91, vcc
	v_xor_b32_e32 v87, v87, v147
	v_sub_u32_e32 v87, v87, v147
	v_lshlrev_b32_e32 v104, 6, v87
	v_ashrrev_i32_e32 v105, 31, v104
	v_lshlrev_b64 v[104:105], 2, v[104:105]
	v_lshl_add_u64 v[106:107], v[142:143], 0, v[104:105]
	v_lshl_add_u64 v[104:105], v[144:145], 0, v[104:105]
	v_mov_b32_e32 v108, v224
	v_mov_b32_e32 v109, v225
	v_mov_b32_e32 v104, v226
	v_mov_b32_e32 v105, v227
	v_mul_hi_u32 v87, v84, v174
	v_mul_lo_u32 v87, v87, s62
	v_sub_u32_e32 v84, v84, v87
	v_cmp_le_u32_e32 vcc, s62, v84
	v_subrev_u32_e32 v87, s62, v84
	v_ashrrev_i32_e32 v91, 31, v90
	v_cndmask_b32_e32 v84, v84, v87, vcc
	v_cmp_le_u32_e32 vcc, s62, v84
	v_subrev_u32_e32 v87, s62, v84
	v_pk_mul_f32 v[106:107], v[112:113], v[104:105]
	v_cndmask_b32_e32 v84, v84, v87, vcc
	v_xor_b32_e32 v84, v84, v147
	v_pk_mul_f32 v[104:105], v[110:111], v[104:105]
	v_sub_u32_e32 v84, v84, v147
	v_pk_fma_f32 v[106:107], v[110:111], v[108:109], v[106:107] neg_lo:[0,0,1] neg_hi:[0,0,1]
	v_pk_fma_f32 v[104:105], v[112:113], v[108:109], v[104:105]
	v_lshlrev_b32_e32 v108, 6, v84
	v_ashrrev_i32_e32 v109, 31, v108
	v_lshlrev_b64 v[108:109], 2, v[108:109]
	v_lshl_add_u64 v[110:111], v[142:143], 0, v[108:109]
	v_lshl_add_u64 v[108:109], v[144:145], 0, v[108:109]
	v_mov_b32_e32 v110, v228
	v_mov_b32_e32 v111, v229
	v_mov_b32_e32 v108, v230
	v_mov_b32_e32 v109, v231
	v_mov_b32_e32 v84, v89
	s_and_b64 vcc, exec, s[8:9]
	v_ashrrev_i32_e32 v87, 31, v86
	v_ashrrev_i32_e32 v89, 31, v88
	v_pk_mul_f32 v[96:97], v[92:93], v[108:109]
	s_nop 0
	v_pk_fma_f32 v[96:97], v[84:85], v[110:111], v[96:97] neg_lo:[0,0,1] neg_hi:[0,0,1]
	v_pk_mul_f32 v[84:85], v[84:85], v[108:109]
	s_nop 0
	v_pk_fma_f32 v[84:85], v[92:93], v[110:111], v[84:85]
	s_cbranch_vccnz .LBB0_774
; DEVINL unsigned pack2(float a, float b) { hf2 v = {a, b}; hbf2 r = __builtin_convertvector(v, hbf2); return __builtin_bit_cast(unsigned, r); }
;   DEVINL void operator()(Acc& acc, int brow, int bcol) const {
;     ...
;           const float ksc = 0.08838834764831845f;
;           float ff[4], fb[4];
;           _Pragma("unroll") for (int j = 0; j < 4; ++j) {
;             const int row = row0 + j, nl = row & 127;
;             o1[0][j] *= ksc; o1[1][j] *= ksc; o2[0][j] *= ksc; o2[1][j] *= ksc;
;             const size_t o = (size_t)row * 512 + head * 128 + i0;
;             *(unsigned*)(P.k + o) = pack2(o1[0][j], o1[1][j]); *(unsigned*)(P.k + o + 64) = pack2(o2[0][j], o2[1][j]);
;             ff[j] = exp2f((float)(127 - nl) * lgf); fb[j] = exp2f((float)nl * lgb);
;           }
;           const int chunk = row0 >> 7, m0 = row0 & 127;
;           _Pragma("unroll") for (int n = 0; n < 2; ++n) {
;             const size_t o = ((size_t)(chunk * 4 + head) * 128 + i0 + n) * 128 + m0;
;             *(bf16x4*)(P.kTf + o) = pack4(o1[n][0] * ff[0], o1[n][1] * ff[1], o1[n][2] * ff[2], o1[n][3] * ff[3]);
;             *(bf16x4*)(P.kTf + o + 64 * 128) = pack4(o2[n][0] * ff[0], o2[n][1] * ff[1], o2[n][2] * ff[2], o2[n][3] * ff[3]);
;             *(bf16x4*)(P.kTb + o) = pack4(o1[n][0] * fb[0], o1[n][1] * fb[1], o1[n][2] * fb[2], o1[n][3] * fb[3]);
;             *(bf16x4*)(P.kTb + o + 64 * 128) = pack4(o2[n][0] * fb[0], o2[n][1] * fb[1], o2[n][2] * fb[2], o2[n][3] * fb[3]);
;           }
	s_load_dwordx4 s[12:15], s[88:89], 0x190
	s_load_dwordx2 s[10:11], s[88:89], 0x1a0
	v_mov_b32_e32 v115, v1
	s_mov_b32 s20, 0x3db504f3
	v_pk_mul_f32 v[108:109], v[102:103], s[20:21] op_sel_hi:[1,0]
	s_waitcnt lgkmcnt(0)
	v_lshl_add_u64 v[92:93], s[12:13], 0, v[0:1]
	v_lshl_add_u64 v[110:111], v[92:93], 0, v[114:115]
	v_lshlrev_b64 v[112:113], 10, v[98:99]
	v_pk_mul_f32 v[92:93], v[100:101], s[20:21] op_sel_hi:[1,0]
	v_cvt_pk_bf16_f32 v117, v108, v109
	v_lshl_add_u64 v[112:113], v[110:111], 0, v[112:113]
	global_store_dword v[112:113], v117, off
	v_cvt_pk_bf16_f32 v117, v92, v93
	global_store_dword v[112:113], v117, off offset:128
	s_movk_i32 s13, 0x7f
	v_mov_b32_e32 v112, 0x6c
	v_bitop3_b32 v112, v98, s13, v112 bitop3:0x6c
	v_cvt_f32_ubyte0_e32 v112, v112
	v_mul_f32_e32 v113, v186, v112
	s_mov_b32 s12, 0xc2fc0000
	v_cmp_gt_f32_e32 vcc, s12, v113
	v_and_b32_e32 v115, 0x6c, v98
	v_pk_mul_f32 v[120:121], v[94:95], s[20:21] op_sel_hi:[1,0]
	v_cndmask_b32_e32 v113, 0, v253, vcc
	v_fmac_f32_e32 v113, v186, v112
	v_exp_f32_e32 v112, v113
	v_cndmask_b32_e32 v113, 0, v252, vcc
	v_lshlrev_b64 v[124:125], 10, v[86:87]
	v_pk_mul_f32 v[122:123], v[82:83], s[20:21] op_sel_hi:[1,0]
	v_ldexp_f32 v112, v112, v113
	v_cvt_f32_ubyte0_e32 v113, v115
	v_mul_f32_e32 v115, v185, v113
	v_cmp_gt_f32_e32 vcc, s12, v115
	v_lshl_add_u64 v[124:125], v[110:111], 0, v[124:125]
	v_lshlrev_b64 v[128:129], 10, v[90:91]
	v_cndmask_b32_e32 v115, 0, v253, vcc
	v_fmac_f32_e32 v115, v185, v113
	v_exp_f32_e32 v113, v115
	v_cndmask_b32_e32 v115, 0, v252, vcc
	v_pk_mul_f32 v[126:127], v[104:105], s[20:21] op_sel_hi:[1,0]
	v_lshl_add_u64 v[128:129], v[110:111], 0, v[128:129]
	v_ldexp_f32 v118, v113, v115
	v_cvt_pk_bf16_f32 v113, v120, v121
	global_store_dword v[124:125], v113, off
	v_cvt_pk_bf16_f32 v113, v122, v123
	global_store_dword v[124:125], v113, off offset:128
	v_mov_b32_e32 v113, 0x6d
	v_bitop3_b32 v113, v86, s13, v113 bitop3:0x6c
	v_cvt_f32_ubyte0_e32 v113, v113
	v_mul_f32_e32 v117, v186, v113
	v_cmp_gt_f32_e32 vcc, s12, v117
	v_and_b32_e32 v115, 0x6d, v86
	v_cvt_f32_ubyte0_e32 v115, v115
	v_cndmask_b32_e32 v117, 0, v253, vcc
	v_fmac_f32_e32 v117, v186, v113
	v_exp_f32_e32 v113, v117
	v_cndmask_b32_e32 v117, 0, v252, vcc
	v_pk_mul_f32 v[124:125], v[106:107], s[20:21] op_sel_hi:[1,0]
	v_pk_mul_f32 v[154:155], v[96:97], s[20:21] op_sel_hi:[1,0]
	v_ldexp_f32 v113, v113, v117
	v_mul_f32_e32 v117, v185, v115
	v_cmp_gt_f32_e32 vcc, s12, v117
	v_lshlrev_b64 v[158:159], 10, v[88:89]
	v_pk_mul_f32 v[156:157], v[84:85], s[20:21] op_sel_hi:[1,0]
	v_cndmask_b32_e32 v117, 0, v253, vcc
	v_fmac_f32_e32 v117, v185, v115
	v_exp_f32_e32 v115, v117
	v_cndmask_b32_e32 v117, 0, v252, vcc
	v_lshl_add_u64 v[110:111], v[110:111], 0, v[158:159]
	v_mov_b32_e32 v158, v108
	v_ldexp_f32 v119, v115, v117
	v_cvt_pk_bf16_f32 v117, v124, v125
	global_store_dword v[128:129], v117, off
	v_cvt_pk_bf16_f32 v117, v126, v127
	global_store_dword v[128:129], v117, off offset:128
	v_mov_b32_e32 v117, 0x6e
	v_bitop3_b32 v117, v90, s13, v117 bitop3:0x6c
	v_cvt_f32_ubyte0_e32 v117, v117
	v_mul_f32_e32 v128, v186, v117
	v_cmp_gt_f32_e32 vcc, s12, v128
	v_and_b32_e32 v115, 0x6e, v90
	v_cvt_f32_ubyte0_e32 v115, v115
	v_cndmask_b32_e32 v128, 0, v253, vcc
	v_fmac_f32_e32 v128, v186, v117
	v_exp_f32_e32 v117, v128
	v_cndmask_b32_e32 v128, 0, v252, vcc
	v_mov_b32_e32 v159, v120
	v_mov_b32_e32 v166, v124
	v_ldexp_f32 v128, v117, v128
	v_mul_f32_e32 v117, v185, v115
	v_cmp_gt_f32_e32 vcc, s12, v117
	v_mov_b32_e32 v167, v154
	v_pk_mul_f32 v[160:161], v[112:113], v[158:159]
	v_cndmask_b32_e32 v117, 0, v253, vcc
	v_fmac_f32_e32 v117, v185, v115
	v_exp_f32_e32 v115, v117
	v_cndmask_b32_e32 v117, 0, v252, vcc
	v_cvt_pk_bf16_f32 v160, v160, v161
	v_mov_b32_e32 v172, v126
	v_ldexp_f32 v152, v115, v117
	v_cvt_pk_bf16_f32 v117, v154, v155
	global_store_dword v[110:111], v117, off
	v_cvt_pk_bf16_f32 v117, v156, v157
	global_store_dword v[110:111], v117, off offset:128
	v_mov_b32_e32 v110, 0x6f
	v_bitop3_b32 v110, v88, s13, v110 bitop3:0x6c
	v_cvt_f32_ubyte0_e32 v110, v110
	v_mul_f32_e32 v111, v186, v110
	v_cmp_gt_f32_e32 vcc, s12, v111
	v_and_b32_e32 v115, 0x6f, v88
	v_ashrrev_i32_e32 v117, 31, v116
	v_cndmask_b32_e32 v111, 0, v253, vcc
	v_fmac_f32_e32 v111, v186, v110
	v_exp_f32_e32 v110, v111
	v_cndmask_b32_e32 v111, 0, v252, vcc
	v_mov_b32_e32 v173, v156
	v_pk_mul_f32 v[158:159], v[118:119], v[158:159]
	v_ldexp_f32 v129, v110, v111
	v_cvt_f32_ubyte0_e32 v110, v115
	v_mul_f32_e32 v111, v185, v110
	v_cmp_gt_f32_e32 vcc, s12, v111
	v_pk_mul_f32 v[168:169], v[128:129], v[166:167]
	v_pk_mul_f32 v[188:189], v[128:129], v[172:173]
	v_cndmask_b32_e32 v111, 0, v253, vcc
	v_fmac_f32_e32 v111, v185, v110
	v_exp_f32_e32 v110, v111
	v_cndmask_b32_e32 v111, 0, v252, vcc
	v_cvt_pk_bf16_f32 v161, v168, v169
	s_movk_i32 s12, 0x4000
	v_ldexp_f32 v153, v110, v111
	v_lshlrev_b64 v[110:111], 14, v[116:117]
	v_lshl_or_b32 v110, v183, 7, v110
	v_or_b32_e32 v110, v110, v148
	v_lshlrev_b64 v[110:111], 1, v[110:111]
	v_lshl_add_u64 v[168:169], s[14:15], 0, v[110:111]
	global_store_dwordx2 v[168:169], v[160:161], off offset:64
	v_mov_b32_e32 v160, v92
	v_mov_b32_e32 v161, v122
	v_pk_mul_f32 v[170:171], v[112:113], v[160:161]
	v_pk_mul_f32 v[166:167], v[152:153], v[166:167]
	v_cvt_pk_bf16_f32 v170, v170, v171
	v_cvt_pk_bf16_f32 v171, v188, v189
	v_add_co_u32_e32 v188, vcc, s12, v168
	v_cvt_pk_bf16_f32 v158, v158, v159
	s_nop 0
	v_addc_co_u32_e32 v189, vcc, 0, v169, vcc
	v_cvt_pk_bf16_f32 v159, v166, v167
	v_lshl_add_u64 v[110:111], s[10:11], 0, v[110:111]
	global_store_dwordx2 v[188:189], v[170:171], off offset:64
	global_store_dwordx2 v[110:111], v[158:159], off offset:64
	v_pk_mul_f32 v[158:159], v[118:119], v[160:161]
	v_pk_mul_f32 v[160:161], v[152:153], v[172:173]
	v_mov_b32_e32 v120, v109
	v_mov_b32_e32 v154, v125
	v_cvt_pk_bf16_f32 v158, v158, v159
	v_cvt_pk_bf16_f32 v159, v160, v161
	v_add_co_u32_e32 v160, vcc, s12, v110
	v_pk_mul_f32 v[108:109], v[112:113], v[120:121]
	v_pk_mul_f32 v[124:125], v[128:129], v[154:155]
	v_addc_co_u32_e32 v161, vcc, 0, v111, vcc
	v_cvt_pk_bf16_f32 v108, v108, v109
	v_cvt_pk_bf16_f32 v109, v124, v125
	v_mov_b32_e32 v122, v93
	v_mov_b32_e32 v156, v127
	global_store_dwordx2 v[160:161], v[158:159], off offset:64
	global_store_dwordx2 v[168:169], v[108:109], off offset:320
	v_pk_mul_f32 v[92:93], v[112:113], v[122:123]
	v_pk_mul_f32 v[108:109], v[128:129], v[156:157]
	v_cvt_pk_bf16_f32 v92, v92, v93
	v_cvt_pk_bf16_f32 v93, v108, v109
	global_store_dwordx2 v[188:189], v[92:93], off offset:320
	v_pk_mul_f32 v[92:93], v[118:119], v[120:121]
	v_pk_mul_f32 v[108:109], v[152:153], v[154:155]
	v_cvt_pk_bf16_f32 v92, v92, v93
	v_cvt_pk_bf16_f32 v93, v108, v109
	global_store_dwordx2 v[110:111], v[92:93], off offset:320
	v_pk_mul_f32 v[92:93], v[118:119], v[122:123]
	v_pk_mul_f32 v[108:109], v[152:153], v[156:157]
	v_cvt_pk_bf16_f32 v92, v92, v93
	v_cvt_pk_bf16_f32 v93, v108, v109
	s_mov_b64 s[10:11], 0
	global_store_dwordx2 v[160:161], v[92:93], off offset:320

;   DEVINL void operator()(Acc& acc, int brow, int bcol) const {
;     ...
;         const int row0 = brow + ai * 128 + wr * 64 + m * 16 + fq * 4;
;         float o1[2][4], o2[2][4];
;         _Pragma("unroll") for (int j = 0; j < 4; ++j) {
;           const int pos = (row0 + j) % L;
;           const float2 cs = *(const float2*)(P.ctab + pos * 64 + i0), sn = *(const float2*)(P.stab + pos * 64 + i0);
;           o1[0][j] = acc[ai][0][m][0][j] * cs.x - acc[ai][1][m][0][j] * sn.x; o2[0][j] = acc[ai][0][m][0][j] * sn.x + acc[ai][1][m][0][j] * cs.x;
;           o1[1][j] = acc[ai][0][m][1][j] * cs.y - acc[ai][1][m][1][j] * sn.y; o2[1][j] = acc[ai][0][m][1][j] * sn.y + acc[ai][1][m][1][j] * cs.y;
;         }
.LBB0_776:
	v_or_b32_e32 v82, 48, v146
	v_add_u32_e32 v83, v82, v147
	v_xor_b32_e32 v83, v83, v147
	v_mul_hi_u32 v84, v83, v174
	v_mul_lo_u32 v84, v84, s62
	v_sub_u32_e32 v83, v83, v84
	v_cmp_le_u32_e32 vcc, s62, v83
	v_subrev_u32_e32 v84, s62, v83
	v_mov_b32_e32 v90, v70
	v_cndmask_b32_e32 v83, v83, v84, vcc
	v_cmp_le_u32_e32 vcc, s62, v83
	v_subrev_u32_e32 v84, s62, v83
	v_or_b32_e32 v70, 49, v146
	v_cndmask_b32_e32 v83, v83, v84, vcc
	v_xor_b32_e32 v83, v83, v147
	v_sub_u32_e32 v83, v83, v147
	v_lshlrev_b32_e32 v84, 6, v83
	v_ashrrev_i32_e32 v85, 31, v84
	v_lshlrev_b64 v[84:85], 2, v[84:85]
	v_lshl_add_u64 v[86:87], v[142:143], 0, v[84:85]
	v_lshl_add_u64 v[84:85], v[144:145], 0, v[84:85]
	global_load_dwordx2 v[220:221], v[86:87], off offset:256
	global_load_dwordx2 v[222:223], v[84:85], off offset:256
	global_load_dwordx2 v[224:225], v[86:87], off offset:512
	global_load_dwordx2 v[226:227], v[84:85], off offset:512
	global_load_dwordx2 v[228:229], v[86:87], off offset:768
	global_load_dwordx2 v[230:231], v[84:85], off offset:768
	global_load_dwordx2 v[88:89], v[86:87], off
	s_nop 0
	global_load_dwordx2 v[84:85], v[84:85], off
	v_mov_b32_e32 v91, v66
	v_add_u32_e32 v66, v70, v147
	v_xor_b32_e32 v66, v66, v147
	v_mov_b32_e32 v93, v74
	v_mul_hi_u32 v74, v66, v174
	v_mul_lo_u32 v74, v74, s62
	v_sub_u32_e32 v66, v66, v74
	v_cmp_le_u32_e32 vcc, s62, v66
	v_subrev_u32_e32 v74, s62, v66
	v_mov_b32_e32 v92, v78
	v_cndmask_b32_e32 v66, v66, v74, vcc
	v_cmp_le_u32_e32 vcc, s62, v66
	v_subrev_u32_e32 v74, s62, v66
	v_mov_b32_e32 v94, v72
	v_cndmask_b32_e32 v66, v66, v74, vcc
	v_xor_b32_e32 v66, v66, v147
	v_sub_u32_e32 v66, v66, v147
	v_mov_b32_e32 v74, v79
	v_or_b32_e32 v72, 51, v146
	v_mov_b32_e32 v95, v68
	v_add_u32_e32 v68, v72, v147
	v_xor_b32_e32 v68, v68, v147
	v_mov_b32_e32 v96, v80
	v_mov_b32_e32 v97, v76
	v_mov_b32_e32 v76, v81
	s_mov_b64 s[10:11], -1
	v_ashrrev_i32_e32 v83, 31, v82
	s_waitcnt vmcnt(0)
	v_pk_mul_f32 v[86:87], v[92:93], v[84:85]
	v_pk_mul_f32 v[84:85], v[90:91], v[84:85]
	v_pk_fma_f32 v[86:87], v[90:91], v[88:89], v[86:87] neg_lo:[0,0,1] neg_hi:[0,0,1]
	v_pk_fma_f32 v[84:85], v[92:93], v[88:89], v[84:85]
	v_lshlrev_b32_e32 v88, 6, v66
	v_ashrrev_i32_e32 v89, 31, v88
	v_lshlrev_b64 v[88:89], 2, v[88:89]
	v_lshl_add_u64 v[90:91], v[142:143], 0, v[88:89]
	v_lshl_add_u64 v[88:89], v[144:145], 0, v[88:89]
	v_mov_b32_e32 v90, v220
	v_mov_b32_e32 v91, v221
	v_mov_b32_e32 v88, v222
	v_mov_b32_e32 v89, v223
	v_mov_b32_e32 v66, v71
	v_pk_mul_f32 v[78:79], v[74:75], v[88:89]
	s_nop 0
	v_pk_fma_f32 v[78:79], v[66:67], v[90:91], v[78:79] neg_lo:[0,0,1] neg_hi:[0,0,1]
	v_pk_mul_f32 v[66:67], v[66:67], v[88:89]
	s_nop 0
	v_pk_fma_f32 v[66:67], v[74:75], v[90:91], v[66:67]
	v_or_b32_e32 v74, 50, v146
	v_add_u32_e32 v71, v74, v147
	v_xor_b32_e32 v71, v71, v147
	v_mul_hi_u32 v75, v71, v174
	v_mul_lo_u32 v75, v75, s62
	v_sub_u32_e32 v71, v71, v75
	v_cmp_le_u32_e32 vcc, s62, v71
	v_subrev_u32_e32 v75, s62, v71
	s_nop 0
	v_cndmask_b32_e32 v71, v71, v75, vcc
	v_cmp_le_u32_e32 vcc, s62, v71
	v_subrev_u32_e32 v75, s62, v71
	s_nop 0
	v_cndmask_b32_e32 v71, v71, v75, vcc
	v_xor_b32_e32 v71, v71, v147
	v_sub_u32_e32 v71, v71, v147
	v_lshlrev_b32_e32 v88, 6, v71
	v_ashrrev_i32_e32 v89, 31, v88
	v_lshlrev_b64 v[88:89], 2, v[88:89]
	v_lshl_add_u64 v[90:91], v[142:143], 0, v[88:89]
	v_lshl_add_u64 v[88:89], v[144:145], 0, v[88:89]
	v_mov_b32_e32 v92, v224
	v_mov_b32_e32 v93, v225
	v_mov_b32_e32 v88, v226
	v_mov_b32_e32 v89, v227
	v_mul_hi_u32 v71, v68, v174
	v_mul_lo_u32 v71, v71, s62
	v_sub_u32_e32 v68, v68, v71
	v_cmp_le_u32_e32 vcc, s62, v68
	v_subrev_u32_e32 v71, s62, v68
	v_ashrrev_i32_e32 v75, 31, v74
	v_cndmask_b32_e32 v68, v68, v71, vcc
	v_cmp_le_u32_e32 vcc, s62, v68
	v_subrev_u32_e32 v71, s62, v68
	v_pk_mul_f32 v[90:91], v[96:97], v[88:89]
	v_cndmask_b32_e32 v68, v68, v71, vcc
	v_xor_b32_e32 v68, v68, v147
	v_pk_mul_f32 v[88:89], v[94:95], v[88:89]
	v_sub_u32_e32 v68, v68, v147
	v_pk_fma_f32 v[90:91], v[94:95], v[92:93], v[90:91] neg_lo:[0,0,1] neg_hi:[0,0,1]
	v_pk_fma_f32 v[88:89], v[96:97], v[92:93], v[88:89]
	v_lshlrev_b32_e32 v92, 6, v68
	v_ashrrev_i32_e32 v93, 31, v92
	v_lshlrev_b64 v[92:93], 2, v[92:93]
	v_lshl_add_u64 v[94:95], v[142:143], 0, v[92:93]
	v_lshl_add_u64 v[92:93], v[144:145], 0, v[92:93]
	v_mov_b32_e32 v94, v228
	v_mov_b32_e32 v95, v229
	v_mov_b32_e32 v92, v230
	v_mov_b32_e32 v93, v231
	v_mov_b32_e32 v68, v73
	s_and_b64 vcc, exec, s[8:9]
	v_ashrrev_i32_e32 v71, 31, v70
	v_ashrrev_i32_e32 v73, 31, v72
	v_pk_mul_f32 v[80:81], v[76:77], v[92:93]
	s_nop 0
	v_pk_fma_f32 v[80:81], v[68:69], v[94:95], v[80:81] neg_lo:[0,0,1] neg_hi:[0,0,1]
	v_pk_mul_f32 v[68:69], v[68:69], v[92:93]
	s_nop 0
	v_pk_fma_f32 v[68:69], v[76:77], v[94:95], v[68:69]
	s_cbranch_vccnz .LBB0_778
; DEVINL unsigned pack2(float a, float b) { hf2 v = {a, b}; hbf2 r = __builtin_convertvector(v, hbf2); return __builtin_bit_cast(unsigned, r); }
;   DEVINL void operator()(Acc& acc, int brow, int bcol) const {
;     ...
;           const float ksc = 0.08838834764831845f;
;           float ff[4], fb[4];
;           _Pragma("unroll") for (int j = 0; j < 4; ++j) {
;             const int row = row0 + j, nl = row & 127;
;             o1[0][j] *= ksc; o1[1][j] *= ksc; o2[0][j] *= ksc; o2[1][j] *= ksc;
;             const size_t o = (size_t)row * 512 + head * 128 + i0;
;             *(unsigned*)(P.k + o) = pack2(o1[0][j], o1[1][j]); *(unsigned*)(P.k + o + 64) = pack2(o2[0][j], o2[1][j]);
;             ff[j] = exp2f((float)(127 - nl) * lgf); fb[j] = exp2f((float)nl * lgb);
;           }
;           const int chunk = row0 >> 7, m0 = row0 & 127;
;           _Pragma("unroll") for (int n = 0; n < 2; ++n) {
;             const size_t o = ((size_t)(chunk * 4 + head) * 128 + i0 + n) * 128 + m0;
;             *(bf16x4*)(P.kTf + o) = pack4(o1[n][0] * ff[0], o1[n][1] * ff[1], o1[n][2] * ff[2], o1[n][3] * ff[3]);
;             *(bf16x4*)(P.kTf + o + 64 * 128) = pack4(o2[n][0] * ff[0], o2[n][1] * ff[1], o2[n][2] * ff[2], o2[n][3] * ff[3]);
;             *(bf16x4*)(P.kTb + o) = pack4(o1[n][0] * fb[0], o1[n][1] * fb[1], o1[n][2] * fb[2], o1[n][3] * fb[3]);
;             *(bf16x4*)(P.kTb + o + 64 * 128) = pack4(o2[n][0] * fb[0], o2[n][1] * fb[1], o2[n][2] * fb[2], o2[n][3] * fb[3]);
;           }
	s_load_dwordx4 s[12:15], s[88:89], 0x190
	s_load_dwordx2 s[10:11], s[88:89], 0x1a0
	v_mov_b32_e32 v115, v1
	s_mov_b32 s20, 0x3db504f3
	v_pk_mul_f32 v[92:93], v[86:87], s[20:21] op_sel_hi:[1,0]
	s_waitcnt lgkmcnt(0)
	v_lshl_add_u64 v[76:77], s[12:13], 0, v[0:1]
	v_lshl_add_u64 v[94:95], v[76:77], 0, v[114:115]
	v_lshlrev_b64 v[96:97], 10, v[82:83]
	v_pk_mul_f32 v[76:77], v[84:85], s[20:21] op_sel_hi:[1,0]
	v_cvt_pk_bf16_f32 v99, v92, v93
	v_lshl_add_u64 v[96:97], v[94:95], 0, v[96:97]
	global_store_dword v[96:97], v99, off
	v_cvt_pk_bf16_f32 v99, v76, v77
	global_store_dword v[96:97], v99, off offset:128
	s_movk_i32 s13, 0x7f
	v_mov_b32_e32 v96, 0x7c
	v_bitop3_b32 v96, v82, s13, v96 bitop3:0x6c
	v_cvt_f32_ubyte0_e32 v96, v96
	v_mul_f32_e32 v97, v186, v96
	s_mov_b32 s12, 0xc2fc0000
	v_cmp_gt_f32_e32 vcc, s12, v97
	v_and_b32_e32 v98, 0x7c, v82
	v_pk_mul_f32 v[100:101], v[78:79], s[20:21] op_sel_hi:[1,0]
	v_cndmask_b32_e32 v97, 0, v253, vcc
	v_fmac_f32_e32 v97, v186, v96
	v_exp_f32_e32 v96, v97
	v_cndmask_b32_e32 v97, 0, v252, vcc
	v_lshlrev_b64 v[104:105], 10, v[70:71]
	v_pk_mul_f32 v[102:103], v[66:67], s[20:21] op_sel_hi:[1,0]
	v_ldexp_f32 v96, v96, v97
	v_cvt_f32_ubyte0_e32 v97, v98
	v_mul_f32_e32 v98, v185, v97
	v_cmp_gt_f32_e32 vcc, s12, v98
	v_lshl_add_u64 v[104:105], v[94:95], 0, v[104:105]
	v_and_b32_e32 v99, 0x7d, v70
	v_cndmask_b32_e32 v98, 0, v253, vcc
	v_fmac_f32_e32 v98, v185, v97
	v_exp_f32_e32 v97, v98
	v_cndmask_b32_e32 v98, 0, v252, vcc
	v_cvt_f32_ubyte0_e32 v99, v99
	v_lshlrev_b64 v[108:109], 10, v[74:75]
	v_ldexp_f32 v98, v97, v98
	v_cvt_pk_bf16_f32 v97, v100, v101
	global_store_dword v[104:105], v97, off
	v_cvt_pk_bf16_f32 v97, v102, v103
	global_store_dword v[104:105], v97, off offset:128
	v_mov_b32_e32 v97, 0x7d
	v_bitop3_b32 v97, v70, s13, v97 bitop3:0x6c
	v_cvt_f32_ubyte0_e32 v97, v97
	v_mul_f32_e32 v104, v186, v97
	v_cmp_gt_f32_e32 vcc, s12, v104
	v_pk_mul_f32 v[106:107], v[88:89], s[20:21] op_sel_hi:[1,0]
	v_lshl_add_u64 v[108:109], v[94:95], 0, v[108:109]
	v_cndmask_b32_e32 v104, 0, v253, vcc
	v_fmac_f32_e32 v104, v186, v97
	v_exp_f32_e32 v97, v104
	v_cndmask_b32_e32 v104, 0, v252, vcc
	v_and_b32_e32 v110, 0x7e, v74
	v_pk_mul_f32 v[112:113], v[80:81], s[20:21] op_sel_hi:[1,0]
	v_ldexp_f32 v97, v97, v104
	v_mul_f32_e32 v104, v185, v99
	v_cmp_gt_f32_e32 vcc, s12, v104
	v_lshlrev_b64 v[120:121], 10, v[72:73]
	v_pk_mul_f32 v[118:119], v[68:69], s[20:21] op_sel_hi:[1,0]
	v_cndmask_b32_e32 v104, 0, v253, vcc
	v_fmac_f32_e32 v104, v185, v99
	v_exp_f32_e32 v99, v104
	v_cndmask_b32_e32 v104, 0, v252, vcc
	v_lshl_add_u64 v[94:95], v[94:95], 0, v[120:121]
	v_ashrrev_i32_e32 v117, 31, v116
	v_ldexp_f32 v99, v99, v104
	v_pk_mul_f32 v[104:105], v[90:91], s[20:21] op_sel_hi:[1,0]
	v_mov_b32_e32 v123, v112
	v_cvt_pk_bf16_f32 v111, v104, v105
	global_store_dword v[108:109], v111, off
	v_cvt_pk_bf16_f32 v111, v106, v107
	global_store_dword v[108:109], v111, off offset:128
	v_mov_b32_e32 v108, 0x7e
	v_bitop3_b32 v108, v74, s13, v108 bitop3:0x6c
	v_cvt_f32_ubyte0_e32 v108, v108
	v_mul_f32_e32 v109, v186, v108
	v_cmp_gt_f32_e32 vcc, s12, v109
	v_and_b32_e32 v111, 0x7f, v72
	v_mov_b32_e32 v122, v104
	v_cndmask_b32_e32 v109, 0, v253, vcc
	v_fmac_f32_e32 v109, v186, v108
	v_exp_f32_e32 v108, v109
	v_cndmask_b32_e32 v109, 0, v252, vcc
	v_mov_b32_e32 v128, v106
	v_mov_b32_e32 v129, v118
	v_ldexp_f32 v108, v108, v109
	v_cvt_f32_ubyte0_e32 v109, v110
	v_mul_f32_e32 v110, v185, v109
	v_cmp_gt_f32_e32 vcc, s12, v110
	s_nop 1
	v_cndmask_b32_e32 v110, 0, v253, vcc
	v_fmac_f32_e32 v110, v185, v109
	v_exp_f32_e32 v109, v110
	v_cndmask_b32_e32 v110, 0, v252, vcc
	v_ldexp_f32 v110, v109, v110
	v_cvt_pk_bf16_f32 v109, v112, v113
	global_store_dword v[94:95], v109, off
	v_cvt_pk_bf16_f32 v109, v118, v119
	global_store_dword v[94:95], v109, off offset:128
	v_bitop3_b32 v94, v72, s13, v72 bitop3:0xc
	v_cvt_f32_ubyte0_e32 v94, v94
	v_mul_f32_e32 v95, v186, v94
	v_cmp_gt_f32_e32 vcc, s12, v95
	v_mov_b32_e32 v112, v105
	v_mov_b32_e32 v118, v107
	v_cndmask_b32_e32 v95, 0, v253, vcc
	v_fmac_f32_e32 v95, v186, v94
	v_exp_f32_e32 v94, v95
	v_cndmask_b32_e32 v95, 0, v252, vcc
	v_ldexp_f32 v109, v94, v95
	v_cvt_f32_ubyte0_e32 v94, v111
	v_mul_f32_e32 v95, v185, v94
	v_cmp_gt_f32_e32 vcc, s12, v95
	v_pk_mul_f32 v[124:125], v[108:109], v[122:123]
	v_pk_mul_f32 v[152:153], v[108:109], v[128:129]
	v_cndmask_b32_e32 v95, 0, v253, vcc
	v_fmac_f32_e32 v95, v185, v94
	v_exp_f32_e32 v94, v95
	v_cndmask_b32_e32 v95, 0, v252, vcc
	s_movk_i32 s12, 0x4000
	v_pk_mul_f32 v[104:105], v[108:109], v[112:113]
	v_ldexp_f32 v111, v94, v95
	v_lshlrev_b64 v[94:95], 14, v[116:117]
	v_lshl_or_b32 v94, v183, 7, v94
	v_mov_b32_e32 v116, v92
	v_mov_b32_e32 v117, v100
	v_or_b32_e32 v94, v94, v148
	v_pk_mul_f32 v[120:121], v[96:97], v[116:117]
	v_lshlrev_b64 v[94:95], 1, v[94:95]
	v_cvt_pk_bf16_f32 v120, v120, v121
	v_cvt_pk_bf16_f32 v121, v124, v125
	v_lshl_add_u64 v[124:125], s[14:15], 0, v[94:95]
	global_store_dwordx2 v[124:125], v[120:121], off offset:96
	v_mov_b32_e32 v120, v76
	v_mov_b32_e32 v121, v102
	v_pk_mul_f32 v[126:127], v[96:97], v[120:121]
	v_pk_mul_f32 v[116:117], v[98:99], v[116:117]
	v_cvt_pk_bf16_f32 v126, v126, v127
	v_cvt_pk_bf16_f32 v127, v152, v153
	v_add_co_u32_e32 v152, vcc, s12, v124
	v_pk_mul_f32 v[122:123], v[110:111], v[122:123]
	s_nop 0
	v_addc_co_u32_e32 v153, vcc, 0, v125, vcc
	v_cvt_pk_bf16_f32 v116, v116, v117
	v_cvt_pk_bf16_f32 v117, v122, v123
	v_lshl_add_u64 v[94:95], s[10:11], 0, v[94:95]
	global_store_dwordx2 v[152:153], v[126:127], off offset:96
	global_store_dwordx2 v[94:95], v[116:117], off offset:96
	v_pk_mul_f32 v[116:117], v[98:99], v[120:121]
	v_pk_mul_f32 v[120:121], v[110:111], v[128:129]
	v_mov_b32_e32 v100, v93
	v_cvt_pk_bf16_f32 v116, v116, v117
	v_cvt_pk_bf16_f32 v117, v120, v121
	v_add_co_u32_e32 v120, vcc, s12, v94
	v_pk_mul_f32 v[92:93], v[96:97], v[100:101]
	s_nop 0
	v_addc_co_u32_e32 v121, vcc, 0, v95, vcc
	v_cvt_pk_bf16_f32 v92, v92, v93
	v_cvt_pk_bf16_f32 v93, v104, v105
	v_mov_b32_e32 v102, v77
	global_store_dwordx2 v[120:121], v[116:117], off offset:96
	global_store_dwordx2 v[124:125], v[92:93], off offset:352
	v_pk_mul_f32 v[76:77], v[96:97], v[102:103]
	v_pk_mul_f32 v[92:93], v[108:109], v[118:119]
	v_cvt_pk_bf16_f32 v76, v76, v77
	v_cvt_pk_bf16_f32 v77, v92, v93
	global_store_dwordx2 v[152:153], v[76:77], off offset:352
	v_pk_mul_f32 v[76:77], v[98:99], v[100:101]
	v_pk_mul_f32 v[92:93], v[110:111], v[112:113]
	v_cvt_pk_bf16_f32 v76, v76, v77
	v_cvt_pk_bf16_f32 v77, v92, v93
	global_store_dwordx2 v[94:95], v[76:77], off offset:352
	v_pk_mul_f32 v[76:77], v[98:99], v[102:103]
	v_pk_mul_f32 v[92:93], v[110:111], v[118:119]
	v_cvt_pk_bf16_f32 v76, v76, v77
	v_cvt_pk_bf16_f32 v77, v92, v93
	s_mov_b64 s[10:11], 0
	global_store_dwordx2 v[120:121], v[76:77], off offset:352

;   DEVINL void operator()(Acc& acc, int brow, int bcol) const {
;     ...
;         const int row0 = brow + ai * 128 + wr * 64 + m * 16 + fq * 4;
;         float o1[2][4], o2[2][4];
;         _Pragma("unroll") for (int j = 0; j < 4; ++j) {
;           const int pos = (row0 + j) % L;
;           const float2 cs = *(const float2*)(P.ctab + pos * 64 + i0), sn = *(const float2*)(P.stab + pos * 64 + i0);
;           o1[0][j] = acc[ai][0][m][0][j] * cs.x - acc[ai][1][m][0][j] * sn.x; o2[0][j] = acc[ai][0][m][0][j] * sn.x + acc[ai][1][m][0][j] * cs.x;
;           o1[1][j] = acc[ai][0][m][1][j] * cs.y - acc[ai][1][m][1][j] * sn.y; o2[1][j] = acc[ai][0][m][1][j] * sn.y + acc[ai][1][m][1][j] * cs.y;
;         }
.LBB0_780:
	v_add_u32_e32 v66, 0x80, v146
	v_sub_u32_e32 v68, 0xffffff80, v146
	v_max_i32_e32 v68, v66, v68
	v_mul_hi_u32 v69, v68, v174
	v_mul_lo_u32 v69, v69, s62
	v_sub_u32_e32 v68, v68, v69
	v_cmp_le_u32_e32 vcc, s62, v68
	v_subrev_u32_e32 v69, s62, v68
	v_ashrrev_i32_e32 v67, 31, v66
	v_cndmask_b32_e32 v68, v68, v69, vcc
	v_cmp_le_u32_e32 vcc, s62, v68
	v_subrev_u32_e32 v69, s62, v68
	v_mov_b32_e32 v74, v54
	v_cndmask_b32_e32 v68, v68, v69, vcc
	v_xor_b32_e32 v68, v68, v67
	v_sub_u32_e32 v68, v68, v67
	v_lshlrev_b32_e32 v68, 6, v68
	v_ashrrev_i32_e32 v69, 31, v68
	v_lshlrev_b64 v[68:69], 2, v[68:69]
	v_lshl_add_u64 v[70:71], v[142:143], 0, v[68:69]
	v_lshl_add_u64 v[68:69], v[144:145], 0, v[68:69]
	global_load_dwordx2 v[220:221], v[70:71], off offset:256
	global_load_dwordx2 v[222:223], v[68:69], off offset:256
	global_load_dwordx2 v[224:225], v[70:71], off offset:512
	global_load_dwordx2 v[226:227], v[68:69], off offset:512
	global_load_dwordx2 v[228:229], v[70:71], off offset:768
	global_load_dwordx2 v[230:231], v[68:69], off offset:768
	global_load_dwordx2 v[72:73], v[70:71], off
	s_nop 0
	global_load_dwordx2 v[68:69], v[68:69], off
	v_mov_b32_e32 v75, v50
	v_mov_b32_e32 v76, v62
	v_mov_b32_e32 v77, v58
	v_sub_u32_e32 v50, 0xffffff7f, v146
	v_mov_b32_e32 v58, v63
	v_sub_u32_e32 v62, 0xffffff7e, v146
	v_mov_b32_e32 v78, v56
	v_mov_b32_e32 v79, v52
	v_mov_b32_e32 v80, v64
	v_mov_b32_e32 v81, v60
	v_sub_u32_e32 v52, 0xffffff7d, v146
	v_mov_b32_e32 v60, v65
	s_mov_b64 s[10:11], -1
	s_waitcnt vmcnt(0)
	v_pk_mul_f32 v[70:71], v[76:77], v[68:69]
	v_pk_mul_f32 v[68:69], v[74:75], v[68:69]
	v_pk_fma_f32 v[70:71], v[74:75], v[72:73], v[70:71] neg_lo:[0,0,1] neg_hi:[0,0,1]
	v_pk_fma_f32 v[68:69], v[76:77], v[72:73], v[68:69]
	v_add_u32_e32 v72, 0x81, v146
	v_max_i32_e32 v50, v72, v50
	v_mul_hi_u32 v54, v50, v174
	v_mul_lo_u32 v54, v54, s62
	v_sub_u32_e32 v50, v50, v54
	v_cmp_le_u32_e32 vcc, s62, v50
	v_subrev_u32_e32 v54, s62, v50
	v_ashrrev_i32_e32 v73, 31, v72
	v_cndmask_b32_e32 v50, v50, v54, vcc
	v_cmp_le_u32_e32 vcc, s62, v50
	v_subrev_u32_e32 v54, s62, v50
	s_nop 0
	v_cndmask_b32_e32 v50, v50, v54, vcc
	v_xor_b32_e32 v50, v50, v73
	v_sub_u32_e32 v50, v50, v73
	v_lshlrev_b32_e32 v74, 6, v50
	v_ashrrev_i32_e32 v75, 31, v74
	v_lshlrev_b64 v[74:75], 2, v[74:75]
	v_lshl_add_u64 v[76:77], v[142:143], 0, v[74:75]
	v_lshl_add_u64 v[74:75], v[144:145], 0, v[74:75]
	v_mov_b32_e32 v76, v220
	v_mov_b32_e32 v77, v221
	v_mov_b32_e32 v74, v222
	v_mov_b32_e32 v75, v223
	v_mov_b32_e32 v50, v55
	v_pk_mul_f32 v[54:55], v[58:59], v[74:75]
	s_nop 0
	v_pk_fma_f32 v[54:55], v[50:51], v[76:77], v[54:55] neg_lo:[0,0,1] neg_hi:[0,0,1]
	v_pk_mul_f32 v[50:51], v[50:51], v[74:75]
	s_nop 0
	v_pk_fma_f32 v[50:51], v[58:59], v[76:77], v[50:51]
	v_add_u32_e32 v58, 0x82, v146
	v_max_i32_e32 v62, v58, v62
	v_mul_hi_u32 v63, v62, v174
	v_mul_lo_u32 v63, v63, s62
	v_sub_u32_e32 v62, v62, v63
	v_cmp_le_u32_e32 vcc, s62, v62
	v_subrev_u32_e32 v63, s62, v62
	v_ashrrev_i32_e32 v59, 31, v58
	v_cndmask_b32_e32 v62, v62, v63, vcc
	v_cmp_le_u32_e32 vcc, s62, v62
	v_subrev_u32_e32 v63, s62, v62
	s_nop 0
	v_cndmask_b32_e32 v62, v62, v63, vcc
	v_xor_b32_e32 v62, v62, v59
	v_sub_u32_e32 v62, v62, v59
	v_lshlrev_b32_e32 v62, 6, v62
	v_ashrrev_i32_e32 v63, 31, v62
	v_lshlrev_b64 v[62:63], 2, v[62:63]
	v_lshl_add_u64 v[74:75], v[142:143], 0, v[62:63]
	v_lshl_add_u64 v[62:63], v[144:145], 0, v[62:63]
	v_mov_b32_e32 v76, v224
	v_mov_b32_e32 v77, v225
	v_mov_b32_e32 v62, v226
	v_mov_b32_e32 v63, v227
	v_pk_mul_f32 v[74:75], v[80:81], v[62:63]
	v_pk_mul_f32 v[62:63], v[78:79], v[62:63]
	v_pk_fma_f32 v[74:75], v[78:79], v[76:77], v[74:75] neg_lo:[0,0,1] neg_hi:[0,0,1]
	v_pk_fma_f32 v[62:63], v[80:81], v[76:77], v[62:63]
	v_add_u32_e32 v76, 0x83, v146
	v_max_i32_e32 v52, v76, v52
	v_mul_hi_u32 v56, v52, v174
	v_mul_lo_u32 v56, v56, s62
	v_sub_u32_e32 v52, v52, v56
	v_cmp_le_u32_e32 vcc, s62, v52
	v_subrev_u32_e32 v56, s62, v52
	v_ashrrev_i32_e32 v77, 31, v76
	v_cndmask_b32_e32 v52, v52, v56, vcc
	v_cmp_le_u32_e32 vcc, s62, v52
	v_subrev_u32_e32 v56, s62, v52
	s_nop 0
	v_cndmask_b32_e32 v52, v52, v56, vcc
	v_xor_b32_e32 v52, v52, v77
	v_sub_u32_e32 v52, v52, v77
	v_lshlrev_b32_e32 v78, 6, v52
	v_ashrrev_i32_e32 v79, 31, v78
	v_lshlrev_b64 v[78:79], 2, v[78:79]
	v_lshl_add_u64 v[80:81], v[142:143], 0, v[78:79]
	v_lshl_add_u64 v[78:79], v[144:145], 0, v[78:79]
	v_mov_b32_e32 v80, v228
	v_mov_b32_e32 v81, v229
	v_mov_b32_e32 v78, v230
	v_mov_b32_e32 v79, v231
	v_mov_b32_e32 v52, v57
	s_and_b64 vcc, exec, s[8:9]
	v_pk_mul_f32 v[56:57], v[60:61], v[78:79]
	s_nop 0
	v_pk_fma_f32 v[56:57], v[52:53], v[80:81], v[56:57] neg_lo:[0,0,1] neg_hi:[0,0,1]
	v_pk_mul_f32 v[52:53], v[52:53], v[78:79]
	s_nop 0
	v_pk_fma_f32 v[52:53], v[60:61], v[80:81], v[52:53]
	s_cbranch_vccnz .LBB0_782
; DEVINL unsigned pack2(float a, float b) { hf2 v = {a, b}; hbf2 r = __builtin_convertvector(v, hbf2); return __builtin_bit_cast(unsigned, r); }
;   DEVINL void operator()(Acc& acc, int brow, int bcol) const {
;     ...
;           const float ksc = 0.08838834764831845f;
;           float ff[4], fb[4];
;           _Pragma("unroll") for (int j = 0; j < 4; ++j) {
;             const int row = row0 + j, nl = row & 127;
;             o1[0][j] *= ksc; o1[1][j] *= ksc; o2[0][j] *= ksc; o2[1][j] *= ksc;
;             const size_t o = (size_t)row * 512 + head * 128 + i0;
;             *(unsigned*)(P.k + o) = pack2(o1[0][j], o1[1][j]); *(unsigned*)(P.k + o + 64) = pack2(o2[0][j], o2[1][j]);
;             ff[j] = exp2f((float)(127 - nl) * lgf); fb[j] = exp2f((float)nl * lgb);
;           }
;           const int chunk = row0 >> 7, m0 = row0 & 127;
;           _Pragma("unroll") for (int n = 0; n < 2; ++n) {
;             const size_t o = ((size_t)(chunk * 4 + head) * 128 + i0 + n) * 128 + m0;
;             *(bf16x4*)(P.kTf + o) = pack4(o1[n][0] * ff[0], o1[n][1] * ff[1], o1[n][2] * ff[2], o1[n][3] * ff[3]);
;             *(bf16x4*)(P.kTf + o + 64 * 128) = pack4(o2[n][0] * ff[0], o2[n][1] * ff[1], o2[n][2] * ff[2], o2[n][3] * ff[3]);
;             *(bf16x4*)(P.kTb + o) = pack4(o1[n][0] * fb[0], o1[n][1] * fb[1], o1[n][2] * fb[2], o1[n][3] * fb[3]);
;             *(bf16x4*)(P.kTb + o + 64 * 128) = pack4(o2[n][0] * fb[0], o2[n][1] * fb[1], o2[n][2] * fb[2], o2[n][3] * fb[3]);
;           }
	s_load_dwordx4 s[12:15], s[88:89], 0x190
	s_load_dwordx2 s[10:11], s[88:89], 0x1a0
	v_mov_b32_e32 v115, v1
	s_mov_b32 s20, 0x3db504f3
	v_pk_mul_f32 v[64:65], v[70:71], s[20:21] op_sel_hi:[1,0]
	s_waitcnt lgkmcnt(0)
	v_lshl_add_u64 v[60:61], s[12:13], 0, v[0:1]
	v_lshl_add_u64 v[78:79], v[60:61], 0, v[114:115]
	v_lshlrev_b64 v[80:81], 10, v[66:67]
	v_pk_mul_f32 v[60:61], v[68:69], s[20:21] op_sel_hi:[1,0]
	v_cvt_pk_bf16_f32 v82, v64, v65
	v_lshl_add_u64 v[80:81], v[78:79], 0, v[80:81]
	global_store_dword v[80:81], v82, off
	v_cvt_pk_bf16_f32 v82, v60, v61
	global_store_dword v[80:81], v82, off offset:128
	v_cvt_f32_ubyte0_e32 v80, v164
	v_mul_f32_e32 v81, v186, v80
	s_mov_b32 s12, 0xc2fc0000
	v_cmp_gt_f32_e32 vcc, s12, v81
	v_pk_mul_f32 v[84:85], v[54:55], s[20:21] op_sel_hi:[1,0]
	v_lshlrev_b64 v[88:89], 10, v[72:73]
	v_cndmask_b32_e32 v81, 0, v253, vcc
	v_fmac_f32_e32 v81, v186, v80
	v_exp_f32_e32 v80, v81
	v_cndmask_b32_e32 v81, 0, v252, vcc
	v_pk_mul_f32 v[86:87], v[50:51], s[20:21] op_sel_hi:[1,0]
	v_lshl_add_u64 v[88:89], v[78:79], 0, v[88:89]
	v_ldexp_f32 v80, v80, v81
	v_mul_f32_e32 v81, v185, v163
	v_cmp_gt_f32_e32 vcc, s12, v81
	s_movk_i32 s13, 0x7f
	v_and_b32_e32 v83, 0x4d, v72
	v_cndmask_b32_e32 v81, 0, v253, vcc
	v_fmac_f32_e32 v81, v185, v163
	v_exp_f32_e32 v81, v81
	v_cndmask_b32_e32 v82, 0, v252, vcc
	v_cvt_f32_ubyte0_e32 v83, v83
	v_lshlrev_b64 v[92:93], 10, v[58:59]
	v_ldexp_f32 v82, v81, v82
	v_cvt_pk_bf16_f32 v81, v84, v85
	global_store_dword v[88:89], v81, off
	v_cvt_pk_bf16_f32 v81, v86, v87
	global_store_dword v[88:89], v81, off offset:128
	v_mov_b32_e32 v81, 0x4d
	v_bitop3_b32 v81, v72, s13, v81 bitop3:0x6c
	v_cvt_f32_ubyte0_e32 v81, v81
	v_mul_f32_e32 v88, v186, v81
	v_cmp_gt_f32_e32 vcc, s12, v88
	v_pk_mul_f32 v[90:91], v[62:63], s[20:21] op_sel_hi:[1,0]
	v_lshl_add_u64 v[92:93], v[78:79], 0, v[92:93]
	v_cndmask_b32_e32 v88, 0, v253, vcc
	v_fmac_f32_e32 v88, v186, v81
	v_exp_f32_e32 v81, v88
	v_cndmask_b32_e32 v88, 0, v252, vcc
	v_and_b32_e32 v94, 0x4e, v58
	v_pk_mul_f32 v[96:97], v[56:57], s[20:21] op_sel_hi:[1,0]
	v_ldexp_f32 v81, v81, v88
	v_mul_f32_e32 v88, v185, v83
	v_cmp_gt_f32_e32 vcc, s12, v88
	v_lshlrev_b64 v[100:101], 10, v[76:77]
	v_pk_mul_f32 v[98:99], v[52:53], s[20:21] op_sel_hi:[1,0]
	v_cndmask_b32_e32 v88, 0, v253, vcc
	v_fmac_f32_e32 v88, v185, v83
	v_exp_f32_e32 v83, v88
	v_cndmask_b32_e32 v88, 0, v252, vcc
	v_lshl_add_u64 v[78:79], v[78:79], 0, v[100:101]
	v_mov_b32_e32 v100, v64
	v_ldexp_f32 v83, v83, v88
	v_pk_mul_f32 v[88:89], v[74:75], s[20:21] op_sel_hi:[1,0]
	v_mov_b32_e32 v101, v84
	v_cvt_pk_bf16_f32 v95, v88, v89
	global_store_dword v[92:93], v95, off
	v_cvt_pk_bf16_f32 v95, v90, v91
	global_store_dword v[92:93], v95, off offset:128
	v_mov_b32_e32 v92, 0x4e
	v_bitop3_b32 v92, v58, s13, v92 bitop3:0x6c
	v_cvt_f32_ubyte0_e32 v92, v92
	v_mul_f32_e32 v93, v186, v92
	v_cmp_gt_f32_e32 vcc, s12, v93
	v_and_b32_e32 v95, 0x4f, v76
	v_mov_b32_e32 v104, v88
	v_cndmask_b32_e32 v93, 0, v253, vcc
	v_fmac_f32_e32 v93, v186, v92
	v_exp_f32_e32 v92, v93
	v_cndmask_b32_e32 v93, 0, v252, vcc
	v_mov_b32_e32 v105, v96
	v_pk_mul_f32 v[102:103], v[80:81], v[100:101]
	v_ldexp_f32 v92, v92, v93
	v_cvt_f32_ubyte0_e32 v93, v94
	v_mul_f32_e32 v94, v185, v93
	v_cmp_gt_f32_e32 vcc, s12, v94
	v_cvt_pk_bf16_f32 v102, v102, v103
	v_mov_b32_e32 v110, v90
	v_cndmask_b32_e32 v94, 0, v253, vcc
	v_fmac_f32_e32 v94, v185, v93
	v_exp_f32_e32 v93, v94
	v_cndmask_b32_e32 v94, 0, v252, vcc
	v_mov_b32_e32 v111, v98
	v_pk_mul_f32 v[100:101], v[82:83], v[100:101]
	v_ldexp_f32 v94, v93, v94
	v_cvt_pk_bf16_f32 v93, v96, v97
	global_store_dword v[78:79], v93, off
	v_cvt_pk_bf16_f32 v93, v98, v99
	global_store_dword v[78:79], v93, off offset:128
	v_mov_b32_e32 v78, 0x4f
	v_bitop3_b32 v78, v76, s13, v78 bitop3:0x6c
	v_cvt_f32_ubyte0_e32 v78, v78
	v_mul_f32_e32 v79, v186, v78
	v_cmp_gt_f32_e32 vcc, s12, v79
	v_cvt_pk_bf16_f32 v100, v100, v101
	v_mov_b32_e32 v84, v65
	v_cndmask_b32_e32 v79, 0, v253, vcc
	v_fmac_f32_e32 v79, v186, v78
	v_exp_f32_e32 v78, v79
	v_cndmask_b32_e32 v79, 0, v252, vcc
	v_mov_b32_e32 v96, v89
	v_pk_mul_f32 v[64:65], v[80:81], v[84:85]
	v_ldexp_f32 v93, v78, v79
	v_cvt_f32_ubyte0_e32 v78, v95
	v_mul_f32_e32 v79, v185, v78
	v_cmp_gt_f32_e32 vcc, s12, v79
	v_pk_mul_f32 v[106:107], v[92:93], v[104:105]
	v_pk_mul_f32 v[112:113], v[92:93], v[110:111]
	v_cndmask_b32_e32 v79, 0, v253, vcc
	v_fmac_f32_e32 v79, v185, v78
	v_exp_f32_e32 v78, v79
	v_cndmask_b32_e32 v79, 0, v252, vcc
	v_cvt_pk_bf16_f32 v103, v106, v107
	s_movk_i32 s12, 0x4000
	v_ldexp_f32 v95, v78, v79
	v_ashrrev_i32_e32 v78, 5, v66
	v_and_or_b32 v78, v78, -4, v184
	v_ashrrev_i32_e32 v79, 31, v78
	v_lshlrev_b64 v[78:79], 14, v[78:79]
	v_lshl_or_b32 v78, v183, 7, v78
	v_or_b32_e32 v78, v78, v162
	v_lshlrev_b64 v[78:79], 1, v[78:79]
	v_lshl_add_u64 v[106:107], s[14:15], 0, v[78:79]
	global_store_dwordx2 v[106:107], v[102:103], off
	v_mov_b32_e32 v102, v60
	v_mov_b32_e32 v103, v86
	v_pk_mul_f32 v[108:109], v[80:81], v[102:103]
	v_pk_mul_f32 v[104:105], v[94:95], v[104:105]
	v_cvt_pk_bf16_f32 v108, v108, v109
	v_cvt_pk_bf16_f32 v109, v112, v113
	v_add_co_u32_e32 v112, vcc, s12, v106
	v_cvt_pk_bf16_f32 v101, v104, v105
	s_nop 0
	v_addc_co_u32_e32 v113, vcc, 0, v107, vcc
	v_lshl_add_u64 v[78:79], s[10:11], 0, v[78:79]
	global_store_dwordx2 v[112:113], v[108:109], off
	global_store_dwordx2 v[78:79], v[100:101], off
	v_pk_mul_f32 v[100:101], v[82:83], v[102:103]
	v_pk_mul_f32 v[102:103], v[94:95], v[110:111]
	v_cvt_pk_bf16_f32 v100, v100, v101
	v_cvt_pk_bf16_f32 v101, v102, v103
	v_add_co_u32_e32 v102, vcc, s12, v78
	v_pk_mul_f32 v[88:89], v[92:93], v[96:97]
	s_nop 0
	v_addc_co_u32_e32 v103, vcc, 0, v79, vcc
	v_cvt_pk_bf16_f32 v64, v64, v65
	v_cvt_pk_bf16_f32 v65, v88, v89
	v_mov_b32_e32 v86, v61
	v_mov_b32_e32 v98, v91
	global_store_dwordx2 v[102:103], v[100:101], off
	global_store_dwordx2 v[106:107], v[64:65], off offset:256
	v_pk_mul_f32 v[60:61], v[80:81], v[86:87]
	v_pk_mul_f32 v[64:65], v[92:93], v[98:99]
	v_cvt_pk_bf16_f32 v60, v60, v61
	v_cvt_pk_bf16_f32 v61, v64, v65
	global_store_dwordx2 v[112:113], v[60:61], off offset:256
	v_pk_mul_f32 v[60:61], v[82:83], v[84:85]
	v_pk_mul_f32 v[64:65], v[94:95], v[96:97]
	v_cvt_pk_bf16_f32 v60, v60, v61
	v_cvt_pk_bf16_f32 v61, v64, v65
	global_store_dwordx2 v[78:79], v[60:61], off offset:256
	v_pk_mul_f32 v[60:61], v[82:83], v[86:87]
	v_pk_mul_f32 v[64:65], v[94:95], v[98:99]
	v_cvt_pk_bf16_f32 v60, v60, v61
	v_cvt_pk_bf16_f32 v61, v64, v65
	s_mov_b64 s[10:11], 0
	global_store_dwordx2 v[102:103], v[60:61], off offset:256

;   DEVINL void operator()(Acc& acc, int brow, int bcol) const {
;     ...
;         const int row0 = brow + ai * 128 + wr * 64 + m * 16 + fq * 4;
;         float o1[2][4], o2[2][4];
;         _Pragma("unroll") for (int j = 0; j < 4; ++j) {
;           const int pos = (row0 + j) % L;
;           const float2 cs = *(const float2*)(P.ctab + pos * 64 + i0), sn = *(const float2*)(P.stab + pos * 64 + i0);
;           o1[0][j] = acc[ai][0][m][0][j] * cs.x - acc[ai][1][m][0][j] * sn.x; o2[0][j] = acc[ai][0][m][0][j] * sn.x + acc[ai][1][m][0][j] * cs.x;
;           o1[1][j] = acc[ai][0][m][1][j] * cs.y - acc[ai][1][m][1][j] * sn.y; o2[1][j] = acc[ai][0][m][1][j] * sn.y + acc[ai][1][m][1][j] * cs.y;
;         }
.LBB0_784:
	v_add_u32_e32 v50, 0x90, v146
	v_sub_u32_e32 v52, 0xffffff70, v146
	v_max_i32_e32 v52, v50, v52
	v_mul_hi_u32 v53, v52, v174
	v_mul_lo_u32 v53, v53, s62
	v_sub_u32_e32 v52, v52, v53
	v_cmp_le_u32_e32 vcc, s62, v52
	v_subrev_u32_e32 v53, s62, v52
	v_ashrrev_i32_e32 v51, 31, v50
	v_cndmask_b32_e32 v52, v52, v53, vcc
	v_cmp_le_u32_e32 vcc, s62, v52
	v_subrev_u32_e32 v53, s62, v52
	v_mov_b32_e32 v58, v38
	v_cndmask_b32_e32 v52, v52, v53, vcc
	v_xor_b32_e32 v52, v52, v51
	v_sub_u32_e32 v52, v52, v51
	v_lshlrev_b32_e32 v52, 6, v52
	v_ashrrev_i32_e32 v53, 31, v52
	v_lshlrev_b64 v[52:53], 2, v[52:53]
	v_lshl_add_u64 v[54:55], v[142:143], 0, v[52:53]
	v_lshl_add_u64 v[52:53], v[144:145], 0, v[52:53]
	global_load_dwordx2 v[220:221], v[54:55], off offset:256
	global_load_dwordx2 v[222:223], v[52:53], off offset:256
	global_load_dwordx2 v[224:225], v[54:55], off offset:512
	global_load_dwordx2 v[226:227], v[52:53], off offset:512
	global_load_dwordx2 v[228:229], v[54:55], off offset:768
	global_load_dwordx2 v[230:231], v[52:53], off offset:768
	global_load_dwordx2 v[56:57], v[54:55], off
	s_nop 0
	global_load_dwordx2 v[52:53], v[52:53], off
	v_mov_b32_e32 v59, v34
	v_mov_b32_e32 v60, v46
	v_mov_b32_e32 v61, v42
	v_sub_u32_e32 v34, 0xffffff6f, v146
	v_mov_b32_e32 v42, v47
	v_sub_u32_e32 v46, 0xffffff6e, v146
	v_mov_b32_e32 v62, v40
	v_mov_b32_e32 v63, v36
	v_mov_b32_e32 v64, v48
	v_mov_b32_e32 v65, v44
	v_sub_u32_e32 v36, 0xffffff6d, v146
	v_mov_b32_e32 v44, v49
	s_mov_b64 s[10:11], -1
	s_waitcnt vmcnt(0)
	v_pk_mul_f32 v[54:55], v[60:61], v[52:53]
	v_pk_mul_f32 v[52:53], v[58:59], v[52:53]
	v_pk_fma_f32 v[54:55], v[58:59], v[56:57], v[54:55] neg_lo:[0,0,1] neg_hi:[0,0,1]
	v_pk_fma_f32 v[52:53], v[60:61], v[56:57], v[52:53]
	v_add_u32_e32 v56, 0x91, v146
	v_max_i32_e32 v34, v56, v34
	v_mul_hi_u32 v38, v34, v174
	v_mul_lo_u32 v38, v38, s62
	v_sub_u32_e32 v34, v34, v38
	v_cmp_le_u32_e32 vcc, s62, v34
	v_subrev_u32_e32 v38, s62, v34
	v_ashrrev_i32_e32 v57, 31, v56
	v_cndmask_b32_e32 v34, v34, v38, vcc
	v_cmp_le_u32_e32 vcc, s62, v34
	v_subrev_u32_e32 v38, s62, v34
	s_nop 0
	v_cndmask_b32_e32 v34, v34, v38, vcc
	v_xor_b32_e32 v34, v34, v57
	v_sub_u32_e32 v34, v34, v57
	v_lshlrev_b32_e32 v58, 6, v34
	v_ashrrev_i32_e32 v59, 31, v58
	v_lshlrev_b64 v[58:59], 2, v[58:59]
	v_lshl_add_u64 v[60:61], v[142:143], 0, v[58:59]
	v_lshl_add_u64 v[58:59], v[144:145], 0, v[58:59]
	v_mov_b32_e32 v60, v220
	v_mov_b32_e32 v61, v221
	v_mov_b32_e32 v58, v222
	v_mov_b32_e32 v59, v223
	v_mov_b32_e32 v34, v39
	v_pk_mul_f32 v[38:39], v[42:43], v[58:59]
	s_nop 0
	v_pk_fma_f32 v[38:39], v[34:35], v[60:61], v[38:39] neg_lo:[0,0,1] neg_hi:[0,0,1]
	v_pk_mul_f32 v[34:35], v[34:35], v[58:59]
	s_nop 0
	v_pk_fma_f32 v[34:35], v[42:43], v[60:61], v[34:35]
	v_add_u32_e32 v42, 0x92, v146
	v_max_i32_e32 v46, v42, v46
	v_mul_hi_u32 v47, v46, v174
	v_mul_lo_u32 v47, v47, s62
	v_sub_u32_e32 v46, v46, v47
	v_cmp_le_u32_e32 vcc, s62, v46
	v_subrev_u32_e32 v47, s62, v46
	v_ashrrev_i32_e32 v43, 31, v42
	v_cndmask_b32_e32 v46, v46, v47, vcc
	v_cmp_le_u32_e32 vcc, s62, v46
	v_subrev_u32_e32 v47, s62, v46
	s_nop 0
	v_cndmask_b32_e32 v46, v46, v47, vcc
	v_xor_b32_e32 v46, v46, v43
	v_sub_u32_e32 v46, v46, v43
	v_lshlrev_b32_e32 v46, 6, v46
	v_ashrrev_i32_e32 v47, 31, v46
	v_lshlrev_b64 v[46:47], 2, v[46:47]
	v_lshl_add_u64 v[58:59], v[142:143], 0, v[46:47]
	v_lshl_add_u64 v[46:47], v[144:145], 0, v[46:47]
	v_mov_b32_e32 v60, v224
	v_mov_b32_e32 v61, v225
	v_mov_b32_e32 v46, v226
	v_mov_b32_e32 v47, v227
	v_pk_mul_f32 v[58:59], v[64:65], v[46:47]
	v_pk_mul_f32 v[46:47], v[62:63], v[46:47]
	v_pk_fma_f32 v[58:59], v[62:63], v[60:61], v[58:59] neg_lo:[0,0,1] neg_hi:[0,0,1]
	v_pk_fma_f32 v[46:47], v[64:65], v[60:61], v[46:47]
	v_add_u32_e32 v60, 0x93, v146
	v_max_i32_e32 v36, v60, v36
	v_mul_hi_u32 v40, v36, v174
	v_mul_lo_u32 v40, v40, s62
	v_sub_u32_e32 v36, v36, v40
	v_cmp_le_u32_e32 vcc, s62, v36
	v_subrev_u32_e32 v40, s62, v36
	v_ashrrev_i32_e32 v61, 31, v60
	v_cndmask_b32_e32 v36, v36, v40, vcc
	v_cmp_le_u32_e32 vcc, s62, v36
	v_subrev_u32_e32 v40, s62, v36
	s_nop 0
	v_cndmask_b32_e32 v36, v36, v40, vcc
	v_xor_b32_e32 v36, v36, v61
	v_sub_u32_e32 v36, v36, v61
	v_lshlrev_b32_e32 v62, 6, v36
	v_ashrrev_i32_e32 v63, 31, v62
	v_lshlrev_b64 v[62:63], 2, v[62:63]
	v_lshl_add_u64 v[64:65], v[142:143], 0, v[62:63]
	v_lshl_add_u64 v[62:63], v[144:145], 0, v[62:63]
	v_mov_b32_e32 v64, v228
	v_mov_b32_e32 v65, v229
	v_mov_b32_e32 v62, v230
	v_mov_b32_e32 v63, v231
	v_mov_b32_e32 v36, v41
	s_and_b64 vcc, exec, s[8:9]
	v_pk_mul_f32 v[40:41], v[44:45], v[62:63]
	s_nop 0
	v_pk_fma_f32 v[40:41], v[36:37], v[64:65], v[40:41] neg_lo:[0,0,1] neg_hi:[0,0,1]
	v_pk_mul_f32 v[36:37], v[36:37], v[62:63]
	s_nop 0
	v_pk_fma_f32 v[36:37], v[44:45], v[64:65], v[36:37]
	s_cbranch_vccnz .LBB0_786
; DEVINL unsigned pack2(float a, float b) { hf2 v = {a, b}; hbf2 r = __builtin_convertvector(v, hbf2); return __builtin_bit_cast(unsigned, r); }
;   DEVINL void operator()(Acc& acc, int brow, int bcol) const {
;     ...
;           const float ksc = 0.08838834764831845f;
;           float ff[4], fb[4];
;           _Pragma("unroll") for (int j = 0; j < 4; ++j) {
;             const int row = row0 + j, nl = row & 127;
;             o1[0][j] *= ksc; o1[1][j] *= ksc; o2[0][j] *= ksc; o2[1][j] *= ksc;
;             const size_t o = (size_t)row * 512 + head * 128 + i0;
;             *(unsigned*)(P.k + o) = pack2(o1[0][j], o1[1][j]); *(unsigned*)(P.k + o + 64) = pack2(o2[0][j], o2[1][j]);
;             ff[j] = exp2f((float)(127 - nl) * lgf); fb[j] = exp2f((float)nl * lgb);
;           }
;           const int chunk = row0 >> 7, m0 = row0 & 127;
;           _Pragma("unroll") for (int n = 0; n < 2; ++n) {
;             const size_t o = ((size_t)(chunk * 4 + head) * 128 + i0 + n) * 128 + m0;
;             *(bf16x4*)(P.kTf + o) = pack4(o1[n][0] * ff[0], o1[n][1] * ff[1], o1[n][2] * ff[2], o1[n][3] * ff[3]);
;             *(bf16x4*)(P.kTf + o + 64 * 128) = pack4(o2[n][0] * ff[0], o2[n][1] * ff[1], o2[n][2] * ff[2], o2[n][3] * ff[3]);
;             *(bf16x4*)(P.kTb + o) = pack4(o1[n][0] * fb[0], o1[n][1] * fb[1], o1[n][2] * fb[2], o1[n][3] * fb[3]);
;             *(bf16x4*)(P.kTb + o + 64 * 128) = pack4(o2[n][0] * fb[0], o2[n][1] * fb[1], o2[n][2] * fb[2], o2[n][3] * fb[3]);
;           }
	s_load_dwordx4 s[12:15], s[88:89], 0x190
	s_load_dwordx2 s[10:11], s[88:89], 0x1a0
	v_mov_b32_e32 v115, v1
	s_mov_b32 s20, 0x3db504f3
	v_pk_mul_f32 v[48:49], v[54:55], s[20:21] op_sel_hi:[1,0]
	s_waitcnt lgkmcnt(0)
	v_lshl_add_u64 v[44:45], s[12:13], 0, v[0:1]
	v_lshl_add_u64 v[62:63], v[44:45], 0, v[114:115]
	v_lshlrev_b64 v[64:65], 10, v[50:51]
	v_pk_mul_f32 v[44:45], v[52:53], s[20:21] op_sel_hi:[1,0]
	v_cvt_pk_bf16_f32 v67, v48, v49
	v_lshl_add_u64 v[64:65], v[62:63], 0, v[64:65]
	global_store_dword v[64:65], v67, off
	v_cvt_pk_bf16_f32 v67, v44, v45
	global_store_dword v[64:65], v67, off offset:128
	s_movk_i32 s13, 0x7f
	v_mov_b32_e32 v64, 0x5c
	v_bitop3_b32 v64, v50, s13, v64 bitop3:0x6c
	v_cvt_f32_ubyte0_e32 v64, v64
	v_mul_f32_e32 v65, v186, v64
	s_mov_b32 s12, 0xc2fc0000
	v_cmp_gt_f32_e32 vcc, s12, v65
	v_and_b32_e32 v66, 0x5c, v50
	v_pk_mul_f32 v[68:69], v[38:39], s[20:21] op_sel_hi:[1,0]
	v_cndmask_b32_e32 v65, 0, v253, vcc
	v_fmac_f32_e32 v65, v186, v64
	v_exp_f32_e32 v64, v65
	v_cndmask_b32_e32 v65, 0, v252, vcc
	v_lshlrev_b64 v[72:73], 10, v[56:57]
	v_pk_mul_f32 v[70:71], v[34:35], s[20:21] op_sel_hi:[1,0]
	v_ldexp_f32 v64, v64, v65
	v_cvt_f32_ubyte0_e32 v65, v66
	v_mul_f32_e32 v66, v185, v65
	v_cmp_gt_f32_e32 vcc, s12, v66
	v_lshl_add_u64 v[72:73], v[62:63], 0, v[72:73]
	v_and_b32_e32 v67, 0x5d, v56
	v_cndmask_b32_e32 v66, 0, v253, vcc
	v_fmac_f32_e32 v66, v185, v65
	v_exp_f32_e32 v65, v66
	v_cndmask_b32_e32 v66, 0, v252, vcc
	v_cvt_f32_ubyte0_e32 v67, v67
	v_lshlrev_b64 v[76:77], 10, v[42:43]
	v_ldexp_f32 v66, v65, v66
	v_cvt_pk_bf16_f32 v65, v68, v69
	global_store_dword v[72:73], v65, off
	v_cvt_pk_bf16_f32 v65, v70, v71
	global_store_dword v[72:73], v65, off offset:128
	v_mov_b32_e32 v65, 0x5d
	v_bitop3_b32 v65, v56, s13, v65 bitop3:0x6c
	v_cvt_f32_ubyte0_e32 v65, v65
	v_mul_f32_e32 v72, v186, v65
	v_cmp_gt_f32_e32 vcc, s12, v72
	v_pk_mul_f32 v[74:75], v[46:47], s[20:21] op_sel_hi:[1,0]
	v_lshl_add_u64 v[76:77], v[62:63], 0, v[76:77]
	v_cndmask_b32_e32 v72, 0, v253, vcc
	v_fmac_f32_e32 v72, v186, v65
	v_exp_f32_e32 v65, v72
	v_cndmask_b32_e32 v72, 0, v252, vcc
	v_and_b32_e32 v78, 0x5e, v42
	v_pk_mul_f32 v[80:81], v[40:41], s[20:21] op_sel_hi:[1,0]
	v_ldexp_f32 v65, v65, v72
	v_mul_f32_e32 v72, v185, v67
	v_cmp_gt_f32_e32 vcc, s12, v72
	v_lshlrev_b64 v[84:85], 10, v[60:61]
	v_pk_mul_f32 v[82:83], v[36:37], s[20:21] op_sel_hi:[1,0]
	v_cndmask_b32_e32 v72, 0, v253, vcc
	v_fmac_f32_e32 v72, v185, v67
	v_exp_f32_e32 v67, v72
	v_cndmask_b32_e32 v72, 0, v252, vcc
	v_lshl_add_u64 v[62:63], v[62:63], 0, v[84:85]
	v_mov_b32_e32 v84, v48
	v_ldexp_f32 v67, v67, v72
	v_pk_mul_f32 v[72:73], v[58:59], s[20:21] op_sel_hi:[1,0]
	v_mov_b32_e32 v85, v68
	v_cvt_pk_bf16_f32 v79, v72, v73
	global_store_dword v[76:77], v79, off
	v_cvt_pk_bf16_f32 v79, v74, v75
	global_store_dword v[76:77], v79, off offset:128
	v_mov_b32_e32 v76, 0x5e
	v_bitop3_b32 v76, v42, s13, v76 bitop3:0x6c
	v_cvt_f32_ubyte0_e32 v76, v76
	v_mul_f32_e32 v77, v186, v76
	v_cmp_gt_f32_e32 vcc, s12, v77
	v_and_b32_e32 v79, 0x5f, v60
	v_mov_b32_e32 v88, v72
	v_cndmask_b32_e32 v77, 0, v253, vcc
	v_fmac_f32_e32 v77, v186, v76
	v_exp_f32_e32 v76, v77
	v_cndmask_b32_e32 v77, 0, v252, vcc
	v_mov_b32_e32 v89, v80
	v_pk_mul_f32 v[86:87], v[64:65], v[84:85]
	v_ldexp_f32 v76, v76, v77
	v_cvt_f32_ubyte0_e32 v77, v78
	v_mul_f32_e32 v78, v185, v77
	v_cmp_gt_f32_e32 vcc, s12, v78
	v_cvt_pk_bf16_f32 v86, v86, v87
	v_mov_b32_e32 v94, v74
	v_cndmask_b32_e32 v78, 0, v253, vcc
	v_fmac_f32_e32 v78, v185, v77
	v_exp_f32_e32 v77, v78
	v_cndmask_b32_e32 v78, 0, v252, vcc
	v_mov_b32_e32 v95, v82
	v_pk_mul_f32 v[84:85], v[66:67], v[84:85]
	v_ldexp_f32 v78, v77, v78
	v_cvt_pk_bf16_f32 v77, v80, v81
	global_store_dword v[62:63], v77, off
	v_cvt_pk_bf16_f32 v77, v82, v83
	global_store_dword v[62:63], v77, off offset:128
	v_mov_b32_e32 v62, 0x5f
	v_bitop3_b32 v62, v60, s13, v62 bitop3:0x6c
	v_cvt_f32_ubyte0_e32 v62, v62
	v_mul_f32_e32 v63, v186, v62
	v_cmp_gt_f32_e32 vcc, s12, v63
	v_cvt_pk_bf16_f32 v84, v84, v85
	v_mov_b32_e32 v68, v49
	v_cndmask_b32_e32 v63, 0, v253, vcc
	v_fmac_f32_e32 v63, v186, v62
	v_exp_f32_e32 v62, v63
	v_cndmask_b32_e32 v63, 0, v252, vcc
	v_mov_b32_e32 v80, v73
	v_pk_mul_f32 v[48:49], v[64:65], v[68:69]
	v_ldexp_f32 v77, v62, v63
	v_cvt_f32_ubyte0_e32 v62, v79
	v_mul_f32_e32 v63, v185, v62
	v_cmp_gt_f32_e32 vcc, s12, v63
	v_pk_mul_f32 v[90:91], v[76:77], v[88:89]
	v_pk_mul_f32 v[96:97], v[76:77], v[94:95]
	v_cndmask_b32_e32 v63, 0, v253, vcc
	v_fmac_f32_e32 v63, v185, v62
	v_exp_f32_e32 v62, v63
	v_cndmask_b32_e32 v63, 0, v252, vcc
	v_cvt_pk_bf16_f32 v87, v90, v91
	s_movk_i32 s12, 0x4000
	v_ldexp_f32 v79, v62, v63
	v_ashrrev_i32_e32 v62, 5, v50
	v_and_or_b32 v62, v62, -4, v184
	v_ashrrev_i32_e32 v63, 31, v62
	v_lshlrev_b64 v[62:63], 14, v[62:63]
	v_lshl_or_b32 v62, v183, 7, v62
	v_or_b32_e32 v62, v62, v148
	v_lshlrev_b64 v[62:63], 1, v[62:63]
	v_lshl_add_u64 v[90:91], s[14:15], 0, v[62:63]
	global_store_dwordx2 v[90:91], v[86:87], off offset:32
	v_mov_b32_e32 v86, v44
	v_mov_b32_e32 v87, v70
	v_pk_mul_f32 v[92:93], v[64:65], v[86:87]
	v_pk_mul_f32 v[88:89], v[78:79], v[88:89]
	v_cvt_pk_bf16_f32 v92, v92, v93
	v_cvt_pk_bf16_f32 v93, v96, v97
	v_add_co_u32_e32 v96, vcc, s12, v90
	v_cvt_pk_bf16_f32 v85, v88, v89
	s_nop 0
	v_addc_co_u32_e32 v97, vcc, 0, v91, vcc
	v_lshl_add_u64 v[62:63], s[10:11], 0, v[62:63]
	global_store_dwordx2 v[96:97], v[92:93], off offset:32
	global_store_dwordx2 v[62:63], v[84:85], off offset:32
	v_pk_mul_f32 v[84:85], v[66:67], v[86:87]
	v_pk_mul_f32 v[86:87], v[78:79], v[94:95]
	v_cvt_pk_bf16_f32 v84, v84, v85
	v_cvt_pk_bf16_f32 v85, v86, v87
	v_add_co_u32_e32 v86, vcc, s12, v62
	v_pk_mul_f32 v[72:73], v[76:77], v[80:81]
	s_nop 0
	v_addc_co_u32_e32 v87, vcc, 0, v63, vcc
	v_cvt_pk_bf16_f32 v48, v48, v49
	v_cvt_pk_bf16_f32 v49, v72, v73
	v_mov_b32_e32 v70, v45
	v_mov_b32_e32 v82, v75
	global_store_dwordx2 v[86:87], v[84:85], off offset:32
	global_store_dwordx2 v[90:91], v[48:49], off offset:288
	v_pk_mul_f32 v[44:45], v[64:65], v[70:71]
	v_pk_mul_f32 v[48:49], v[76:77], v[82:83]
	v_cvt_pk_bf16_f32 v44, v44, v45
	v_cvt_pk_bf16_f32 v45, v48, v49
	global_store_dwordx2 v[96:97], v[44:45], off offset:288
	v_pk_mul_f32 v[44:45], v[66:67], v[68:69]
	v_pk_mul_f32 v[48:49], v[78:79], v[80:81]
	v_cvt_pk_bf16_f32 v44, v44, v45
	v_cvt_pk_bf16_f32 v45, v48, v49
	global_store_dwordx2 v[62:63], v[44:45], off offset:288
	v_pk_mul_f32 v[44:45], v[66:67], v[70:71]
	v_pk_mul_f32 v[48:49], v[78:79], v[82:83]
	v_cvt_pk_bf16_f32 v44, v44, v45
	v_cvt_pk_bf16_f32 v45, v48, v49
	s_mov_b64 s[10:11], 0
	global_store_dwordx2 v[86:87], v[44:45], off offset:288

;   DEVINL void operator()(Acc& acc, int brow, int bcol) const {
;     ...
;         const int row0 = brow + ai * 128 + wr * 64 + m * 16 + fq * 4;
;         float o1[2][4], o2[2][4];
;         _Pragma("unroll") for (int j = 0; j < 4; ++j) {
;           const int pos = (row0 + j) % L;
;           const float2 cs = *(const float2*)(P.ctab + pos * 64 + i0), sn = *(const float2*)(P.stab + pos * 64 + i0);
;           o1[0][j] = acc[ai][0][m][0][j] * cs.x - acc[ai][1][m][0][j] * sn.x; o2[0][j] = acc[ai][0][m][0][j] * sn.x + acc[ai][1][m][0][j] * cs.x;
;           o1[1][j] = acc[ai][0][m][1][j] * cs.y - acc[ai][1][m][1][j] * sn.y; o2[1][j] = acc[ai][0][m][1][j] * sn.y + acc[ai][1][m][1][j] * cs.y;
;         }
.LBB0_788:
	v_add_u32_e32 v34, 0xa0, v146
	v_sub_u32_e32 v36, 0xffffff60, v146
	v_max_i32_e32 v36, v34, v36
	v_mul_hi_u32 v37, v36, v174
	v_mul_lo_u32 v37, v37, s62
	v_sub_u32_e32 v36, v36, v37
	v_cmp_le_u32_e32 vcc, s62, v36
	v_subrev_u32_e32 v37, s62, v36
	v_ashrrev_i32_e32 v35, 31, v34
	v_cndmask_b32_e32 v36, v36, v37, vcc
	v_cmp_le_u32_e32 vcc, s62, v36
	v_subrev_u32_e32 v37, s62, v36
	v_mov_b32_e32 v42, v22
	v_cndmask_b32_e32 v36, v36, v37, vcc
	v_xor_b32_e32 v36, v36, v35
	v_sub_u32_e32 v36, v36, v35
	v_lshlrev_b32_e32 v36, 6, v36
	v_ashrrev_i32_e32 v37, 31, v36
	v_lshlrev_b64 v[36:37], 2, v[36:37]
	v_lshl_add_u64 v[38:39], v[142:143], 0, v[36:37]
	v_lshl_add_u64 v[36:37], v[144:145], 0, v[36:37]
	global_load_dwordx2 v[220:221], v[38:39], off offset:256
	global_load_dwordx2 v[222:223], v[36:37], off offset:256
	global_load_dwordx2 v[224:225], v[38:39], off offset:512
	global_load_dwordx2 v[226:227], v[36:37], off offset:512
	global_load_dwordx2 v[228:229], v[38:39], off offset:768
	global_load_dwordx2 v[230:231], v[36:37], off offset:768
	global_load_dwordx2 v[40:41], v[38:39], off
	s_nop 0
	global_load_dwordx2 v[36:37], v[36:37], off
	v_mov_b32_e32 v43, v18
	v_mov_b32_e32 v44, v30
	v_mov_b32_e32 v45, v26
	v_sub_u32_e32 v18, 0xffffff5f, v146
	v_mov_b32_e32 v26, v31
	v_sub_u32_e32 v30, 0xffffff5e, v146
	v_mov_b32_e32 v46, v24
	v_mov_b32_e32 v47, v20
	v_mov_b32_e32 v48, v32
	v_mov_b32_e32 v49, v28
	v_sub_u32_e32 v20, 0xffffff5d, v146
	v_mov_b32_e32 v28, v33
	s_mov_b64 s[10:11], -1
	s_waitcnt vmcnt(0)
	v_pk_mul_f32 v[38:39], v[44:45], v[36:37]
	v_pk_mul_f32 v[36:37], v[42:43], v[36:37]
	v_pk_fma_f32 v[38:39], v[42:43], v[40:41], v[38:39] neg_lo:[0,0,1] neg_hi:[0,0,1]
	v_pk_fma_f32 v[36:37], v[44:45], v[40:41], v[36:37]
	v_add_u32_e32 v40, 0xa1, v146
	v_max_i32_e32 v18, v40, v18
	v_mul_hi_u32 v22, v18, v174
	v_mul_lo_u32 v22, v22, s62
	v_sub_u32_e32 v18, v18, v22
	v_cmp_le_u32_e32 vcc, s62, v18
	v_subrev_u32_e32 v22, s62, v18
	v_ashrrev_i32_e32 v41, 31, v40
	v_cndmask_b32_e32 v18, v18, v22, vcc
	v_cmp_le_u32_e32 vcc, s62, v18
	v_subrev_u32_e32 v22, s62, v18
	s_nop 0
	v_cndmask_b32_e32 v18, v18, v22, vcc
	v_xor_b32_e32 v18, v18, v41
	v_sub_u32_e32 v18, v18, v41
	v_lshlrev_b32_e32 v42, 6, v18
	v_ashrrev_i32_e32 v43, 31, v42
	v_lshlrev_b64 v[42:43], 2, v[42:43]
	v_lshl_add_u64 v[44:45], v[142:143], 0, v[42:43]
	v_lshl_add_u64 v[42:43], v[144:145], 0, v[42:43]
	v_mov_b32_e32 v44, v220
	v_mov_b32_e32 v45, v221
	v_mov_b32_e32 v42, v222
	v_mov_b32_e32 v43, v223
	v_mov_b32_e32 v18, v23
	v_pk_mul_f32 v[22:23], v[26:27], v[42:43]
	s_nop 0
	v_pk_fma_f32 v[22:23], v[18:19], v[44:45], v[22:23] neg_lo:[0,0,1] neg_hi:[0,0,1]
	v_pk_mul_f32 v[18:19], v[18:19], v[42:43]
	s_nop 0
	v_pk_fma_f32 v[18:19], v[26:27], v[44:45], v[18:19]
	v_add_u32_e32 v26, 0xa2, v146
	v_max_i32_e32 v30, v26, v30
	v_mul_hi_u32 v31, v30, v174
	v_mul_lo_u32 v31, v31, s62
	v_sub_u32_e32 v30, v30, v31
	v_cmp_le_u32_e32 vcc, s62, v30
	v_subrev_u32_e32 v31, s62, v30
	v_ashrrev_i32_e32 v27, 31, v26
	v_cndmask_b32_e32 v30, v30, v31, vcc
	v_cmp_le_u32_e32 vcc, s62, v30
	v_subrev_u32_e32 v31, s62, v30
	s_nop 0
	v_cndmask_b32_e32 v30, v30, v31, vcc
	v_xor_b32_e32 v30, v30, v27
	v_sub_u32_e32 v30, v30, v27
	v_lshlrev_b32_e32 v30, 6, v30
	v_ashrrev_i32_e32 v31, 31, v30
	v_lshlrev_b64 v[30:31], 2, v[30:31]
	v_lshl_add_u64 v[42:43], v[142:143], 0, v[30:31]
	v_lshl_add_u64 v[30:31], v[144:145], 0, v[30:31]
	v_mov_b32_e32 v44, v224
	v_mov_b32_e32 v45, v225
	v_mov_b32_e32 v30, v226
	v_mov_b32_e32 v31, v227
	v_pk_mul_f32 v[42:43], v[48:49], v[30:31]
	v_pk_mul_f32 v[30:31], v[46:47], v[30:31]
	v_pk_fma_f32 v[42:43], v[46:47], v[44:45], v[42:43] neg_lo:[0,0,1] neg_hi:[0,0,1]
	v_pk_fma_f32 v[30:31], v[48:49], v[44:45], v[30:31]
	v_add_u32_e32 v44, 0xa3, v146
	v_max_i32_e32 v20, v44, v20
	v_mul_hi_u32 v24, v20, v174
	v_mul_lo_u32 v24, v24, s62
	v_sub_u32_e32 v20, v20, v24
	v_cmp_le_u32_e32 vcc, s62, v20
	v_subrev_u32_e32 v24, s62, v20
	v_ashrrev_i32_e32 v45, 31, v44
	v_cndmask_b32_e32 v20, v20, v24, vcc
	v_cmp_le_u32_e32 vcc, s62, v20
	v_subrev_u32_e32 v24, s62, v20
	s_nop 0
	v_cndmask_b32_e32 v20, v20, v24, vcc
	v_xor_b32_e32 v20, v20, v45
	v_sub_u32_e32 v20, v20, v45
	v_lshlrev_b32_e32 v46, 6, v20
	v_ashrrev_i32_e32 v47, 31, v46
	v_lshlrev_b64 v[46:47], 2, v[46:47]
	v_lshl_add_u64 v[48:49], v[142:143], 0, v[46:47]
	v_lshl_add_u64 v[46:47], v[144:145], 0, v[46:47]
	v_mov_b32_e32 v48, v228
	v_mov_b32_e32 v49, v229
	v_mov_b32_e32 v46, v230
	v_mov_b32_e32 v47, v231
	v_mov_b32_e32 v20, v25
	s_and_b64 vcc, exec, s[8:9]
	v_pk_mul_f32 v[24:25], v[28:29], v[46:47]
	s_nop 0
	v_pk_fma_f32 v[24:25], v[20:21], v[48:49], v[24:25] neg_lo:[0,0,1] neg_hi:[0,0,1]
	v_pk_mul_f32 v[20:21], v[20:21], v[46:47]
	s_nop 0
	v_pk_fma_f32 v[20:21], v[28:29], v[48:49], v[20:21]
	s_cbranch_vccnz .LBB0_790
; DEVINL unsigned pack2(float a, float b) { hf2 v = {a, b}; hbf2 r = __builtin_convertvector(v, hbf2); return __builtin_bit_cast(unsigned, r); }
;   DEVINL void operator()(Acc& acc, int brow, int bcol) const {
;     ...
;           const float ksc = 0.08838834764831845f;
;           float ff[4], fb[4];
;           _Pragma("unroll") for (int j = 0; j < 4; ++j) {
;             const int row = row0 + j, nl = row & 127;
;             o1[0][j] *= ksc; o1[1][j] *= ksc; o2[0][j] *= ksc; o2[1][j] *= ksc;
;             const size_t o = (size_t)row * 512 + head * 128 + i0;
;             *(unsigned*)(P.k + o) = pack2(o1[0][j], o1[1][j]); *(unsigned*)(P.k + o + 64) = pack2(o2[0][j], o2[1][j]);
;             ff[j] = exp2f((float)(127 - nl) * lgf); fb[j] = exp2f((float)nl * lgb);
;           }
;           const int chunk = row0 >> 7, m0 = row0 & 127;
;           _Pragma("unroll") for (int n = 0; n < 2; ++n) {
;             const size_t o = ((size_t)(chunk * 4 + head) * 128 + i0 + n) * 128 + m0;
;             *(bf16x4*)(P.kTf + o) = pack4(o1[n][0] * ff[0], o1[n][1] * ff[1], o1[n][2] * ff[2], o1[n][3] * ff[3]);
;             *(bf16x4*)(P.kTf + o + 64 * 128) = pack4(o2[n][0] * ff[0], o2[n][1] * ff[1], o2[n][2] * ff[2], o2[n][3] * ff[3]);
;             *(bf16x4*)(P.kTb + o) = pack4(o1[n][0] * fb[0], o1[n][1] * fb[1], o1[n][2] * fb[2], o1[n][3] * fb[3]);
;             *(bf16x4*)(P.kTb + o + 64 * 128) = pack4(o2[n][0] * fb[0], o2[n][1] * fb[1], o2[n][2] * fb[2], o2[n][3] * fb[3]);
;           }
	s_load_dwordx4 s[12:15], s[88:89], 0x190
	s_load_dwordx2 s[10:11], s[88:89], 0x1a0
	v_mov_b32_e32 v115, v1
	s_mov_b32 s20, 0x3db504f3
	v_pk_mul_f32 v[32:33], v[38:39], s[20:21] op_sel_hi:[1,0]
	s_waitcnt lgkmcnt(0)
	v_lshl_add_u64 v[28:29], s[12:13], 0, v[0:1]
	v_lshl_add_u64 v[46:47], v[28:29], 0, v[114:115]
	v_lshlrev_b64 v[48:49], 10, v[34:35]
	v_pk_mul_f32 v[28:29], v[36:37], s[20:21] op_sel_hi:[1,0]
	v_cvt_pk_bf16_f32 v51, v32, v33
	v_lshl_add_u64 v[48:49], v[46:47], 0, v[48:49]
	global_store_dword v[48:49], v51, off
	v_cvt_pk_bf16_f32 v51, v28, v29
	global_store_dword v[48:49], v51, off offset:128
	s_movk_i32 s13, 0x7f
	v_mov_b32_e32 v48, 0x6c
	v_bitop3_b32 v48, v34, s13, v48 bitop3:0x6c
	v_cvt_f32_ubyte0_e32 v48, v48
	v_mul_f32_e32 v49, v186, v48
	s_mov_b32 s12, 0xc2fc0000
	v_cmp_gt_f32_e32 vcc, s12, v49
	v_and_b32_e32 v50, 0x6c, v34
	v_pk_mul_f32 v[52:53], v[22:23], s[20:21] op_sel_hi:[1,0]
	v_cndmask_b32_e32 v49, 0, v253, vcc
	v_fmac_f32_e32 v49, v186, v48
	v_exp_f32_e32 v48, v49
	v_cndmask_b32_e32 v49, 0, v252, vcc
	v_lshlrev_b64 v[56:57], 10, v[40:41]
	v_pk_mul_f32 v[54:55], v[18:19], s[20:21] op_sel_hi:[1,0]
	v_ldexp_f32 v48, v48, v49
	v_cvt_f32_ubyte0_e32 v49, v50
	v_mul_f32_e32 v50, v185, v49
	v_cmp_gt_f32_e32 vcc, s12, v50
	v_lshl_add_u64 v[56:57], v[46:47], 0, v[56:57]
	v_and_b32_e32 v51, 0x6d, v40
	v_cndmask_b32_e32 v50, 0, v253, vcc
	v_fmac_f32_e32 v50, v185, v49
	v_exp_f32_e32 v49, v50
	v_cndmask_b32_e32 v50, 0, v252, vcc
	v_cvt_f32_ubyte0_e32 v51, v51
	v_lshlrev_b64 v[60:61], 10, v[26:27]
	v_ldexp_f32 v50, v49, v50
	v_cvt_pk_bf16_f32 v49, v52, v53
	global_store_dword v[56:57], v49, off
	v_cvt_pk_bf16_f32 v49, v54, v55
	global_store_dword v[56:57], v49, off offset:128
	v_mov_b32_e32 v49, 0x6d
	v_bitop3_b32 v49, v40, s13, v49 bitop3:0x6c
	v_cvt_f32_ubyte0_e32 v49, v49
	v_mul_f32_e32 v56, v186, v49
	v_cmp_gt_f32_e32 vcc, s12, v56
	v_pk_mul_f32 v[58:59], v[30:31], s[20:21] op_sel_hi:[1,0]
	v_lshl_add_u64 v[60:61], v[46:47], 0, v[60:61]
	v_cndmask_b32_e32 v56, 0, v253, vcc
	v_fmac_f32_e32 v56, v186, v49
	v_exp_f32_e32 v49, v56
	v_cndmask_b32_e32 v56, 0, v252, vcc
	v_and_b32_e32 v62, 0x6e, v26
	v_pk_mul_f32 v[64:65], v[24:25], s[20:21] op_sel_hi:[1,0]
	v_ldexp_f32 v49, v49, v56
	v_mul_f32_e32 v56, v185, v51
	v_cmp_gt_f32_e32 vcc, s12, v56
	v_lshlrev_b64 v[68:69], 10, v[44:45]
	v_pk_mul_f32 v[66:67], v[20:21], s[20:21] op_sel_hi:[1,0]
	v_cndmask_b32_e32 v56, 0, v253, vcc
	v_fmac_f32_e32 v56, v185, v51
	v_exp_f32_e32 v51, v56
	v_cndmask_b32_e32 v56, 0, v252, vcc
	v_lshl_add_u64 v[46:47], v[46:47], 0, v[68:69]
	v_mov_b32_e32 v68, v32
	v_ldexp_f32 v51, v51, v56
	v_pk_mul_f32 v[56:57], v[42:43], s[20:21] op_sel_hi:[1,0]
	v_mov_b32_e32 v69, v52
	v_cvt_pk_bf16_f32 v63, v56, v57
	global_store_dword v[60:61], v63, off
	v_cvt_pk_bf16_f32 v63, v58, v59
	global_store_dword v[60:61], v63, off offset:128
	v_mov_b32_e32 v60, 0x6e
	v_bitop3_b32 v60, v26, s13, v60 bitop3:0x6c
	v_cvt_f32_ubyte0_e32 v60, v60
	v_mul_f32_e32 v61, v186, v60
	v_cmp_gt_f32_e32 vcc, s12, v61
	v_and_b32_e32 v63, 0x6f, v44
	v_mov_b32_e32 v72, v56
	v_cndmask_b32_e32 v61, 0, v253, vcc
	v_fmac_f32_e32 v61, v186, v60
	v_exp_f32_e32 v60, v61
	v_cndmask_b32_e32 v61, 0, v252, vcc
	v_mov_b32_e32 v73, v64
	v_pk_mul_f32 v[70:71], v[48:49], v[68:69]
	v_ldexp_f32 v60, v60, v61
	v_cvt_f32_ubyte0_e32 v61, v62
	v_mul_f32_e32 v62, v185, v61
	v_cmp_gt_f32_e32 vcc, s12, v62
	v_cvt_pk_bf16_f32 v70, v70, v71
	v_mov_b32_e32 v78, v58
	v_cndmask_b32_e32 v62, 0, v253, vcc
	v_fmac_f32_e32 v62, v185, v61
	v_exp_f32_e32 v61, v62
	v_cndmask_b32_e32 v62, 0, v252, vcc
	v_mov_b32_e32 v79, v66
	v_pk_mul_f32 v[68:69], v[50:51], v[68:69]
	v_ldexp_f32 v62, v61, v62
	v_cvt_pk_bf16_f32 v61, v64, v65
	global_store_dword v[46:47], v61, off
	v_cvt_pk_bf16_f32 v61, v66, v67
	global_store_dword v[46:47], v61, off offset:128
	v_mov_b32_e32 v46, 0x6f
	v_bitop3_b32 v46, v44, s13, v46 bitop3:0x6c
	v_cvt_f32_ubyte0_e32 v46, v46
	v_mul_f32_e32 v47, v186, v46
	v_cmp_gt_f32_e32 vcc, s12, v47
	v_cvt_pk_bf16_f32 v68, v68, v69
	v_mov_b32_e32 v52, v33
	v_cndmask_b32_e32 v47, 0, v253, vcc
	v_fmac_f32_e32 v47, v186, v46
	v_exp_f32_e32 v46, v47
	v_cndmask_b32_e32 v47, 0, v252, vcc
	v_mov_b32_e32 v64, v57
	v_pk_mul_f32 v[32:33], v[48:49], v[52:53]
	v_ldexp_f32 v61, v46, v47
	v_cvt_f32_ubyte0_e32 v46, v63
	v_mul_f32_e32 v47, v185, v46
	v_cmp_gt_f32_e32 vcc, s12, v47
	v_pk_mul_f32 v[74:75], v[60:61], v[72:73]
	v_pk_mul_f32 v[80:81], v[60:61], v[78:79]
	v_cndmask_b32_e32 v47, 0, v253, vcc
	v_fmac_f32_e32 v47, v185, v46
	v_exp_f32_e32 v46, v47
	v_cndmask_b32_e32 v47, 0, v252, vcc
	v_cvt_pk_bf16_f32 v71, v74, v75
	s_movk_i32 s12, 0x4000
	v_ldexp_f32 v63, v46, v47
	v_ashrrev_i32_e32 v46, 5, v34
	v_and_or_b32 v46, v46, -4, v184
	v_ashrrev_i32_e32 v47, 31, v46
	v_lshlrev_b64 v[46:47], 14, v[46:47]
	v_lshl_or_b32 v46, v183, 7, v46
	v_or_b32_e32 v46, v46, v148
	v_lshlrev_b64 v[46:47], 1, v[46:47]
	v_lshl_add_u64 v[74:75], s[14:15], 0, v[46:47]
	global_store_dwordx2 v[74:75], v[70:71], off offset:64
	v_mov_b32_e32 v70, v28
	v_mov_b32_e32 v71, v54
	v_pk_mul_f32 v[76:77], v[48:49], v[70:71]
	v_pk_mul_f32 v[72:73], v[62:63], v[72:73]
	v_cvt_pk_bf16_f32 v76, v76, v77
	v_cvt_pk_bf16_f32 v77, v80, v81
	v_add_co_u32_e32 v80, vcc, s12, v74
	v_cvt_pk_bf16_f32 v69, v72, v73
	s_nop 0
	v_addc_co_u32_e32 v81, vcc, 0, v75, vcc
	v_lshl_add_u64 v[46:47], s[10:11], 0, v[46:47]
	global_store_dwordx2 v[80:81], v[76:77], off offset:64
	global_store_dwordx2 v[46:47], v[68:69], off offset:64
	v_pk_mul_f32 v[68:69], v[50:51], v[70:71]
	v_pk_mul_f32 v[70:71], v[62:63], v[78:79]
	v_cvt_pk_bf16_f32 v68, v68, v69
	v_cvt_pk_bf16_f32 v69, v70, v71
	v_add_co_u32_e32 v70, vcc, s12, v46
	v_pk_mul_f32 v[56:57], v[60:61], v[64:65]
	s_nop 0
	v_addc_co_u32_e32 v71, vcc, 0, v47, vcc
	v_cvt_pk_bf16_f32 v32, v32, v33
	v_cvt_pk_bf16_f32 v33, v56, v57
	v_mov_b32_e32 v54, v29
	v_mov_b32_e32 v66, v59
	global_store_dwordx2 v[70:71], v[68:69], off offset:64
	global_store_dwordx2 v[74:75], v[32:33], off offset:320
	v_pk_mul_f32 v[28:29], v[48:49], v[54:55]
	v_pk_mul_f32 v[32:33], v[60:61], v[66:67]
	v_cvt_pk_bf16_f32 v28, v28, v29
	v_cvt_pk_bf16_f32 v29, v32, v33
	global_store_dwordx2 v[80:81], v[28:29], off offset:320
	v_pk_mul_f32 v[28:29], v[50:51], v[52:53]
	v_pk_mul_f32 v[32:33], v[62:63], v[64:65]
	v_cvt_pk_bf16_f32 v28, v28, v29
	v_cvt_pk_bf16_f32 v29, v32, v33
	global_store_dwordx2 v[46:47], v[28:29], off offset:320
	v_pk_mul_f32 v[28:29], v[50:51], v[54:55]
	v_pk_mul_f32 v[32:33], v[62:63], v[66:67]
	v_cvt_pk_bf16_f32 v28, v28, v29
	v_cvt_pk_bf16_f32 v29, v32, v33
	s_mov_b64 s[10:11], 0
	global_store_dwordx2 v[70:71], v[28:29], off offset:320

;   DEVINL void operator()(Acc& acc, int brow, int bcol) const {
;     ...
;         const int row0 = brow + ai * 128 + wr * 64 + m * 16 + fq * 4;
;         float o1[2][4], o2[2][4];
;         _Pragma("unroll") for (int j = 0; j < 4; ++j) {
;           const int pos = (row0 + j) % L;
;           const float2 cs = *(const float2*)(P.ctab + pos * 64 + i0), sn = *(const float2*)(P.stab + pos * 64 + i0);
;           o1[0][j] = acc[ai][0][m][0][j] * cs.x - acc[ai][1][m][0][j] * sn.x; o2[0][j] = acc[ai][0][m][0][j] * sn.x + acc[ai][1][m][0][j] * cs.x;
;           o1[1][j] = acc[ai][0][m][1][j] * cs.y - acc[ai][1][m][1][j] * sn.y; o2[1][j] = acc[ai][0][m][1][j] * sn.y + acc[ai][1][m][1][j] * cs.y;
;         }
.LBB0_792:
	v_add_u32_e32 v18, 0xb0, v146
	v_sub_u32_e32 v20, 0xffffff50, v146
	v_max_i32_e32 v20, v18, v20
	v_mul_hi_u32 v21, v20, v174
	v_mul_lo_u32 v21, v21, s62
	v_sub_u32_e32 v20, v20, v21
	v_cmp_le_u32_e32 vcc, s62, v20
	v_subrev_u32_e32 v21, s62, v20
	v_ashrrev_i32_e32 v19, 31, v18
	v_cndmask_b32_e32 v20, v20, v21, vcc
	v_cmp_le_u32_e32 vcc, s62, v20
	v_subrev_u32_e32 v21, s62, v20
	v_mov_b32_e32 v26, v6
	v_cndmask_b32_e32 v20, v20, v21, vcc
	v_xor_b32_e32 v20, v20, v19
	v_sub_u32_e32 v20, v20, v19
	v_lshlrev_b32_e32 v20, 6, v20
	v_ashrrev_i32_e32 v21, 31, v20
	v_lshlrev_b64 v[20:21], 2, v[20:21]
	v_lshl_add_u64 v[22:23], v[142:143], 0, v[20:21]
	v_lshl_add_u64 v[20:21], v[144:145], 0, v[20:21]
	global_load_dwordx2 v[220:221], v[22:23], off offset:256
	global_load_dwordx2 v[222:223], v[20:21], off offset:256
	global_load_dwordx2 v[224:225], v[22:23], off offset:512
	global_load_dwordx2 v[226:227], v[20:21], off offset:512
	global_load_dwordx2 v[228:229], v[22:23], off offset:768
	global_load_dwordx2 v[230:231], v[20:21], off offset:768
	global_load_dwordx2 v[24:25], v[22:23], off
	s_nop 0
	global_load_dwordx2 v[20:21], v[20:21], off
	v_mov_b32_e32 v27, v2
	v_mov_b32_e32 v28, v14
	v_mov_b32_e32 v29, v10
	v_sub_u32_e32 v2, 0xffffff4f, v146
	v_mov_b32_e32 v10, v15
	v_sub_u32_e32 v14, 0xffffff4e, v146
	v_mov_b32_e32 v30, v8
	v_mov_b32_e32 v31, v4
	v_mov_b32_e32 v32, v16
	v_mov_b32_e32 v33, v12
	v_sub_u32_e32 v4, 0xffffff4d, v146
	v_mov_b32_e32 v12, v17
	s_mov_b64 s[10:11], -1
	s_waitcnt vmcnt(0)
	v_pk_mul_f32 v[22:23], v[28:29], v[20:21]
	v_pk_mul_f32 v[20:21], v[26:27], v[20:21]
	v_pk_fma_f32 v[22:23], v[26:27], v[24:25], v[22:23] neg_lo:[0,0,1] neg_hi:[0,0,1]
	v_pk_fma_f32 v[20:21], v[28:29], v[24:25], v[20:21]
	v_add_u32_e32 v24, 0xb1, v146
	v_max_i32_e32 v2, v24, v2
	v_mul_hi_u32 v6, v2, v174
	v_mul_lo_u32 v6, v6, s62
	v_sub_u32_e32 v2, v2, v6
	v_cmp_le_u32_e32 vcc, s62, v2
	v_subrev_u32_e32 v6, s62, v2
	v_ashrrev_i32_e32 v25, 31, v24
	v_cndmask_b32_e32 v2, v2, v6, vcc
	v_cmp_le_u32_e32 vcc, s62, v2
	v_subrev_u32_e32 v6, s62, v2
	s_nop 0
	v_cndmask_b32_e32 v2, v2, v6, vcc
	v_xor_b32_e32 v2, v2, v25
	v_sub_u32_e32 v2, v2, v25
	v_lshlrev_b32_e32 v26, 6, v2
	v_ashrrev_i32_e32 v27, 31, v26
	v_lshlrev_b64 v[26:27], 2, v[26:27]
	v_lshl_add_u64 v[28:29], v[142:143], 0, v[26:27]
	v_lshl_add_u64 v[26:27], v[144:145], 0, v[26:27]
	v_mov_b32_e32 v28, v220
	v_mov_b32_e32 v29, v221
	v_mov_b32_e32 v26, v222
	v_mov_b32_e32 v27, v223
	v_mov_b32_e32 v2, v7
	v_pk_mul_f32 v[6:7], v[10:11], v[26:27]
	s_nop 0
	v_pk_fma_f32 v[6:7], v[2:3], v[28:29], v[6:7] neg_lo:[0,0,1] neg_hi:[0,0,1]
	v_pk_mul_f32 v[2:3], v[2:3], v[26:27]
	s_nop 0
	v_pk_fma_f32 v[2:3], v[10:11], v[28:29], v[2:3]
	v_add_u32_e32 v10, 0xb2, v146
	v_max_i32_e32 v14, v10, v14
	v_mul_hi_u32 v15, v14, v174
	v_mul_lo_u32 v15, v15, s62
	v_sub_u32_e32 v14, v14, v15
	v_cmp_le_u32_e32 vcc, s62, v14
	v_subrev_u32_e32 v15, s62, v14
	v_ashrrev_i32_e32 v11, 31, v10
	v_cndmask_b32_e32 v14, v14, v15, vcc
	v_cmp_le_u32_e32 vcc, s62, v14
	v_subrev_u32_e32 v15, s62, v14
	s_nop 0
	v_cndmask_b32_e32 v14, v14, v15, vcc
	v_xor_b32_e32 v14, v14, v11
	v_sub_u32_e32 v14, v14, v11
	v_lshlrev_b32_e32 v14, 6, v14
	v_ashrrev_i32_e32 v15, 31, v14
	v_lshlrev_b64 v[14:15], 2, v[14:15]
	v_lshl_add_u64 v[26:27], v[142:143], 0, v[14:15]
	v_lshl_add_u64 v[14:15], v[144:145], 0, v[14:15]
	v_mov_b32_e32 v28, v224
	v_mov_b32_e32 v29, v225
	v_mov_b32_e32 v14, v226
	v_mov_b32_e32 v15, v227
	v_pk_mul_f32 v[26:27], v[32:33], v[14:15]
	v_pk_mul_f32 v[14:15], v[30:31], v[14:15]
	v_pk_fma_f32 v[26:27], v[30:31], v[28:29], v[26:27] neg_lo:[0,0,1] neg_hi:[0,0,1]
	v_pk_fma_f32 v[14:15], v[32:33], v[28:29], v[14:15]
	v_add_u32_e32 v28, 0xb3, v146
	v_max_i32_e32 v4, v28, v4
	v_mul_hi_u32 v8, v4, v174
	v_mul_lo_u32 v8, v8, s62
	v_sub_u32_e32 v4, v4, v8
	v_cmp_le_u32_e32 vcc, s62, v4
	v_subrev_u32_e32 v8, s62, v4
	v_ashrrev_i32_e32 v29, 31, v28
	v_cndmask_b32_e32 v4, v4, v8, vcc
	v_cmp_le_u32_e32 vcc, s62, v4
	v_subrev_u32_e32 v8, s62, v4
	s_nop 0
	v_cndmask_b32_e32 v4, v4, v8, vcc
	v_xor_b32_e32 v4, v4, v29
	v_sub_u32_e32 v4, v4, v29
	v_lshlrev_b32_e32 v30, 6, v4
	v_ashrrev_i32_e32 v31, 31, v30
	v_lshlrev_b64 v[30:31], 2, v[30:31]
	v_lshl_add_u64 v[32:33], v[142:143], 0, v[30:31]
	v_lshl_add_u64 v[30:31], v[144:145], 0, v[30:31]
	v_mov_b32_e32 v32, v228
	v_mov_b32_e32 v33, v229
	v_mov_b32_e32 v30, v230
	v_mov_b32_e32 v31, v231
	v_mov_b32_e32 v4, v9
	s_and_b64 vcc, exec, s[8:9]
	v_pk_mul_f32 v[8:9], v[12:13], v[30:31]
	s_nop 0
	v_pk_fma_f32 v[8:9], v[4:5], v[32:33], v[8:9] neg_lo:[0,0,1] neg_hi:[0,0,1]
	v_pk_mul_f32 v[4:5], v[4:5], v[30:31]
	s_nop 0
	v_pk_fma_f32 v[4:5], v[12:13], v[32:33], v[4:5]
	s_cbranch_vccnz .LBB0_794
; DEVINL unsigned pack2(float a, float b) { hf2 v = {a, b}; hbf2 r = __builtin_convertvector(v, hbf2); return __builtin_bit_cast(unsigned, r); }
;   DEVINL void operator()(Acc& acc, int brow, int bcol) const {
;     ...
;           const float ksc = 0.08838834764831845f;
;           float ff[4], fb[4];
;           _Pragma("unroll") for (int j = 0; j < 4; ++j) {
;             const int row = row0 + j, nl = row & 127;
;             o1[0][j] *= ksc; o1[1][j] *= ksc; o2[0][j] *= ksc; o2[1][j] *= ksc;
;             const size_t o = (size_t)row * 512 + head * 128 + i0;
;             *(unsigned*)(P.k + o) = pack2(o1[0][j], o1[1][j]); *(unsigned*)(P.k + o + 64) = pack2(o2[0][j], o2[1][j]);
;             ff[j] = exp2f((float)(127 - nl) * lgf); fb[j] = exp2f((float)nl * lgb);
;           }
;           const int chunk = row0 >> 7, m0 = row0 & 127;
;           _Pragma("unroll") for (int n = 0; n < 2; ++n) {
;             const size_t o = ((size_t)(chunk * 4 + head) * 128 + i0 + n) * 128 + m0;
;             *(bf16x4*)(P.kTf + o) = pack4(o1[n][0] * ff[0], o1[n][1] * ff[1], o1[n][2] * ff[2], o1[n][3] * ff[3]);
;             *(bf16x4*)(P.kTf + o + 64 * 128) = pack4(o2[n][0] * ff[0], o2[n][1] * ff[1], o2[n][2] * ff[2], o2[n][3] * ff[3]);
;             *(bf16x4*)(P.kTb + o) = pack4(o1[n][0] * fb[0], o1[n][1] * fb[1], o1[n][2] * fb[2], o1[n][3] * fb[3]);
;             *(bf16x4*)(P.kTb + o + 64 * 128) = pack4(o2[n][0] * fb[0], o2[n][1] * fb[1], o2[n][2] * fb[2], o2[n][3] * fb[3]);
;           }
	s_load_dwordx4 s[8:11], s[88:89], 0x190
	s_load_dwordx2 s[12:13], s[88:89], 0x1a0
	v_mov_b32_e32 v115, v1
	s_mov_b32 s14, 0x3db504f3
	v_pk_mul_f32 v[16:17], v[22:23], s[14:15] op_sel_hi:[1,0]
	s_waitcnt lgkmcnt(0)
	v_lshl_add_u64 v[12:13], s[8:9], 0, v[0:1]
	v_lshl_add_u64 v[30:31], v[12:13], 0, v[114:115]
	v_lshlrev_b64 v[32:33], 10, v[18:19]
	v_pk_mul_f32 v[12:13], v[20:21], s[14:15] op_sel_hi:[1,0]
	v_cvt_pk_bf16_f32 v35, v16, v17
	v_lshl_add_u64 v[32:33], v[30:31], 0, v[32:33]
	global_store_dword v[32:33], v35, off
	v_cvt_pk_bf16_f32 v35, v12, v13
	global_store_dword v[32:33], v35, off offset:128
	s_movk_i32 s9, 0x7f
	v_mov_b32_e32 v32, 0x7c
	v_bitop3_b32 v32, v18, s9, v32 bitop3:0x6c
	v_cvt_f32_ubyte0_e32 v32, v32
	v_mul_f32_e32 v33, v186, v32
	s_mov_b32 s8, 0xc2fc0000
	v_cmp_gt_f32_e32 vcc, s8, v33
	v_and_b32_e32 v34, 0x7c, v18
	v_pk_mul_f32 v[36:37], v[6:7], s[14:15] op_sel_hi:[1,0]
	v_cndmask_b32_e32 v33, 0, v253, vcc
	v_fmac_f32_e32 v33, v186, v32
	v_exp_f32_e32 v32, v33
	v_cndmask_b32_e32 v33, 0, v252, vcc
	v_lshlrev_b64 v[40:41], 10, v[24:25]
	v_pk_mul_f32 v[38:39], v[2:3], s[14:15] op_sel_hi:[1,0]
	v_ldexp_f32 v32, v32, v33
	v_cvt_f32_ubyte0_e32 v33, v34
	v_mul_f32_e32 v34, v185, v33
	v_cmp_gt_f32_e32 vcc, s8, v34
	v_lshl_add_u64 v[40:41], v[30:31], 0, v[40:41]
	v_and_b32_e32 v35, 0x7d, v24
	v_cndmask_b32_e32 v34, 0, v253, vcc
	v_fmac_f32_e32 v34, v185, v33
	v_exp_f32_e32 v33, v34
	v_cndmask_b32_e32 v34, 0, v252, vcc
	v_cvt_f32_ubyte0_e32 v35, v35
	v_lshlrev_b64 v[44:45], 10, v[10:11]
	v_ldexp_f32 v34, v33, v34
	v_cvt_pk_bf16_f32 v33, v36, v37
	global_store_dword v[40:41], v33, off
	v_cvt_pk_bf16_f32 v33, v38, v39
	global_store_dword v[40:41], v33, off offset:128
	v_mov_b32_e32 v33, 0x7d
	v_bitop3_b32 v33, v24, s9, v33 bitop3:0x6c
	v_cvt_f32_ubyte0_e32 v33, v33
	v_mul_f32_e32 v40, v186, v33
	v_cmp_gt_f32_e32 vcc, s8, v40
	v_pk_mul_f32 v[42:43], v[14:15], s[14:15] op_sel_hi:[1,0]
	v_lshl_add_u64 v[44:45], v[30:31], 0, v[44:45]
	v_cndmask_b32_e32 v40, 0, v253, vcc
	v_fmac_f32_e32 v40, v186, v33
	v_exp_f32_e32 v33, v40
	v_cndmask_b32_e32 v40, 0, v252, vcc
	v_and_b32_e32 v46, 0x7e, v10
	v_pk_mul_f32 v[48:49], v[8:9], s[14:15] op_sel_hi:[1,0]
	v_ldexp_f32 v33, v33, v40
	v_mul_f32_e32 v40, v185, v35
	v_cmp_gt_f32_e32 vcc, s8, v40
	v_lshlrev_b64 v[52:53], 10, v[28:29]
	v_pk_mul_f32 v[50:51], v[4:5], s[14:15] op_sel_hi:[1,0]
	v_cndmask_b32_e32 v40, 0, v253, vcc
	v_fmac_f32_e32 v40, v185, v35
	v_exp_f32_e32 v35, v40
	v_cndmask_b32_e32 v40, 0, v252, vcc
	v_lshl_add_u64 v[30:31], v[30:31], 0, v[52:53]
	v_mov_b32_e32 v52, v16
	v_ldexp_f32 v35, v35, v40
	v_pk_mul_f32 v[40:41], v[26:27], s[14:15] op_sel_hi:[1,0]
	v_mov_b32_e32 v53, v36
	v_cvt_pk_bf16_f32 v47, v40, v41
	global_store_dword v[44:45], v47, off
	v_cvt_pk_bf16_f32 v47, v42, v43
	global_store_dword v[44:45], v47, off offset:128
	v_mov_b32_e32 v44, 0x7e
	v_bitop3_b32 v44, v10, s9, v44 bitop3:0x6c
	v_cvt_f32_ubyte0_e32 v44, v44
	v_mul_f32_e32 v45, v186, v44
	v_cmp_gt_f32_e32 vcc, s8, v45
	v_and_b32_e32 v47, 0x7f, v28
	v_mov_b32_e32 v56, v40
	v_cndmask_b32_e32 v45, 0, v253, vcc
	v_fmac_f32_e32 v45, v186, v44
	v_exp_f32_e32 v44, v45
	v_cndmask_b32_e32 v45, 0, v252, vcc
	v_mov_b32_e32 v57, v48
	v_pk_mul_f32 v[54:55], v[32:33], v[52:53]
	v_ldexp_f32 v44, v44, v45
	v_cvt_f32_ubyte0_e32 v45, v46
	v_mul_f32_e32 v46, v185, v45
	v_cmp_gt_f32_e32 vcc, s8, v46
	v_cvt_pk_bf16_f32 v54, v54, v55
	v_mov_b32_e32 v62, v42
	v_cndmask_b32_e32 v46, 0, v253, vcc
	v_fmac_f32_e32 v46, v185, v45
	v_exp_f32_e32 v45, v46
	v_cndmask_b32_e32 v46, 0, v252, vcc
	v_mov_b32_e32 v63, v50
	v_pk_mul_f32 v[52:53], v[34:35], v[52:53]
	v_ldexp_f32 v46, v45, v46
	v_cvt_pk_bf16_f32 v45, v48, v49
	global_store_dword v[30:31], v45, off
	v_cvt_pk_bf16_f32 v45, v50, v51
	global_store_dword v[30:31], v45, off offset:128
	v_bitop3_b32 v30, v28, s9, v28 bitop3:0xc
	v_cvt_f32_ubyte0_e32 v30, v30
	v_mul_f32_e32 v31, v186, v30
	v_cmp_gt_f32_e32 vcc, s8, v31
	v_cvt_pk_bf16_f32 v52, v52, v53
	v_mov_b32_e32 v36, v17
	v_cndmask_b32_e32 v31, 0, v253, vcc
	v_fmac_f32_e32 v31, v186, v30
	v_exp_f32_e32 v30, v31
	v_cndmask_b32_e32 v31, 0, v252, vcc
	v_mov_b32_e32 v48, v41
	v_pk_mul_f32 v[16:17], v[32:33], v[36:37]
	v_ldexp_f32 v45, v30, v31
	v_cvt_f32_ubyte0_e32 v30, v47
	v_mul_f32_e32 v31, v185, v30
	v_cmp_gt_f32_e32 vcc, s8, v31
	v_pk_mul_f32 v[58:59], v[44:45], v[56:57]
	v_pk_mul_f32 v[64:65], v[44:45], v[62:63]
	v_cndmask_b32_e32 v31, 0, v253, vcc
	v_fmac_f32_e32 v31, v185, v30
	v_exp_f32_e32 v30, v31
	v_cndmask_b32_e32 v31, 0, v252, vcc
	v_cvt_pk_bf16_f32 v55, v58, v59
	s_movk_i32 s8, 0x4000
	v_ldexp_f32 v47, v30, v31
	v_ashrrev_i32_e32 v30, 5, v18
	v_and_or_b32 v30, v30, -4, v184
	v_ashrrev_i32_e32 v31, 31, v30
	v_lshlrev_b64 v[30:31], 14, v[30:31]
	v_lshl_or_b32 v30, v183, 7, v30
	v_or_b32_e32 v30, v30, v148
	v_lshlrev_b64 v[30:31], 1, v[30:31]
	v_lshl_add_u64 v[58:59], s[10:11], 0, v[30:31]
	global_store_dwordx2 v[58:59], v[54:55], off offset:96
	v_mov_b32_e32 v54, v12
	v_mov_b32_e32 v55, v38
	v_pk_mul_f32 v[60:61], v[32:33], v[54:55]
	v_pk_mul_f32 v[56:57], v[46:47], v[56:57]
	v_cvt_pk_bf16_f32 v60, v60, v61
	v_cvt_pk_bf16_f32 v61, v64, v65
	v_add_co_u32_e32 v64, vcc, s8, v58
	v_cvt_pk_bf16_f32 v53, v56, v57
	s_nop 0
	v_addc_co_u32_e32 v65, vcc, 0, v59, vcc
	v_lshl_add_u64 v[30:31], s[12:13], 0, v[30:31]
	global_store_dwordx2 v[64:65], v[60:61], off offset:96
	global_store_dwordx2 v[30:31], v[52:53], off offset:96
	v_pk_mul_f32 v[52:53], v[34:35], v[54:55]
	v_pk_mul_f32 v[54:55], v[46:47], v[62:63]
	v_cvt_pk_bf16_f32 v52, v52, v53
	v_cvt_pk_bf16_f32 v53, v54, v55
	v_add_co_u32_e32 v54, vcc, s8, v30
	v_pk_mul_f32 v[40:41], v[44:45], v[48:49]
	s_nop 0
	v_addc_co_u32_e32 v55, vcc, 0, v31, vcc
	v_cvt_pk_bf16_f32 v16, v16, v17
	v_cvt_pk_bf16_f32 v17, v40, v41
	v_mov_b32_e32 v38, v13
	v_mov_b32_e32 v50, v43
	global_store_dwordx2 v[54:55], v[52:53], off offset:96
	global_store_dwordx2 v[58:59], v[16:17], off offset:352
	v_pk_mul_f32 v[12:13], v[32:33], v[38:39]
	v_pk_mul_f32 v[16:17], v[44:45], v[50:51]
	v_cvt_pk_bf16_f32 v12, v12, v13
	v_cvt_pk_bf16_f32 v13, v16, v17
	global_store_dwordx2 v[64:65], v[12:13], off offset:352
	v_pk_mul_f32 v[12:13], v[34:35], v[36:37]
	v_pk_mul_f32 v[16:17], v[46:47], v[48:49]
	v_cvt_pk_bf16_f32 v12, v12, v13
	v_cvt_pk_bf16_f32 v13, v16, v17
	global_store_dwordx2 v[30:31], v[12:13], off offset:352
	v_pk_mul_f32 v[12:13], v[34:35], v[38:39]
	v_pk_mul_f32 v[16:17], v[46:47], v[50:51]
	v_cvt_pk_bf16_f32 v12, v12, v13
	v_cvt_pk_bf16_f32 v13, v16, v17
	s_mov_b64 s[10:11], 0
	global_store_dwordx2 v[54:55], v[12:13], off offset:352

; DEVINL unsigned xb_add(unsigned* p, unsigned v) { return __hip_atomic_fetch_add(p, v, __ATOMIC_RELAXED, __HIP_MEMORY_SCOPE_AGENT); }
; DEVINL void xcd_barrier(unsigned* bar_) {
;     ...
;   if (threadIdx.x == 0) {
;     unsigned* bar = bar_;
;     XcdBarrier b; { const unsigned* st = bar + XCD_BAR_WORDS + blockIdx.x * 4; b.x = st[0]; b.nloc = st[1]; b.nx = st[2]; }
;     __builtin_amdgcn_s_waitcnt(0);
;     const unsigned old = xb_add(&bar[XB_XSUB(b.x)], 1u);
.LBB0_1593:
	v_readlane_b32 s8, v255, 60
	v_readlane_b32 s9, v255, 61
	v_readlane_b32 s10, v255, 62
	s_nop 1
	v_mov_b32_e32 v2, s8
	v_mov_b32_e32 v3, s9
	v_mov_b32_e32 v4, s10
	s_waitcnt vmcnt(0) expcnt(0) lgkmcnt(0)
	v_readfirstlane_b32 s8, v2
	s_lshl_b32 s24, s8, 6
	s_mov_b64 s[8:9], exec
	v_mbcnt_lo_u32_b32 v0, s8, 0
	v_mbcnt_hi_u32_b32 v0, s9, v0
	v_cmp_eq_u32_e32 vcc, 0, v0
	s_and_saveexec_b64 s[10:11], vcc
	s_cbranch_execz .LBB0_1595
	s_add_i32 s96, s24, 0x500
	s_lshl_b64 s[12:13], s[96:97], 2
	v_readlane_b32 s14, v255, 3
	v_readlane_b32 s15, v255, 4
	s_add_u32 s12, s14, s12
	s_addc_u32 s13, s15, s13
	s_bcnt1_i32_b64 s8, s[8:9]
	v_mov_b32_e32 v2, s8
	global_atomic_add v2, v1, v2, s[12:13] sc0
	s_mov_b32 s58, 0x10000
